# GEMM unit transition: wr==1 re-stagger barrier deferred from right after the epilogue to the K-loop entry, so both wave halves run the next-unit scheduler math and accumulator zeroing concurrently; on
# speedup vs baseline: 1.0106x; 1.0106x over previous
_Z6mk_fwd4Args:
	s_mov_b32 s100, 0
	s_mov_b32 s91, s2
	s_mov_b64 s[94:95], s[0:1]
	s_load_dword s54, s[0:1], 0x150
	s_nop 0
	s_load_dwordx4 s[0:3], s[94:95], 0x140
	s_mov_b32 s92, s91
	s_waitcnt lgkmcnt(0)
	v_writelane_b32 v252, s0, 0
	s_nop 1
	v_writelane_b32 v252, s1, 1
	v_writelane_b32 v252, s2, 2
	v_writelane_b32 v252, s3, 3
	s_add_u32 s0, s94, 0x150
	s_addc_u32 s1, s95, 0
	v_writelane_b32 v252, s0, 4
	s_nop 1
	v_writelane_b32 v252, s1, 5
	s_and_b32 s0, s54, 7
	s_cmp_lg_u32 s0, 0
	s_cbranch_scc0 .LBB0_463
	v_cmp_gt_u32_e32 vcc, 16, v0
	s_and_saveexec_b64 s[0:1], vcc

.LBB0_903:
	s_ashr_i32 s45, s44, 31
	s_lshl_b64 s[48:49], s[44:45], 20
	s_add_u32 s0, s10, s48
	s_addc_u32 s1, s11, s49
	s_ashr_i32 s41, s40, 31
	s_lshl_b64 s[50:51], s[40:41], 1
	s_add_u32 s48, s0, s50
	s_addc_u32 s49, s1, s51
	s_and_b64 s[58:59], s[46:47], exec
	s_cselect_b32 s41, s49, s9
	s_cselect_b32 s45, s48, s8
	s_ashr_i32 s43, s42, 31
	s_lshl_b64 s[58:59], s[42:43], 20
	s_add_u32 s0, s2, s58
	s_addc_u32 s1, s3, s59
	s_add_u32 s50, s0, s50
	s_addc_u32 s51, s1, s51
	s_and_b64 s[58:59], s[46:47], exec
	s_cselect_b32 s43, s51, s53
	s_cselect_b32 s65, s50, s52
	s_add_i32 s66, s62, -2
	s_add_u32 s67, s52, 0x100
	s_addc_u32 s68, s53, 0
	s_add_u32 s52, s8, 0x80080
	v_mov_b32_e32 v2, 0
	s_addc_u32 s53, s9, 0
	s_mov_b32 s8, 0
	v_mov_b32_e32 v3, v2
	v_mov_b32_e32 v4, v2
	v_mov_b32_e32 v5, v2
	v_mov_b32_e32 v10, v2
	v_mov_b32_e32 v11, v2
	v_mov_b32_e32 v12, v2
	v_mov_b32_e32 v13, v2
	v_mov_b32_e32 v18, v2
	v_mov_b32_e32 v19, v2
	v_mov_b32_e32 v20, v2
	v_mov_b32_e32 v21, v2
	v_mov_b32_e32 v26, v2
	v_mov_b32_e32 v27, v2
	v_mov_b32_e32 v28, v2
	v_mov_b32_e32 v29, v2
	v_mov_b32_e32 v34, v2
	v_mov_b32_e32 v35, v2
	v_mov_b32_e32 v36, v2
	v_mov_b32_e32 v37, v2
	v_mov_b32_e32 v42, v2
	v_mov_b32_e32 v43, v2
	v_mov_b32_e32 v44, v2
	v_mov_b32_e32 v45, v2
	v_mov_b32_e32 v50, v2
	v_mov_b32_e32 v51, v2
	v_mov_b32_e32 v52, v2
	v_mov_b32_e32 v53, v2
	v_mov_b32_e32 v58, v2
	v_mov_b32_e32 v59, v2
	v_mov_b32_e32 v60, v2
	v_mov_b32_e32 v61, v2
	v_mov_b32_e32 v6, v2
	v_mov_b32_e32 v7, v2
	v_mov_b32_e32 v8, v2
	v_mov_b32_e32 v9, v2
	v_mov_b32_e32 v14, v2
	v_mov_b32_e32 v15, v2
	v_mov_b32_e32 v16, v2
	v_mov_b32_e32 v17, v2
	v_mov_b32_e32 v22, v2
	v_mov_b32_e32 v23, v2
	v_mov_b32_e32 v24, v2
	v_mov_b32_e32 v25, v2
	v_mov_b32_e32 v30, v2
	v_mov_b32_e32 v31, v2
	v_mov_b32_e32 v32, v2
	v_mov_b32_e32 v33, v2
	v_mov_b32_e32 v38, v2
	v_mov_b32_e32 v39, v2
	v_mov_b32_e32 v40, v2
	v_mov_b32_e32 v41, v2
	s_nop 0
	v_mov_b32_e32 v46, v2
	v_mov_b32_e32 v47, v2
	v_mov_b32_e32 v48, v2
	v_mov_b32_e32 v49, v2
	v_mov_b32_e32 v54, v2
	v_mov_b32_e32 v55, v2
	v_mov_b32_e32 v56, v2
	v_mov_b32_e32 v57, v2
	v_mov_b32_e32 v62, v2
	v_mov_b32_e32 v63, v2
	v_mov_b32_e32 v64, v2
	v_mov_b32_e32 v65, v2
	v_mov_b32_e32 v66, v2
	v_mov_b32_e32 v67, v2
	v_mov_b32_e32 v68, v2
	v_mov_b32_e32 v69, v2
	v_mov_b32_e32 v74, v2
	v_mov_b32_e32 v75, v2
	v_mov_b32_e32 v76, v2
	v_mov_b32_e32 v77, v2
	v_mov_b32_e32 v82, v2
	v_mov_b32_e32 v83, v2
	v_mov_b32_e32 v84, v2
	v_mov_b32_e32 v85, v2
	v_mov_b32_e32 v90, v2
	v_mov_b32_e32 v91, v2
	v_mov_b32_e32 v92, v2
	v_mov_b32_e32 v93, v2
	v_mov_b32_e32 v98, v2
	v_mov_b32_e32 v99, v2
	v_mov_b32_e32 v100, v2
	v_mov_b32_e32 v101, v2
	v_mov_b32_e32 v106, v2
	v_mov_b32_e32 v107, v2
	v_mov_b32_e32 v108, v2
	v_mov_b32_e32 v109, v2
	v_mov_b32_e32 v114, v2
	v_mov_b32_e32 v115, v2
	v_mov_b32_e32 v116, v2
	v_mov_b32_e32 v117, v2
	v_mov_b32_e32 v122, v2
	v_mov_b32_e32 v123, v2
	v_mov_b32_e32 v124, v2
	v_mov_b32_e32 v125, v2
	v_mov_b32_e32 v70, v2
	v_mov_b32_e32 v71, v2
	v_mov_b32_e32 v72, v2
	v_mov_b32_e32 v73, v2
	v_mov_b32_e32 v78, v2
	v_mov_b32_e32 v79, v2
	v_mov_b32_e32 v80, v2
	v_mov_b32_e32 v81, v2
	v_mov_b32_e32 v86, v2
	v_mov_b32_e32 v87, v2
	v_mov_b32_e32 v88, v2
	v_mov_b32_e32 v89, v2
	v_mov_b32_e32 v94, v2
	v_mov_b32_e32 v95, v2
	v_mov_b32_e32 v96, v2
	v_mov_b32_e32 v97, v2
	v_mov_b32_e32 v102, v2
	v_mov_b32_e32 v103, v2
	v_mov_b32_e32 v104, v2
	v_mov_b32_e32 v105, v2
	v_mov_b32_e32 v110, v2
	v_mov_b32_e32 v111, v2
	v_mov_b32_e32 v112, v2
	v_mov_b32_e32 v113, v2
	v_mov_b32_e32 v118, v2
	v_mov_b32_e32 v119, v2
	v_mov_b32_e32 v120, v2
	v_mov_b32_e32 v121, v2
	v_mov_b32_e32 v126, v2
	v_mov_b32_e32 v127, v2
	v_mov_b32_e32 v128, v2
	v_mov_b32_e32 v129, v2
	s_cmp_eq_u32 s100, 1
	s_cbranch_scc0 .Ldefbar_skip_0
	s_mov_b32 s100, 0
	s_barrier
.Ldefbar_skip_0:
.LBB0_904:
	s_add_i32 s69, s8, 2
	s_add_u32 s0, s52, 0xfff80080
	s_addc_u32 s1, s53, -1
	s_add_i32 s70, 0, 0x10000
	s_cmp_eq_u32 s66, s8
	s_cselect_b32 s59, s41, s1
	s_cselect_b32 s58, s45, s0
	s_cselect_b32 s9, s43, s68
	s_cselect_b32 s8, s65, s67
	s_add_i32 s0, 0, 0x14000
	v_add_u32_e32 v156, s70, v141
	v_add_u32_e32 v172, s0, v141
	ds_read_b128 v[144:147], v156
	ds_read_b128 v[148:151], v156 offset:1024
	ds_read_b128 v[152:155], v156 offset:2048
	ds_read_b128 v[156:159], v156 offset:3072
	ds_read_b128 v[160:163], v172
	ds_read_b128 v[164:167], v172 offset:1024
	ds_read_b128 v[168:171], v172 offset:2048
	ds_read_b128 v[172:175], v172 offset:3072
	v_lshl_add_u64 v[214:215], s[52:53], 0, v[138:139]
	s_add_i32 m0, s27, 0xc000
	ds_read_b128 v[176:179], v143
	ds_read_b128 v[180:183], v143 offset:1024
	ds_read_b128 v[184:187], v143 offset:2048
	ds_read_b128 v[188:191], v143 offset:3072
	ds_read_b128 v[192:195], v143 offset:4096
	ds_read_b128 v[202:205], v143 offset:5120
	ds_read_b128 v[206:209], v143 offset:6144
	ds_read_b128 v[210:213], v143 offset:7168
	global_load_lds_dwordx4 v[214:215], off
	v_lshl_add_u64 v[214:215], s[52:53], 0, v[136:137]
	s_add_i32 m0, s27, 0xe000
	s_nop 0
	global_load_lds_dwordx4 v[214:215], off
	s_waitcnt vmcnt(8)
	s_waitcnt lgkmcnt(0)
	s_setprio 1
	s_barrier
	v_mfma_f32_16x16x32_bf16 v[126:129], v[144:147], v[176:179], v[126:129]
	v_mfma_f32_16x16x32_bf16 v[118:121], v[152:155], v[176:179], v[118:121]
	v_mfma_f32_16x16x32_bf16 v[110:113], v[144:147], v[184:187], v[110:113]
	v_mfma_f32_16x16x32_bf16 v[102:105], v[152:155], v[184:187], v[102:105]
	v_mfma_f32_16x16x32_bf16 v[94:97], v[144:147], v[192:195], v[94:97]
	v_mfma_f32_16x16x32_bf16 v[86:89], v[152:155], v[192:195], v[86:89]
	v_mfma_f32_16x16x32_bf16 v[78:81], v[144:147], v[206:209], v[78:81]
	v_mfma_f32_16x16x32_bf16 v[70:73], v[152:155], v[206:209], v[70:73]
	v_mfma_f32_16x16x32_bf16 v[126:129], v[148:151], v[180:183], v[126:129]
	v_mfma_f32_16x16x32_bf16 v[118:121], v[156:159], v[180:183], v[118:121]
	v_mfma_f32_16x16x32_bf16 v[110:113], v[148:151], v[188:191], v[110:113]
	v_mfma_f32_16x16x32_bf16 v[102:105], v[156:159], v[188:191], v[102:105]
	v_mfma_f32_16x16x32_bf16 v[94:97], v[148:151], v[202:205], v[94:97]
	v_mfma_f32_16x16x32_bf16 v[86:89], v[156:159], v[202:205], v[86:89]
	v_mfma_f32_16x16x32_bf16 v[78:81], v[148:151], v[210:213], v[78:81]
	v_mfma_f32_16x16x32_bf16 v[70:73], v[156:159], v[210:213], v[70:73]
	v_mfma_f32_16x16x32_bf16 v[122:125], v[160:163], v[176:179], v[122:125]
	v_mfma_f32_16x16x32_bf16 v[114:117], v[168:171], v[176:179], v[114:117]
	v_mfma_f32_16x16x32_bf16 v[106:109], v[160:163], v[184:187], v[106:109]
	v_mfma_f32_16x16x32_bf16 v[98:101], v[168:171], v[184:187], v[98:101]
	v_mfma_f32_16x16x32_bf16 v[90:93], v[160:163], v[192:195], v[90:93]
	v_mfma_f32_16x16x32_bf16 v[82:85], v[168:171], v[192:195], v[82:85]
	v_mfma_f32_16x16x32_bf16 v[74:77], v[160:163], v[206:209], v[74:77]
	v_mfma_f32_16x16x32_bf16 v[66:69], v[168:171], v[206:209], v[66:69]
	v_mfma_f32_16x16x32_bf16 v[122:125], v[164:167], v[180:183], v[122:125]
	v_mfma_f32_16x16x32_bf16 v[114:117], v[172:175], v[180:183], v[114:117]
	v_mfma_f32_16x16x32_bf16 v[106:109], v[164:167], v[188:191], v[106:109]
	v_mfma_f32_16x16x32_bf16 v[98:101], v[172:175], v[188:191], v[98:101]
	v_mfma_f32_16x16x32_bf16 v[90:93], v[164:167], v[202:205], v[90:93]
	v_mfma_f32_16x16x32_bf16 v[82:85], v[172:175], v[202:205], v[82:85]
	v_mfma_f32_16x16x32_bf16 v[74:77], v[164:167], v[210:213], v[74:77]
	v_mfma_f32_16x16x32_bf16 v[66:69], v[172:175], v[210:213], v[66:69]
	s_barrier
	s_setprio 0
	s_add_i32 s1, s70, s26
	v_lshl_add_u64 v[214:215], s[8:9], 0, v[196:197]
	s_mov_b32 m0, s1
	ds_read_b128 v[176:179], v143 offset:16384
	ds_read_b128 v[180:183], v143 offset:17408
	ds_read_b128 v[184:187], v143 offset:18432
	ds_read_b128 v[188:191], v143 offset:19456
	ds_read_b128 v[192:195], v143 offset:20480
	ds_read_b128 v[202:205], v143 offset:21504
	ds_read_b128 v[206:209], v143 offset:22528
	ds_read_b128 v[210:213], v143 offset:23552
	global_load_lds_dwordx4 v[214:215], off
	s_add_i32 m0, s1, 0x2000
	s_add_u32 s70, s8, 0x80000
	v_lshl_add_u64 v[216:217], s[8:9], 0, v[130:131]
	s_addc_u32 s71, s9, 0
	s_add_i32 s0, s0, s26
	global_load_lds_dwordx4 v[216:217], off
	v_lshl_add_u64 v[218:219], s[70:71], 0, v[196:197]
	s_mov_b32 m0, s0
	v_lshl_add_u64 v[220:221], s[58:59], 0, v[132:133]
	global_load_lds_dwordx4 v[218:219], off
	v_lshl_add_u64 v[218:219], s[70:71], 0, v[130:131]
	s_add_i32 m0, s0, 0x2000
	s_nop 0
	global_load_lds_dwordx4 v[218:219], off
	v_lshl_add_u64 v[218:219], s[58:59], 0, v[134:135]
	s_mov_b32 m0, s27
	s_nop 0
	global_load_lds_dwordx4 v[218:219], off
	s_mov_b32 m0, s28
	s_nop 0
	global_load_lds_dwordx4 v[220:221], off
	s_waitcnt vmcnt(8)
	s_waitcnt lgkmcnt(0)
	s_setprio 1
	s_barrier
	v_mfma_f32_16x16x32_bf16 v[62:65], v[144:147], v[176:179], v[62:65]
	v_mfma_f32_16x16x32_bf16 v[54:57], v[152:155], v[176:179], v[54:57]
	v_mfma_f32_16x16x32_bf16 v[46:49], v[144:147], v[184:187], v[46:49]
	v_mfma_f32_16x16x32_bf16 v[38:41], v[152:155], v[184:187], v[38:41]
	v_mfma_f32_16x16x32_bf16 v[30:33], v[144:147], v[192:195], v[30:33]
	v_mfma_f32_16x16x32_bf16 v[22:25], v[152:155], v[192:195], v[22:25]
	v_mfma_f32_16x16x32_bf16 v[14:17], v[144:147], v[206:209], v[14:17]
	v_mfma_f32_16x16x32_bf16 v[6:9], v[152:155], v[206:209], v[6:9]
	v_mfma_f32_16x16x32_bf16 v[62:65], v[148:151], v[180:183], v[62:65]
	v_mfma_f32_16x16x32_bf16 v[54:57], v[156:159], v[180:183], v[54:57]
	v_mfma_f32_16x16x32_bf16 v[46:49], v[148:151], v[188:191], v[46:49]
	v_mfma_f32_16x16x32_bf16 v[38:41], v[156:159], v[188:191], v[38:41]
	v_mfma_f32_16x16x32_bf16 v[30:33], v[148:151], v[202:205], v[30:33]
	v_mfma_f32_16x16x32_bf16 v[22:25], v[156:159], v[202:205], v[22:25]
	v_mfma_f32_16x16x32_bf16 v[14:17], v[148:151], v[210:213], v[14:17]
	v_mfma_f32_16x16x32_bf16 v[6:9], v[156:159], v[210:213], v[6:9]
	v_mfma_f32_16x16x32_bf16 v[58:61], v[160:163], v[176:179], v[58:61]
	v_mfma_f32_16x16x32_bf16 v[50:53], v[168:171], v[176:179], v[50:53]
	v_mfma_f32_16x16x32_bf16 v[42:45], v[160:163], v[184:187], v[42:45]
	v_mfma_f32_16x16x32_bf16 v[34:37], v[168:171], v[184:187], v[34:37]
	v_mfma_f32_16x16x32_bf16 v[26:29], v[160:163], v[192:195], v[26:29]
	v_mfma_f32_16x16x32_bf16 v[18:21], v[168:171], v[192:195], v[18:21]
	v_mfma_f32_16x16x32_bf16 v[10:13], v[160:163], v[206:209], v[10:13]
	v_mfma_f32_16x16x32_bf16 v[2:5], v[168:171], v[206:209], v[2:5]
	v_mfma_f32_16x16x32_bf16 v[58:61], v[164:167], v[180:183], v[58:61]
	v_mfma_f32_16x16x32_bf16 v[50:53], v[172:175], v[180:183], v[50:53]
	v_mfma_f32_16x16x32_bf16 v[42:45], v[164:167], v[188:191], v[42:45]
	v_mfma_f32_16x16x32_bf16 v[34:37], v[172:175], v[188:191], v[34:37]
	v_mfma_f32_16x16x32_bf16 v[26:29], v[164:167], v[202:205], v[26:29]
	v_mfma_f32_16x16x32_bf16 v[18:21], v[172:175], v[202:205], v[18:21]
	v_mfma_f32_16x16x32_bf16 v[10:13], v[164:167], v[210:213], v[10:13]
	v_mfma_f32_16x16x32_bf16 v[2:5], v[172:175], v[210:213], v[2:5]
	s_barrier
	s_setprio 0
	s_add_i32 s0, 0, 0x18000
	s_add_i32 s1, 0, 0x1c000
	v_add_u32_e32 v156, s0, v141
	v_add_u32_e32 v172, s1, v141
	ds_read_b128 v[144:147], v156
	ds_read_b128 v[148:151], v156 offset:1024
	ds_read_b128 v[152:155], v156 offset:2048
	ds_read_b128 v[156:159], v156 offset:3072
	ds_read_b128 v[160:163], v172
	ds_read_b128 v[164:167], v172 offset:1024
	ds_read_b128 v[168:171], v172 offset:2048
	ds_read_b128 v[172:175], v172 offset:3072
	s_add_u32 s58, s58, 0x80000
	s_addc_u32 s59, s59, 0
	s_mov_b32 m0, s29
	v_lshl_add_u64 v[222:223], s[58:59], 0, v[134:135]
	ds_read_b128 v[176:179], v143 offset:32768
	ds_read_b128 v[180:183], v143 offset:33792
	ds_read_b128 v[184:187], v143 offset:34816
	ds_read_b128 v[188:191], v143 offset:35840
	ds_read_b128 v[192:195], v143 offset:36864
	ds_read_b128 v[202:205], v143 offset:37888
	ds_read_b128 v[206:209], v143 offset:38912
	ds_read_b128 v[210:213], v143 offset:39936
	global_load_lds_dwordx4 v[222:223], off
	v_lshl_add_u64 v[222:223], s[58:59], 0, v[132:133]
	s_mov_b32 m0, s30
	s_nop 0
	global_load_lds_dwordx4 v[222:223], off
	s_waitcnt vmcnt(8)
	s_waitcnt lgkmcnt(0)
	s_setprio 1
	s_barrier
	v_mfma_f32_16x16x32_bf16 v[126:129], v[144:147], v[176:179], v[126:129]
	v_mfma_f32_16x16x32_bf16 v[118:121], v[152:155], v[176:179], v[118:121]
	v_mfma_f32_16x16x32_bf16 v[110:113], v[144:147], v[184:187], v[110:113]
	v_mfma_f32_16x16x32_bf16 v[102:105], v[152:155], v[184:187], v[102:105]
	v_mfma_f32_16x16x32_bf16 v[94:97], v[144:147], v[192:195], v[94:97]
	v_mfma_f32_16x16x32_bf16 v[86:89], v[152:155], v[192:195], v[86:89]
	v_mfma_f32_16x16x32_bf16 v[78:81], v[144:147], v[206:209], v[78:81]
	v_mfma_f32_16x16x32_bf16 v[70:73], v[152:155], v[206:209], v[70:73]
	v_mfma_f32_16x16x32_bf16 v[126:129], v[148:151], v[180:183], v[126:129]
	v_mfma_f32_16x16x32_bf16 v[118:121], v[156:159], v[180:183], v[118:121]
	v_mfma_f32_16x16x32_bf16 v[110:113], v[148:151], v[188:191], v[110:113]
	v_mfma_f32_16x16x32_bf16 v[102:105], v[156:159], v[188:191], v[102:105]
	v_mfma_f32_16x16x32_bf16 v[94:97], v[148:151], v[202:205], v[94:97]
	v_mfma_f32_16x16x32_bf16 v[86:89], v[156:159], v[202:205], v[86:89]
	v_mfma_f32_16x16x32_bf16 v[78:81], v[148:151], v[210:213], v[78:81]
	v_mfma_f32_16x16x32_bf16 v[70:73], v[156:159], v[210:213], v[70:73]
	v_mfma_f32_16x16x32_bf16 v[122:125], v[160:163], v[176:179], v[122:125]
	v_mfma_f32_16x16x32_bf16 v[114:117], v[168:171], v[176:179], v[114:117]
	v_mfma_f32_16x16x32_bf16 v[106:109], v[160:163], v[184:187], v[106:109]
	v_mfma_f32_16x16x32_bf16 v[98:101], v[168:171], v[184:187], v[98:101]
	v_mfma_f32_16x16x32_bf16 v[90:93], v[160:163], v[192:195], v[90:93]
	v_mfma_f32_16x16x32_bf16 v[82:85], v[168:171], v[192:195], v[82:85]
	v_mfma_f32_16x16x32_bf16 v[74:77], v[160:163], v[206:209], v[74:77]
	v_mfma_f32_16x16x32_bf16 v[66:69], v[168:171], v[206:209], v[66:69]
	v_mfma_f32_16x16x32_bf16 v[122:125], v[164:167], v[180:183], v[122:125]
	v_mfma_f32_16x16x32_bf16 v[114:117], v[172:175], v[180:183], v[114:117]
	v_mfma_f32_16x16x32_bf16 v[106:109], v[164:167], v[188:191], v[106:109]
	v_mfma_f32_16x16x32_bf16 v[98:101], v[172:175], v[188:191], v[98:101]
	v_mfma_f32_16x16x32_bf16 v[90:93], v[164:167], v[202:205], v[90:93]
	v_mfma_f32_16x16x32_bf16 v[82:85], v[172:175], v[202:205], v[82:85]
	v_mfma_f32_16x16x32_bf16 v[74:77], v[164:167], v[210:213], v[74:77]
	v_mfma_f32_16x16x32_bf16 v[66:69], v[172:175], v[210:213], v[66:69]
	s_barrier
	s_setprio 0
	s_add_i32 s0, s0, s26
	v_lshl_add_u64 v[214:215], v[214:215], 0, s[16:17]
	s_mov_b32 m0, s0
	ds_read_b128 v[176:179], v143 offset:49152
	ds_read_b128 v[180:183], v143 offset:50176
	ds_read_b128 v[184:187], v143 offset:51200
	ds_read_b128 v[188:191], v143 offset:52224
	ds_read_b128 v[192:195], v143 offset:53248
	ds_read_b128 v[202:205], v143 offset:54272
	ds_read_b128 v[206:209], v143 offset:55296
	ds_read_b128 v[210:213], v143 offset:56320
	global_load_lds_dwordx4 v[214:215], off
	s_add_i32 m0, s0, 0x2000
	s_add_u32 s8, s8, 0x80080
	v_lshl_add_u64 v[214:215], v[216:217], 0, s[16:17]
	s_addc_u32 s9, s9, 0
	s_add_i32 s0, s1, s26
	global_load_lds_dwordx4 v[214:215], off
	v_lshl_add_u64 v[214:215], s[8:9], 0, v[196:197]
	s_mov_b32 m0, s0
	s_nop 0
	global_load_lds_dwordx4 v[214:215], off
	v_lshl_add_u64 v[214:215], s[8:9], 0, v[130:131]
	s_add_i32 m0, s0, 0x2000
	s_nop 0
	global_load_lds_dwordx4 v[214:215], off
	v_lshl_add_u64 v[214:215], v[218:219], 0, s[16:17]
	s_mov_b32 m0, s31
	s_nop 0
	global_load_lds_dwordx4 v[214:215], off
	v_lshl_add_u64 v[214:215], v[220:221], 0, s[16:17]
	s_mov_b32 m0, s34
	s_nop 0
	global_load_lds_dwordx4 v[214:215], off
	s_waitcnt vmcnt(8)
	s_waitcnt lgkmcnt(0)
	s_setprio 1
	s_barrier
	v_mfma_f32_16x16x32_bf16 v[62:65], v[144:147], v[176:179], v[62:65]
	v_mfma_f32_16x16x32_bf16 v[54:57], v[152:155], v[176:179], v[54:57]
	v_mfma_f32_16x16x32_bf16 v[46:49], v[144:147], v[184:187], v[46:49]
	v_mfma_f32_16x16x32_bf16 v[38:41], v[152:155], v[184:187], v[38:41]
	v_mfma_f32_16x16x32_bf16 v[30:33], v[144:147], v[192:195], v[30:33]
	v_mfma_f32_16x16x32_bf16 v[22:25], v[152:155], v[192:195], v[22:25]
	v_mfma_f32_16x16x32_bf16 v[14:17], v[144:147], v[206:209], v[14:17]
	v_mfma_f32_16x16x32_bf16 v[6:9], v[152:155], v[206:209], v[6:9]
	v_mfma_f32_16x16x32_bf16 v[62:65], v[148:151], v[180:183], v[62:65]
	v_mfma_f32_16x16x32_bf16 v[54:57], v[156:159], v[180:183], v[54:57]
	v_mfma_f32_16x16x32_bf16 v[46:49], v[148:151], v[188:191], v[46:49]
	v_mfma_f32_16x16x32_bf16 v[38:41], v[156:159], v[188:191], v[38:41]
	v_mfma_f32_16x16x32_bf16 v[30:33], v[148:151], v[202:205], v[30:33]
	v_mfma_f32_16x16x32_bf16 v[22:25], v[156:159], v[202:205], v[22:25]
	v_mfma_f32_16x16x32_bf16 v[14:17], v[148:151], v[210:213], v[14:17]
	v_mfma_f32_16x16x32_bf16 v[6:9], v[156:159], v[210:213], v[6:9]
	v_mfma_f32_16x16x32_bf16 v[58:61], v[160:163], v[176:179], v[58:61]
	v_mfma_f32_16x16x32_bf16 v[50:53], v[168:171], v[176:179], v[50:53]
	v_mfma_f32_16x16x32_bf16 v[42:45], v[160:163], v[184:187], v[42:45]
	v_mfma_f32_16x16x32_bf16 v[34:37], v[168:171], v[184:187], v[34:37]
	v_mfma_f32_16x16x32_bf16 v[26:29], v[160:163], v[192:195], v[26:29]
	v_mfma_f32_16x16x32_bf16 v[18:21], v[168:171], v[192:195], v[18:21]
	v_mfma_f32_16x16x32_bf16 v[10:13], v[160:163], v[206:209], v[10:13]
	v_mfma_f32_16x16x32_bf16 v[2:5], v[168:171], v[206:209], v[2:5]
	v_mfma_f32_16x16x32_bf16 v[58:61], v[164:167], v[180:183], v[58:61]
	v_mfma_f32_16x16x32_bf16 v[50:53], v[172:175], v[180:183], v[50:53]
	v_mfma_f32_16x16x32_bf16 v[42:45], v[164:167], v[188:191], v[42:45]
	v_mfma_f32_16x16x32_bf16 v[34:37], v[172:175], v[188:191], v[34:37]
	v_mfma_f32_16x16x32_bf16 v[26:29], v[164:167], v[202:205], v[26:29]
	v_mfma_f32_16x16x32_bf16 v[18:21], v[172:175], v[202:205], v[18:21]
	v_mfma_f32_16x16x32_bf16 v[10:13], v[164:167], v[210:213], v[10:13]
	v_mfma_f32_16x16x32_bf16 v[2:5], v[172:175], v[210:213], v[2:5]
	s_barrier
	s_setprio 0
	s_add_u32 s67, s67, 0x100
	s_addc_u32 s68, s68, 0
	s_add_u32 s52, s52, 0x100
	s_addc_u32 s53, s53, 0
	s_cmp_ge_i32 s69, s62
	s_mov_b32 s8, s69
	s_cbranch_scc0 .LBB0_904
	s_and_b64 vcc, exec, s[38:39]
	s_cbranch_vccz .LBB0_907
	s_barrier
.LBB0_907:
	v_mul_f32_e32 v145, 0xbfb8aa3b, v126
	v_exp_f32_e32 v145, v145
	v_lshl_or_b32 v146, s63, 7, v142
	v_lshl_add_u32 v144, s64, 8, v140
	v_ashrrev_i32_e32 v147, 31, v146
	v_add_f32_e32 v145, 1.0, v145
	v_rcp_f32_e32 v145, v145
	s_movk_i32 s0, 0x2b00
	s_andn2_b64 vcc, exec, s[46:47]
	s_mov_b64 s[66:67], 0x3000
	v_mul_f32_e32 v126, v126, v145
	v_mul_f32_e32 v122, v126, v122
	v_mul_f32_e32 v126, 0xbfb8aa3b, v118
	v_exp_f32_e32 v126, v126
	s_nop 0
	v_add_f32_e32 v126, 1.0, v126
	v_rcp_f32_e32 v126, v126
	s_nop 0
	v_mul_f32_e32 v118, v118, v126
	v_mul_f32_e32 v114, v118, v114
	v_mul_f32_e32 v118, 0xbfb8aa3b, v127
	v_exp_f32_e32 v118, v118
	s_nop 0
	v_add_f32_e32 v118, 1.0, v118
	v_rcp_f32_e32 v118, v118
	s_nop 0
	v_mul_f32_e32 v118, v127, v118
	v_mul_f32_e32 v118, v118, v123
	v_mul_f32_e32 v123, 0xbfb8aa3b, v119
	v_exp_f32_e32 v123, v123
	v_cvt_pk_bf16_f32 v118, v122, v118
	s_nop 0
	v_add_f32_e32 v123, 1.0, v123
	v_rcp_f32_e32 v123, v123
	s_nop 0
	v_mul_f32_e32 v119, v119, v123
	v_mul_f32_e32 v123, 0xbfb8aa3b, v120
	v_exp_f32_e32 v123, v123
	v_mul_f32_e32 v115, v119, v115
	v_mul_f32_e32 v119, 0xbfb8aa3b, v128
	v_exp_f32_e32 v119, v119
	v_add_f32_e32 v123, 1.0, v123
	v_rcp_f32_e32 v123, v123
	v_add_f32_e32 v119, 1.0, v119
	v_rcp_f32_e32 v119, v119
	v_mul_f32_e32 v120, v120, v123
	v_mul_f32_e32 v116, v120, v116
	v_mul_f32_e32 v120, 0xbfb8aa3b, v129
	v_exp_f32_e32 v120, v120
	v_mul_f32_e32 v123, 0xbfb8aa3b, v121
	v_exp_f32_e32 v123, v123
	v_mul_f32_e32 v119, v128, v119
	v_add_f32_e32 v120, 1.0, v120
	v_rcp_f32_e32 v120, v120
	v_add_f32_e32 v123, 1.0, v123
	v_rcp_f32_e32 v123, v123
	v_mul_f32_e32 v119, v119, v124
	v_mul_f32_e32 v120, v129, v120
	v_mul_f32_e32 v120, v120, v125
	v_mul_f32_e32 v121, v121, v123
	v_mul_f32_e32 v117, v121, v117
	v_cvt_pk_bf16_f32 v119, v119, v120
	v_cvt_pk_bf16_f32 v120, v114, v115
	v_mov_b64_e32 v[114:115], s[6:7]
	v_cvt_pk_bf16_f32 v121, v116, v117
	v_mad_i64_i32 v[122:123], s[8:9], v144, s0, v[114:115]
	v_lshlrev_b64 v[116:117], 1, v[146:147]
	v_lshl_add_u64 v[122:123], v[122:123], 0, v[116:117]
	global_store_dwordx4 v[122:123], v[118:121], off
	s_nop 1
	v_mul_f32_e32 v118, 0xbfb8aa3b, v110
	v_exp_f32_e32 v118, v118
	s_nop 0
	v_add_f32_e32 v118, 1.0, v118
	v_rcp_f32_e32 v118, v118
	s_nop 0
	v_mul_f32_e32 v110, v110, v118
	v_mul_f32_e32 v106, v110, v106
	v_mul_f32_e32 v110, 0xbfb8aa3b, v102
	v_exp_f32_e32 v110, v110
	s_nop 0
	v_add_f32_e32 v110, 1.0, v110
	v_rcp_f32_e32 v110, v110
	s_nop 0
	v_mul_f32_e32 v102, v102, v110
	v_mul_f32_e32 v102, v102, v98
	v_mul_f32_e32 v98, 0xbfb8aa3b, v111
	v_exp_f32_e32 v98, v98
	s_nop 0
	v_add_f32_e32 v98, 1.0, v98
	v_rcp_f32_e32 v98, v98
	s_nop 0
	v_mul_f32_e32 v98, v111, v98
	v_mul_f32_e32 v98, v98, v107
	v_mul_f32_e32 v107, 0xbfb8aa3b, v103
	v_exp_f32_e32 v107, v107
	v_cvt_pk_bf16_f32 v98, v106, v98
	s_nop 0
	v_add_f32_e32 v107, 1.0, v107
	v_rcp_f32_e32 v107, v107
	s_nop 0
	v_mul_f32_e32 v103, v103, v107
	v_mul_f32_e32 v107, 0xbfb8aa3b, v104
	v_exp_f32_e32 v107, v107
	v_mul_f32_e32 v103, v103, v99
	v_mul_f32_e32 v99, 0xbfb8aa3b, v112
	v_exp_f32_e32 v99, v99
	v_add_f32_e32 v107, 1.0, v107
	v_rcp_f32_e32 v107, v107
	v_add_f32_e32 v99, 1.0, v99
	v_rcp_f32_e32 v99, v99
	v_mul_f32_e32 v104, v104, v107
	v_mul_f32_e32 v104, v104, v100
	v_mul_f32_e32 v100, 0xbfb8aa3b, v113
	v_exp_f32_e32 v100, v100
	v_mul_f32_e32 v107, 0xbfb8aa3b, v105
	v_exp_f32_e32 v107, v107
	v_mul_f32_e32 v99, v112, v99
	v_add_f32_e32 v100, 1.0, v100
	v_rcp_f32_e32 v100, v100
	v_add_f32_e32 v107, 1.0, v107
	v_rcp_f32_e32 v107, v107
	v_mul_f32_e32 v99, v99, v108
	v_mul_f32_e32 v100, v113, v100
	v_mul_f32_e32 v100, v100, v109
	v_cvt_pk_bf16_f32 v99, v99, v100
	v_cvt_pk_bf16_f32 v100, v102, v103
	v_or_b32_e32 v102, 16, v144
	v_mul_f32_e32 v105, v105, v107
	v_mad_i64_i32 v[102:103], s[8:9], v102, s0, v[114:115]
	v_mul_f32_e32 v101, v105, v101
	v_lshl_add_u64 v[102:103], v[102:103], 0, v[116:117]
	v_cvt_pk_bf16_f32 v101, v104, v101
	global_store_dwordx4 v[102:103], v[98:101], off
	s_nop 1
	v_mul_f32_e32 v98, 0xbfb8aa3b, v94
	v_exp_f32_e32 v98, v98
	s_nop 0
	v_add_f32_e32 v98, 1.0, v98
	v_rcp_f32_e32 v98, v98
	s_nop 0
	v_mul_f32_e32 v94, v94, v98
	v_mul_f32_e32 v90, v94, v90
	v_mul_f32_e32 v94, 0xbfb8aa3b, v86
	v_exp_f32_e32 v94, v94
	s_nop 0
	v_add_f32_e32 v94, 1.0, v94
	v_rcp_f32_e32 v94, v94
	s_nop 0
	v_mul_f32_e32 v86, v86, v94
	v_mul_f32_e32 v86, v86, v82
	v_mul_f32_e32 v82, 0xbfb8aa3b, v95
	v_exp_f32_e32 v82, v82
	s_nop 0
	v_add_f32_e32 v82, 1.0, v82
	v_rcp_f32_e32 v82, v82
	s_nop 0
	v_mul_f32_e32 v82, v95, v82
	v_mul_f32_e32 v82, v82, v91
	v_mul_f32_e32 v91, 0xbfb8aa3b, v87
	v_exp_f32_e32 v91, v91
	v_cvt_pk_bf16_f32 v82, v90, v82
	s_nop 0
	v_add_f32_e32 v91, 1.0, v91
	v_rcp_f32_e32 v91, v91
	s_nop 0
	v_mul_f32_e32 v87, v87, v91
	v_mul_f32_e32 v91, 0xbfb8aa3b, v88
	v_exp_f32_e32 v91, v91
	v_mul_f32_e32 v87, v87, v83
	v_mul_f32_e32 v83, 0xbfb8aa3b, v96
	v_exp_f32_e32 v83, v83
	v_add_f32_e32 v91, 1.0, v91
	v_rcp_f32_e32 v91, v91
	v_add_f32_e32 v83, 1.0, v83
	v_rcp_f32_e32 v83, v83
	v_mul_f32_e32 v88, v88, v91
	v_mul_f32_e32 v88, v88, v84
	v_mul_f32_e32 v84, 0xbfb8aa3b, v97
	v_exp_f32_e32 v84, v84
	v_mul_f32_e32 v91, 0xbfb8aa3b, v89
	v_exp_f32_e32 v91, v91
	v_mul_f32_e32 v83, v96, v83
	v_add_f32_e32 v84, 1.0, v84
	v_rcp_f32_e32 v84, v84
	v_add_f32_e32 v91, 1.0, v91
	v_rcp_f32_e32 v91, v91
	v_mul_f32_e32 v83, v83, v92
	v_mul_f32_e32 v84, v97, v84
	v_mul_f32_e32 v84, v84, v93
	v_cvt_pk_bf16_f32 v83, v83, v84
	v_cvt_pk_bf16_f32 v84, v86, v87
	v_or_b32_e32 v86, 32, v144
	v_mul_f32_e32 v89, v89, v91
	v_mad_i64_i32 v[86:87], s[8:9], v86, s0, v[114:115]
	v_mul_f32_e32 v85, v89, v85
	v_lshl_add_u64 v[86:87], v[86:87], 0, v[116:117]
	v_cvt_pk_bf16_f32 v85, v88, v85
	global_store_dwordx4 v[86:87], v[82:85], off
	s_nop 1
	v_mul_f32_e32 v82, 0xbfb8aa3b, v78
	v_exp_f32_e32 v82, v82
	s_nop 0
	v_add_f32_e32 v82, 1.0, v82
	v_rcp_f32_e32 v82, v82
	s_nop 0
	v_mul_f32_e32 v78, v78, v82
	v_mul_f32_e32 v74, v78, v74
	v_mul_f32_e32 v78, 0xbfb8aa3b, v70
	v_exp_f32_e32 v78, v78
	s_nop 0
	v_add_f32_e32 v78, 1.0, v78
	v_rcp_f32_e32 v78, v78
	s_nop 0
	v_mul_f32_e32 v70, v70, v78
	v_mul_f32_e32 v70, v70, v66
	v_mul_f32_e32 v66, 0xbfb8aa3b, v79
	v_exp_f32_e32 v66, v66
	s_nop 0
	v_add_f32_e32 v66, 1.0, v66
	v_rcp_f32_e32 v66, v66
	s_nop 0
	v_mul_f32_e32 v66, v79, v66
	v_mul_f32_e32 v66, v66, v75
	v_mul_f32_e32 v75, 0xbfb8aa3b, v71
	v_exp_f32_e32 v75, v75
	v_cvt_pk_bf16_f32 v66, v74, v66
	s_nop 0
	v_add_f32_e32 v75, 1.0, v75
	v_rcp_f32_e32 v75, v75
	s_nop 0
	v_mul_f32_e32 v71, v71, v75
	v_mul_f32_e32 v75, 0xbfb8aa3b, v72
	v_exp_f32_e32 v75, v75
	v_mul_f32_e32 v71, v71, v67
	v_mul_f32_e32 v67, 0xbfb8aa3b, v80
	v_exp_f32_e32 v67, v67
	v_add_f32_e32 v75, 1.0, v75
	v_rcp_f32_e32 v75, v75
	v_add_f32_e32 v67, 1.0, v67
	v_rcp_f32_e32 v67, v67
	v_mul_f32_e32 v72, v72, v75
	v_mul_f32_e32 v72, v72, v68
	v_mul_f32_e32 v68, 0xbfb8aa3b, v81
	v_exp_f32_e32 v68, v68
	v_mul_f32_e32 v75, 0xbfb8aa3b, v73
	v_exp_f32_e32 v75, v75
	v_mul_f32_e32 v67, v80, v67
	v_add_f32_e32 v68, 1.0, v68
	v_rcp_f32_e32 v68, v68
	v_add_f32_e32 v75, 1.0, v75
	v_rcp_f32_e32 v75, v75
	v_mul_f32_e32 v67, v67, v76
	v_mul_f32_e32 v68, v81, v68
	v_mul_f32_e32 v68, v68, v77
	v_cvt_pk_bf16_f32 v67, v67, v68
	v_cvt_pk_bf16_f32 v68, v70, v71
	v_or_b32_e32 v70, 48, v144
	v_mul_f32_e32 v73, v73, v75
	v_mad_i64_i32 v[70:71], s[8:9], v70, s0, v[114:115]
	v_mul_f32_e32 v69, v73, v69
	v_lshl_add_u64 v[70:71], v[70:71], 0, v[116:117]
	v_cvt_pk_bf16_f32 v69, v72, v69
	global_store_dwordx4 v[70:71], v[66:69], off
	s_nop 1
	v_mul_f32_e32 v67, 0xbfb8aa3b, v62
	v_exp_f32_e32 v67, v67
	v_add_u32_e32 v66, 0x80, v144
	v_add_f32_e32 v67, 1.0, v67
	v_rcp_f32_e32 v67, v67
	s_nop 0
	v_mul_f32_e32 v62, v62, v67
	v_mul_f32_e32 v58, v62, v58
	v_mul_f32_e32 v62, 0xbfb8aa3b, v54
	v_exp_f32_e32 v62, v62
	s_nop 0
	v_add_f32_e32 v62, 1.0, v62
	v_rcp_f32_e32 v62, v62
	s_nop 0
	v_mul_f32_e32 v54, v54, v62
	v_mul_f32_e32 v54, v54, v50
	v_mul_f32_e32 v50, 0xbfb8aa3b, v63
	v_exp_f32_e32 v50, v50
	s_nop 0
	v_add_f32_e32 v50, 1.0, v50
	v_rcp_f32_e32 v50, v50
	s_nop 0
	v_mul_f32_e32 v50, v63, v50
	v_mul_f32_e32 v50, v50, v59
	v_mul_f32_e32 v59, 0xbfb8aa3b, v55
	v_exp_f32_e32 v59, v59
	v_cvt_pk_bf16_f32 v50, v58, v50
	s_nop 0
	v_add_f32_e32 v59, 1.0, v59
	v_rcp_f32_e32 v59, v59
	s_nop 0
	v_mul_f32_e32 v55, v55, v59
	v_mul_f32_e32 v59, 0xbfb8aa3b, v56
	v_exp_f32_e32 v59, v59
	v_mul_f32_e32 v55, v55, v51
	v_mul_f32_e32 v51, 0xbfb8aa3b, v64
	v_exp_f32_e32 v51, v51
	v_add_f32_e32 v59, 1.0, v59
	v_rcp_f32_e32 v59, v59
	v_add_f32_e32 v51, 1.0, v51
	v_rcp_f32_e32 v51, v51
	v_mul_f32_e32 v56, v56, v59
	v_mul_f32_e32 v56, v56, v52
	v_mul_f32_e32 v52, 0xbfb8aa3b, v65
	v_exp_f32_e32 v52, v52
	v_mul_f32_e32 v59, 0xbfb8aa3b, v57
	v_exp_f32_e32 v59, v59
	v_mul_f32_e32 v51, v64, v51
	v_add_f32_e32 v52, 1.0, v52
	v_rcp_f32_e32 v52, v52
	v_add_f32_e32 v59, 1.0, v59
	v_rcp_f32_e32 v59, v59
	v_mul_f32_e32 v51, v51, v60
	v_mul_f32_e32 v52, v65, v52
	v_mul_f32_e32 v52, v52, v61
	v_mul_f32_e32 v57, v57, v59
	v_cvt_pk_bf16_f32 v51, v51, v52
	v_cvt_pk_bf16_f32 v52, v54, v55
	v_mad_i64_i32 v[54:55], s[8:9], v66, s0, v[114:115]
	v_mul_f32_e32 v53, v57, v53
	v_lshl_add_u64 v[54:55], v[54:55], 0, v[116:117]
	v_cvt_pk_bf16_f32 v53, v56, v53
	global_store_dwordx4 v[54:55], v[50:53], off
	s_nop 1
	v_mul_f32_e32 v50, 0xbfb8aa3b, v46
	v_exp_f32_e32 v50, v50
	s_nop 0
	v_add_f32_e32 v50, 1.0, v50
	v_rcp_f32_e32 v50, v50
	s_nop 0
	v_mul_f32_e32 v46, v46, v50
	v_mul_f32_e32 v42, v46, v42
	v_mul_f32_e32 v46, 0xbfb8aa3b, v38
	v_exp_f32_e32 v46, v46
	s_nop 0
	v_add_f32_e32 v46, 1.0, v46
	v_rcp_f32_e32 v46, v46
	s_nop 0
	v_mul_f32_e32 v38, v38, v46
	v_mul_f32_e32 v38, v38, v34
	v_mul_f32_e32 v34, 0xbfb8aa3b, v47
	v_exp_f32_e32 v34, v34
	s_nop 0
	v_add_f32_e32 v34, 1.0, v34
	v_rcp_f32_e32 v34, v34
	s_nop 0
	v_mul_f32_e32 v34, v47, v34
	v_mul_f32_e32 v34, v34, v43
	v_mul_f32_e32 v43, 0xbfb8aa3b, v39
	v_exp_f32_e32 v43, v43
	v_cvt_pk_bf16_f32 v34, v42, v34
	s_nop 0
	v_add_f32_e32 v43, 1.0, v43
	v_rcp_f32_e32 v43, v43
	s_nop 0
	v_mul_f32_e32 v39, v39, v43
	v_mul_f32_e32 v43, 0xbfb8aa3b, v40
	v_exp_f32_e32 v43, v43
	v_mul_f32_e32 v39, v39, v35
	v_mul_f32_e32 v35, 0xbfb8aa3b, v48
	v_exp_f32_e32 v35, v35
	v_add_f32_e32 v43, 1.0, v43
	v_rcp_f32_e32 v43, v43
	v_add_f32_e32 v35, 1.0, v35
	v_rcp_f32_e32 v35, v35
	v_mul_f32_e32 v40, v40, v43
	v_mul_f32_e32 v40, v40, v36
	v_mul_f32_e32 v36, 0xbfb8aa3b, v49
	v_exp_f32_e32 v36, v36
	v_mul_f32_e32 v43, 0xbfb8aa3b, v41
	v_exp_f32_e32 v43, v43
	v_mul_f32_e32 v35, v48, v35
	v_add_f32_e32 v36, 1.0, v36
	v_rcp_f32_e32 v36, v36
	v_add_f32_e32 v43, 1.0, v43
	v_rcp_f32_e32 v43, v43
	v_mul_f32_e32 v35, v35, v44
	v_mul_f32_e32 v36, v49, v36
	v_mul_f32_e32 v36, v36, v45
	v_cvt_pk_bf16_f32 v35, v35, v36
	v_cvt_pk_bf16_f32 v36, v38, v39
	v_add_u32_e32 v38, 0x90, v144
	v_mul_f32_e32 v41, v41, v43
	v_mad_i64_i32 v[38:39], s[8:9], v38, s0, v[114:115]
	v_mul_f32_e32 v37, v41, v37
	v_lshl_add_u64 v[38:39], v[38:39], 0, v[116:117]
	v_cvt_pk_bf16_f32 v37, v40, v37
	global_store_dwordx4 v[38:39], v[34:37], off
	s_nop 1
	v_mul_f32_e32 v34, 0xbfb8aa3b, v30
	v_exp_f32_e32 v34, v34
	s_nop 0
	v_add_f32_e32 v34, 1.0, v34
	v_rcp_f32_e32 v34, v34
	s_nop 0
	v_mul_f32_e32 v30, v30, v34
	v_mul_f32_e32 v26, v30, v26
	v_mul_f32_e32 v30, 0xbfb8aa3b, v22
	v_exp_f32_e32 v30, v30
	s_nop 0
	v_add_f32_e32 v30, 1.0, v30
	v_rcp_f32_e32 v30, v30
	s_nop 0
	v_mul_f32_e32 v22, v22, v30
	v_mul_f32_e32 v22, v22, v18
	v_mul_f32_e32 v18, 0xbfb8aa3b, v31
	v_exp_f32_e32 v18, v18
	s_nop 0
	v_add_f32_e32 v18, 1.0, v18
	v_rcp_f32_e32 v18, v18
	s_nop 0
	v_mul_f32_e32 v18, v31, v18
	v_mul_f32_e32 v18, v18, v27
	v_mul_f32_e32 v27, 0xbfb8aa3b, v23
	v_exp_f32_e32 v27, v27
	v_cvt_pk_bf16_f32 v18, v26, v18
	s_nop 0
	v_add_f32_e32 v27, 1.0, v27
	v_rcp_f32_e32 v27, v27
	s_nop 0
	v_mul_f32_e32 v23, v23, v27
	v_mul_f32_e32 v27, 0xbfb8aa3b, v24
	v_exp_f32_e32 v27, v27
	v_mul_f32_e32 v23, v23, v19
	v_mul_f32_e32 v19, 0xbfb8aa3b, v32
	v_exp_f32_e32 v19, v19
	v_add_f32_e32 v27, 1.0, v27
	v_rcp_f32_e32 v27, v27
	v_add_f32_e32 v19, 1.0, v19
	v_rcp_f32_e32 v19, v19
	v_mul_f32_e32 v24, v24, v27
	v_mul_f32_e32 v24, v24, v20
	v_mul_f32_e32 v20, 0xbfb8aa3b, v33
	v_exp_f32_e32 v20, v20
	v_mul_f32_e32 v27, 0xbfb8aa3b, v25
	v_exp_f32_e32 v27, v27
	v_mul_f32_e32 v19, v32, v19
	v_add_f32_e32 v20, 1.0, v20
	v_rcp_f32_e32 v20, v20
	v_add_f32_e32 v27, 1.0, v27
	v_rcp_f32_e32 v27, v27
	v_mul_f32_e32 v19, v19, v28
	v_mul_f32_e32 v20, v33, v20
	v_mul_f32_e32 v20, v20, v29
	v_cvt_pk_bf16_f32 v19, v19, v20
	v_cvt_pk_bf16_f32 v20, v22, v23
	v_add_u32_e32 v22, 0xa0, v144
	v_mul_f32_e32 v25, v25, v27
	v_mad_i64_i32 v[22:23], s[8:9], v22, s0, v[114:115]
	v_mul_f32_e32 v21, v25, v21
	v_lshl_add_u64 v[22:23], v[22:23], 0, v[116:117]
	v_cvt_pk_bf16_f32 v21, v24, v21
	global_store_dwordx4 v[22:23], v[18:21], off
	s_nop 1
	v_mul_f32_e32 v18, 0xbfb8aa3b, v14
	v_exp_f32_e32 v18, v18
	s_nop 0
	v_add_f32_e32 v18, 1.0, v18
	v_rcp_f32_e32 v18, v18
	s_nop 0
	v_mul_f32_e32 v14, v14, v18
	v_mul_f32_e32 v10, v14, v10
	v_mul_f32_e32 v14, 0xbfb8aa3b, v6
	v_exp_f32_e32 v14, v14
	s_nop 0
	v_add_f32_e32 v14, 1.0, v14
	v_rcp_f32_e32 v14, v14
	s_nop 0
	v_mul_f32_e32 v6, v6, v14
	v_mul_f32_e32 v6, v6, v2
	v_mul_f32_e32 v2, 0xbfb8aa3b, v15
	v_exp_f32_e32 v2, v2
	s_nop 0
	v_add_f32_e32 v2, 1.0, v2
	v_rcp_f32_e32 v2, v2
	s_nop 0
	v_mul_f32_e32 v2, v15, v2
	v_mul_f32_e32 v2, v2, v11
	v_mul_f32_e32 v11, 0xbfb8aa3b, v7
	v_exp_f32_e32 v11, v11
	v_cvt_pk_bf16_f32 v2, v10, v2
	s_nop 0
	v_add_f32_e32 v11, 1.0, v11
	v_rcp_f32_e32 v11, v11
	s_nop 0
	v_mul_f32_e32 v7, v7, v11
	v_mul_f32_e32 v11, 0xbfb8aa3b, v8
	v_exp_f32_e32 v11, v11
	v_mul_f32_e32 v7, v7, v3
	v_mul_f32_e32 v3, 0xbfb8aa3b, v16
	v_exp_f32_e32 v3, v3
	v_add_f32_e32 v11, 1.0, v11
	v_rcp_f32_e32 v11, v11
	v_add_f32_e32 v3, 1.0, v3
	v_rcp_f32_e32 v3, v3
	v_mul_f32_e32 v8, v8, v11
	v_mul_f32_e32 v8, v8, v4
	v_mul_f32_e32 v4, 0xbfb8aa3b, v17
	v_exp_f32_e32 v4, v4
	v_mul_f32_e32 v11, 0xbfb8aa3b, v9
	v_exp_f32_e32 v11, v11
	v_mul_f32_e32 v3, v16, v3
	v_add_f32_e32 v4, 1.0, v4
	v_rcp_f32_e32 v4, v4
	v_add_f32_e32 v11, 1.0, v11
	v_rcp_f32_e32 v11, v11
	v_mul_f32_e32 v3, v3, v12
	v_mul_f32_e32 v4, v17, v4
	v_mul_f32_e32 v4, v4, v13
	v_cvt_pk_bf16_f32 v3, v3, v4
	v_cvt_pk_bf16_f32 v4, v6, v7
	v_add_u32_e32 v6, 0xb0, v144
	v_mul_f32_e32 v9, v9, v11
	v_mad_i64_i32 v[6:7], s[8:9], v6, s0, v[114:115]
	v_mul_f32_e32 v5, v9, v5
	v_lshl_add_u64 v[6:7], v[6:7], 0, v[116:117]
	s_mov_b64 s[8:9], -1
	v_cvt_pk_bf16_f32 v5, v8, v5
	global_store_dwordx4 v[6:7], v[2:5], off
	s_cbranch_vccnz .LBB0_894
	s_andn2_b64 vcc, exec, s[4:5]
	s_cbranch_vccnz .LBB0_893
	s_mov_b32 s100, 1
	s_branch .LBB0_893

.LBB0_986:
	s_add_i32 s41, s69, -2
	s_add_u32 s70, s8, 0x100
	v_mov_b32_e32 v2, 0
	s_addc_u32 s71, s9, 0
	s_mov_b32 s50, 0
	v_mov_b32_e32 v3, v2
	v_mov_b32_e32 v4, v2
	v_mov_b32_e32 v5, v2
	v_mov_b32_e32 v6, v2
	v_mov_b32_e32 v7, v2
	v_mov_b32_e32 v8, v2
	v_mov_b32_e32 v9, v2
	v_mov_b32_e32 v14, v2
	v_mov_b32_e32 v15, v2
	v_mov_b32_e32 v16, v2
	v_mov_b32_e32 v17, v2
	v_mov_b32_e32 v22, v2
	v_mov_b32_e32 v23, v2
	v_mov_b32_e32 v24, v2
	v_mov_b32_e32 v25, v2
	v_mov_b32_e32 v30, v2
	v_mov_b32_e32 v31, v2
	v_mov_b32_e32 v32, v2
	v_mov_b32_e32 v33, v2
	v_mov_b32_e32 v38, v2
	v_mov_b32_e32 v39, v2
	v_mov_b32_e32 v40, v2
	v_mov_b32_e32 v41, v2
	s_nop 0
	v_mov_b32_e32 v46, v2
	v_mov_b32_e32 v47, v2
	v_mov_b32_e32 v48, v2
	v_mov_b32_e32 v49, v2
	v_mov_b32_e32 v54, v2
	v_mov_b32_e32 v55, v2
	v_mov_b32_e32 v56, v2
	v_mov_b32_e32 v57, v2
	v_mov_b32_e32 v10, v2
	v_mov_b32_e32 v11, v2
	v_mov_b32_e32 v12, v2
	v_mov_b32_e32 v13, v2
	v_mov_b32_e32 v18, v2
	v_mov_b32_e32 v19, v2
	v_mov_b32_e32 v20, v2
	v_mov_b32_e32 v21, v2
	v_mov_b32_e32 v26, v2
	v_mov_b32_e32 v27, v2
	v_mov_b32_e32 v28, v2
	v_mov_b32_e32 v29, v2
	v_mov_b32_e32 v34, v2
	v_mov_b32_e32 v35, v2
	v_mov_b32_e32 v36, v2
	v_mov_b32_e32 v37, v2
	v_mov_b32_e32 v42, v2
	v_mov_b32_e32 v43, v2
	v_mov_b32_e32 v44, v2
	v_mov_b32_e32 v45, v2
	v_mov_b32_e32 v50, v2
	v_mov_b32_e32 v51, v2
	v_mov_b32_e32 v52, v2
	v_mov_b32_e32 v53, v2
	v_mov_b32_e32 v58, v2
	v_mov_b32_e32 v59, v2
	v_mov_b32_e32 v60, v2
	v_mov_b32_e32 v61, v2
	v_mov_b32_e32 v62, v2
	v_mov_b32_e32 v63, v2
	v_mov_b32_e32 v64, v2
	v_mov_b32_e32 v65, v2
	v_mov_b32_e32 v66, v2
	v_mov_b32_e32 v67, v2
	v_mov_b32_e32 v68, v2
	v_mov_b32_e32 v69, v2
	v_mov_b32_e32 v70, v2
	v_mov_b32_e32 v71, v2
	v_mov_b32_e32 v72, v2
	v_mov_b32_e32 v73, v2
	v_mov_b32_e32 v78, v2
	v_mov_b32_e32 v79, v2
	v_mov_b32_e32 v80, v2
	v_mov_b32_e32 v81, v2
	v_mov_b32_e32 v86, v2
	v_mov_b32_e32 v87, v2
	v_mov_b32_e32 v88, v2
	v_mov_b32_e32 v89, v2
	v_mov_b32_e32 v94, v2
	v_mov_b32_e32 v95, v2
	v_mov_b32_e32 v96, v2
	v_mov_b32_e32 v97, v2
	v_mov_b32_e32 v102, v2
	v_mov_b32_e32 v103, v2
	v_mov_b32_e32 v104, v2
	v_mov_b32_e32 v105, v2
	v_mov_b32_e32 v114, v2
	v_mov_b32_e32 v115, v2
	v_mov_b32_e32 v116, v2
	v_mov_b32_e32 v117, v2
	v_mov_b32_e32 v118, v2
	v_mov_b32_e32 v119, v2
	v_mov_b32_e32 v120, v2
	v_mov_b32_e32 v121, v2
	v_mov_b32_e32 v74, v2
	v_mov_b32_e32 v75, v2
	v_mov_b32_e32 v76, v2
	v_mov_b32_e32 v77, v2
	v_mov_b32_e32 v82, v2
	v_mov_b32_e32 v83, v2
	v_mov_b32_e32 v84, v2
	v_mov_b32_e32 v85, v2
	v_mov_b32_e32 v90, v2
	v_mov_b32_e32 v91, v2
	v_mov_b32_e32 v92, v2
	v_mov_b32_e32 v93, v2
	v_mov_b32_e32 v98, v2
	v_mov_b32_e32 v99, v2
	v_mov_b32_e32 v100, v2
	v_mov_b32_e32 v101, v2
	v_mov_b32_e32 v106, v2
	v_mov_b32_e32 v107, v2
	v_mov_b32_e32 v108, v2
	v_mov_b32_e32 v109, v2
	v_mov_b32_e32 v110, v2
	v_mov_b32_e32 v111, v2
	v_mov_b32_e32 v112, v2
	v_mov_b32_e32 v113, v2
	v_mov_b32_e32 v122, v2
	v_mov_b32_e32 v123, v2
	v_mov_b32_e32 v124, v2
	v_mov_b32_e32 v125, v2
	v_mov_b32_e32 v126, v2
	v_mov_b32_e32 v127, v2
	v_mov_b32_e32 v128, v2
	v_mov_b32_e32 v129, v2
	s_cmp_eq_u32 s100, 1
	s_cbranch_scc0 .Ldefbar_skip_1
	s_mov_b32 s100, 0
	s_barrier
.Ldefbar_skip_1:
.LBB0_987:
	s_add_i32 s72, s50, 2
	s_add_u32 s8, s48, 0x100
	s_addc_u32 s9, s49, 0
	s_add_i32 s0, 0, 0x10000
	s_cmp_eq_u32 s41, s50
	s_cselect_b32 s53, s45, s9
	s_cselect_b32 s52, s44, s8
	s_cselect_b32 s51, s47, s71
	s_cselect_b32 s50, s46, s70
	s_add_i32 s1, 0, 0x14000
	v_add_u32_e32 v142, s0, v188
	v_add_u32_e32 v172, s1, v188
	ds_read_b128 v[130:133], v142
	ds_read_b128 v[134:137], v142 offset:1024
	ds_read_b128 v[138:141], v142 offset:2048
	ds_read_b128 v[142:145], v142 offset:3072
	ds_read_b128 v[146:149], v172
	ds_read_b128 v[164:167], v172 offset:1024
	ds_read_b128 v[168:171], v172 offset:2048
	ds_read_b128 v[172:175], v172 offset:3072
	v_lshl_add_u64 v[194:195], s[48:49], 0, v[162:163]
	s_add_i32 m0, s27, 0xc000
	ds_read_b128 v[176:179], v189
	ds_read_b128 v[180:183], v189 offset:1024
	ds_read_b128 v[184:187], v189 offset:2048
	ds_read_b128 v[190:193], v189 offset:3072
	ds_read_b128 v[202:205], v189 offset:4096
	ds_read_b128 v[206:209], v189 offset:5120
	ds_read_b128 v[210:213], v189 offset:6144
	ds_read_b128 v[214:217], v189 offset:7168
	global_load_lds_dwordx4 v[194:195], off
	v_lshl_add_u64 v[194:195], s[48:49], 0, v[160:161]
	s_add_i32 m0, s27, 0xe000
	s_nop 0
	global_load_lds_dwordx4 v[194:195], off
	s_waitcnt vmcnt(8)
	s_waitcnt lgkmcnt(0)
	s_setprio 1
	s_barrier
	v_mfma_f32_16x16x32_bf16 v[126:129], v[130:133], v[176:179], v[126:129]
	v_mfma_f32_16x16x32_bf16 v[122:125], v[138:141], v[176:179], v[122:125]
	v_mfma_f32_16x16x32_bf16 v[110:113], v[130:133], v[184:187], v[110:113]
	v_mfma_f32_16x16x32_bf16 v[106:109], v[138:141], v[184:187], v[106:109]
	v_mfma_f32_16x16x32_bf16 v[98:101], v[130:133], v[202:205], v[98:101]
	v_mfma_f32_16x16x32_bf16 v[90:93], v[138:141], v[202:205], v[90:93]
	v_mfma_f32_16x16x32_bf16 v[82:85], v[130:133], v[210:213], v[82:85]
	v_mfma_f32_16x16x32_bf16 v[74:77], v[138:141], v[210:213], v[74:77]
	v_mfma_f32_16x16x32_bf16 v[126:129], v[134:137], v[180:183], v[126:129]
	v_mfma_f32_16x16x32_bf16 v[122:125], v[142:145], v[180:183], v[122:125]
	v_mfma_f32_16x16x32_bf16 v[110:113], v[134:137], v[190:193], v[110:113]
	v_mfma_f32_16x16x32_bf16 v[106:109], v[142:145], v[190:193], v[106:109]
	v_mfma_f32_16x16x32_bf16 v[98:101], v[134:137], v[206:209], v[98:101]
	v_mfma_f32_16x16x32_bf16 v[90:93], v[142:145], v[206:209], v[90:93]
	v_mfma_f32_16x16x32_bf16 v[82:85], v[134:137], v[214:217], v[82:85]
	v_mfma_f32_16x16x32_bf16 v[74:77], v[142:145], v[214:217], v[74:77]
	v_mfma_f32_16x16x32_bf16 v[118:121], v[146:149], v[176:179], v[118:121]
	v_mfma_f32_16x16x32_bf16 v[114:117], v[168:171], v[176:179], v[114:117]
	v_mfma_f32_16x16x32_bf16 v[102:105], v[146:149], v[184:187], v[102:105]
	v_mfma_f32_16x16x32_bf16 v[94:97], v[168:171], v[184:187], v[94:97]
	v_mfma_f32_16x16x32_bf16 v[86:89], v[146:149], v[202:205], v[86:89]
	v_mfma_f32_16x16x32_bf16 v[78:81], v[168:171], v[202:205], v[78:81]
	v_mfma_f32_16x16x32_bf16 v[70:73], v[146:149], v[210:213], v[70:73]
	v_mfma_f32_16x16x32_bf16 v[66:69], v[168:171], v[210:213], v[66:69]
	v_mfma_f32_16x16x32_bf16 v[118:121], v[164:167], v[180:183], v[118:121]
	v_mfma_f32_16x16x32_bf16 v[114:117], v[172:175], v[180:183], v[114:117]
	v_mfma_f32_16x16x32_bf16 v[102:105], v[164:167], v[190:193], v[102:105]
	v_mfma_f32_16x16x32_bf16 v[94:97], v[172:175], v[190:193], v[94:97]
	v_mfma_f32_16x16x32_bf16 v[86:89], v[164:167], v[206:209], v[86:89]
	v_mfma_f32_16x16x32_bf16 v[78:81], v[172:175], v[206:209], v[78:81]
	v_mfma_f32_16x16x32_bf16 v[70:73], v[164:167], v[214:217], v[70:73]
	v_mfma_f32_16x16x32_bf16 v[66:69], v[172:175], v[214:217], v[66:69]
	s_barrier
	s_setprio 0
	s_add_i32 s0, s0, s26
	v_lshl_add_u64 v[194:195], s[50:51], 0, v[196:197]
	s_mov_b32 m0, s0
	ds_read_b128 v[176:179], v189 offset:16384
	ds_read_b128 v[180:183], v189 offset:17408
	ds_read_b128 v[184:187], v189 offset:18432
	ds_read_b128 v[190:193], v189 offset:19456
	ds_read_b128 v[202:205], v189 offset:20480
	ds_read_b128 v[206:209], v189 offset:21504
	ds_read_b128 v[210:213], v189 offset:22528
	ds_read_b128 v[214:217], v189 offset:23552
	global_load_lds_dwordx4 v[194:195], off
	s_add_i32 m0, s0, 0x2000
	s_add_u32 s48, s50, 0x158000
	v_lshl_add_u64 v[218:219], s[50:51], 0, v[154:155]
	s_addc_u32 s49, s51, 0
	s_add_i32 s0, s1, s26
	global_load_lds_dwordx4 v[218:219], off
	v_lshl_add_u64 v[220:221], s[48:49], 0, v[196:197]
	s_mov_b32 m0, s0
	v_lshl_add_u64 v[222:223], s[52:53], 0, v[152:153]
	global_load_lds_dwordx4 v[220:221], off
	v_lshl_add_u64 v[220:221], s[48:49], 0, v[154:155]
	s_add_i32 m0, s0, 0x2000
	s_nop 0
	global_load_lds_dwordx4 v[220:221], off
	v_lshl_add_u64 v[220:221], s[52:53], 0, v[150:151]
	s_mov_b32 m0, s27
	s_nop 0
	global_load_lds_dwordx4 v[220:221], off
	s_mov_b32 m0, s28
	s_nop 0
	global_load_lds_dwordx4 v[222:223], off
	s_waitcnt vmcnt(8)
	s_waitcnt lgkmcnt(0)
	s_setprio 1
	s_barrier
	v_mfma_f32_16x16x32_bf16 v[62:65], v[130:133], v[176:179], v[62:65]
	v_mfma_f32_16x16x32_bf16 v[58:61], v[138:141], v[176:179], v[58:61]
	v_mfma_f32_16x16x32_bf16 v[50:53], v[130:133], v[184:187], v[50:53]
	v_mfma_f32_16x16x32_bf16 v[42:45], v[138:141], v[184:187], v[42:45]
	v_mfma_f32_16x16x32_bf16 v[34:37], v[130:133], v[202:205], v[34:37]
	v_mfma_f32_16x16x32_bf16 v[26:29], v[138:141], v[202:205], v[26:29]
	v_mfma_f32_16x16x32_bf16 v[18:21], v[130:133], v[210:213], v[18:21]
	v_mfma_f32_16x16x32_bf16 v[10:13], v[138:141], v[210:213], v[10:13]
	v_mfma_f32_16x16x32_bf16 v[62:65], v[134:137], v[180:183], v[62:65]
	v_mfma_f32_16x16x32_bf16 v[58:61], v[142:145], v[180:183], v[58:61]
	v_mfma_f32_16x16x32_bf16 v[50:53], v[134:137], v[190:193], v[50:53]
	v_mfma_f32_16x16x32_bf16 v[42:45], v[142:145], v[190:193], v[42:45]
	v_mfma_f32_16x16x32_bf16 v[34:37], v[134:137], v[206:209], v[34:37]
	v_mfma_f32_16x16x32_bf16 v[26:29], v[142:145], v[206:209], v[26:29]
	v_mfma_f32_16x16x32_bf16 v[18:21], v[134:137], v[214:217], v[18:21]
	v_mfma_f32_16x16x32_bf16 v[10:13], v[142:145], v[214:217], v[10:13]
	v_mfma_f32_16x16x32_bf16 v[54:57], v[146:149], v[176:179], v[54:57]
	v_mfma_f32_16x16x32_bf16 v[46:49], v[168:171], v[176:179], v[46:49]
	v_mfma_f32_16x16x32_bf16 v[38:41], v[146:149], v[184:187], v[38:41]
	v_mfma_f32_16x16x32_bf16 v[30:33], v[168:171], v[184:187], v[30:33]
	v_mfma_f32_16x16x32_bf16 v[22:25], v[146:149], v[202:205], v[22:25]
	v_mfma_f32_16x16x32_bf16 v[14:17], v[168:171], v[202:205], v[14:17]
	v_mfma_f32_16x16x32_bf16 v[6:9], v[146:149], v[210:213], v[6:9]
	v_mfma_f32_16x16x32_bf16 v[2:5], v[168:171], v[210:213], v[2:5]
	v_mfma_f32_16x16x32_bf16 v[54:57], v[164:167], v[180:183], v[54:57]
	v_mfma_f32_16x16x32_bf16 v[46:49], v[172:175], v[180:183], v[46:49]
	v_mfma_f32_16x16x32_bf16 v[38:41], v[164:167], v[190:193], v[38:41]
	v_mfma_f32_16x16x32_bf16 v[30:33], v[172:175], v[190:193], v[30:33]
	v_mfma_f32_16x16x32_bf16 v[22:25], v[164:167], v[206:209], v[22:25]
	v_mfma_f32_16x16x32_bf16 v[14:17], v[172:175], v[206:209], v[14:17]
	v_mfma_f32_16x16x32_bf16 v[6:9], v[164:167], v[214:217], v[6:9]
	v_mfma_f32_16x16x32_bf16 v[2:5], v[172:175], v[214:217], v[2:5]
	s_barrier
	s_setprio 0
	s_add_i32 s0, 0, 0x18000
	s_add_i32 s1, 0, 0x1c000
	v_add_u32_e32 v142, s0, v188
	v_add_u32_e32 v172, s1, v188
	ds_read_b128 v[130:133], v142
	ds_read_b128 v[134:137], v142 offset:1024
	ds_read_b128 v[138:141], v142 offset:2048
	ds_read_b128 v[142:145], v142 offset:3072
	ds_read_b128 v[146:149], v172
	ds_read_b128 v[164:167], v172 offset:1024
	ds_read_b128 v[168:171], v172 offset:2048
	ds_read_b128 v[172:175], v172 offset:3072
	s_add_u32 s48, s52, 0x158000
	s_addc_u32 s49, s53, 0
	s_mov_b32 m0, s29
	v_lshl_add_u64 v[224:225], s[48:49], 0, v[150:151]
	ds_read_b128 v[176:179], v189 offset:32768
	ds_read_b128 v[180:183], v189 offset:33792
	ds_read_b128 v[184:187], v189 offset:34816
	ds_read_b128 v[190:193], v189 offset:35840
	ds_read_b128 v[202:205], v189 offset:36864
	ds_read_b128 v[206:209], v189 offset:37888
	ds_read_b128 v[210:213], v189 offset:38912
	ds_read_b128 v[214:217], v189 offset:39936
	global_load_lds_dwordx4 v[224:225], off
	v_lshl_add_u64 v[224:225], s[48:49], 0, v[152:153]
	s_mov_b32 m0, s30
	s_nop 0
	global_load_lds_dwordx4 v[224:225], off
	s_waitcnt vmcnt(8)
	s_waitcnt lgkmcnt(0)
	s_setprio 1
	s_barrier
	v_mfma_f32_16x16x32_bf16 v[126:129], v[130:133], v[176:179], v[126:129]
	v_mfma_f32_16x16x32_bf16 v[122:125], v[138:141], v[176:179], v[122:125]
	v_mfma_f32_16x16x32_bf16 v[110:113], v[130:133], v[184:187], v[110:113]
	v_mfma_f32_16x16x32_bf16 v[106:109], v[138:141], v[184:187], v[106:109]
	v_mfma_f32_16x16x32_bf16 v[98:101], v[130:133], v[202:205], v[98:101]
	v_mfma_f32_16x16x32_bf16 v[90:93], v[138:141], v[202:205], v[90:93]
	v_mfma_f32_16x16x32_bf16 v[82:85], v[130:133], v[210:213], v[82:85]
	v_mfma_f32_16x16x32_bf16 v[74:77], v[138:141], v[210:213], v[74:77]
	v_mfma_f32_16x16x32_bf16 v[126:129], v[134:137], v[180:183], v[126:129]
	v_mfma_f32_16x16x32_bf16 v[122:125], v[142:145], v[180:183], v[122:125]
	v_mfma_f32_16x16x32_bf16 v[110:113], v[134:137], v[190:193], v[110:113]
	v_mfma_f32_16x16x32_bf16 v[106:109], v[142:145], v[190:193], v[106:109]
	v_mfma_f32_16x16x32_bf16 v[98:101], v[134:137], v[206:209], v[98:101]
	v_mfma_f32_16x16x32_bf16 v[90:93], v[142:145], v[206:209], v[90:93]
	v_mfma_f32_16x16x32_bf16 v[82:85], v[134:137], v[214:217], v[82:85]
	v_mfma_f32_16x16x32_bf16 v[74:77], v[142:145], v[214:217], v[74:77]
	v_mfma_f32_16x16x32_bf16 v[118:121], v[146:149], v[176:179], v[118:121]
	v_mfma_f32_16x16x32_bf16 v[114:117], v[168:171], v[176:179], v[114:117]
	v_mfma_f32_16x16x32_bf16 v[102:105], v[146:149], v[184:187], v[102:105]
	v_mfma_f32_16x16x32_bf16 v[94:97], v[168:171], v[184:187], v[94:97]
	v_mfma_f32_16x16x32_bf16 v[86:89], v[146:149], v[202:205], v[86:89]
	v_mfma_f32_16x16x32_bf16 v[78:81], v[168:171], v[202:205], v[78:81]
	v_mfma_f32_16x16x32_bf16 v[70:73], v[146:149], v[210:213], v[70:73]
	v_mfma_f32_16x16x32_bf16 v[66:69], v[168:171], v[210:213], v[66:69]
	v_mfma_f32_16x16x32_bf16 v[118:121], v[164:167], v[180:183], v[118:121]
	v_mfma_f32_16x16x32_bf16 v[114:117], v[172:175], v[180:183], v[114:117]
	v_mfma_f32_16x16x32_bf16 v[102:105], v[164:167], v[190:193], v[102:105]
	v_mfma_f32_16x16x32_bf16 v[94:97], v[172:175], v[190:193], v[94:97]
	v_mfma_f32_16x16x32_bf16 v[86:89], v[164:167], v[206:209], v[86:89]
	v_mfma_f32_16x16x32_bf16 v[78:81], v[172:175], v[206:209], v[78:81]
	v_mfma_f32_16x16x32_bf16 v[70:73], v[164:167], v[214:217], v[70:73]
	v_mfma_f32_16x16x32_bf16 v[66:69], v[172:175], v[214:217], v[66:69]
	s_barrier
	s_setprio 0
	s_add_i32 s0, s0, s26
	v_lshl_add_u64 v[194:195], v[194:195], 0, s[16:17]
	s_mov_b32 m0, s0
	ds_read_b128 v[176:179], v189 offset:49152
	ds_read_b128 v[180:183], v189 offset:50176
	ds_read_b128 v[184:187], v189 offset:51200
	ds_read_b128 v[190:193], v189 offset:52224
	ds_read_b128 v[202:205], v189 offset:53248
	ds_read_b128 v[206:209], v189 offset:54272
	ds_read_b128 v[210:213], v189 offset:55296
	ds_read_b128 v[214:217], v189 offset:56320
	global_load_lds_dwordx4 v[194:195], off
	s_add_i32 m0, s0, 0x2000
	s_add_u32 s48, s50, 0x158080
	v_lshl_add_u64 v[194:195], v[218:219], 0, s[16:17]
	s_addc_u32 s49, s51, 0
	s_add_i32 s0, s1, s26
	global_load_lds_dwordx4 v[194:195], off
	v_lshl_add_u64 v[194:195], s[48:49], 0, v[196:197]
	s_mov_b32 m0, s0
	s_nop 0
	global_load_lds_dwordx4 v[194:195], off
	v_lshl_add_u64 v[194:195], s[48:49], 0, v[154:155]
	s_add_i32 m0, s0, 0x2000
	s_nop 0
	global_load_lds_dwordx4 v[194:195], off
	v_lshl_add_u64 v[194:195], v[220:221], 0, s[16:17]
	s_mov_b32 m0, s35
	s_nop 0
	global_load_lds_dwordx4 v[194:195], off
	v_lshl_add_u64 v[194:195], v[222:223], 0, s[16:17]
	s_mov_b32 m0, s58
	s_nop 0
	global_load_lds_dwordx4 v[194:195], off
	s_waitcnt vmcnt(8)
	s_waitcnt lgkmcnt(0)
	s_setprio 1
	s_barrier
	v_mfma_f32_16x16x32_bf16 v[62:65], v[130:133], v[176:179], v[62:65]
	v_mfma_f32_16x16x32_bf16 v[58:61], v[138:141], v[176:179], v[58:61]
	v_mfma_f32_16x16x32_bf16 v[50:53], v[130:133], v[184:187], v[50:53]
	v_mfma_f32_16x16x32_bf16 v[42:45], v[138:141], v[184:187], v[42:45]
	v_mfma_f32_16x16x32_bf16 v[34:37], v[130:133], v[202:205], v[34:37]
	v_mfma_f32_16x16x32_bf16 v[26:29], v[138:141], v[202:205], v[26:29]
	v_mfma_f32_16x16x32_bf16 v[18:21], v[130:133], v[210:213], v[18:21]
	v_mfma_f32_16x16x32_bf16 v[10:13], v[138:141], v[210:213], v[10:13]
	v_mfma_f32_16x16x32_bf16 v[62:65], v[134:137], v[180:183], v[62:65]
	v_mfma_f32_16x16x32_bf16 v[58:61], v[142:145], v[180:183], v[58:61]
	v_mfma_f32_16x16x32_bf16 v[50:53], v[134:137], v[190:193], v[50:53]
	v_mfma_f32_16x16x32_bf16 v[42:45], v[142:145], v[190:193], v[42:45]
	v_mfma_f32_16x16x32_bf16 v[34:37], v[134:137], v[206:209], v[34:37]
	v_mfma_f32_16x16x32_bf16 v[26:29], v[142:145], v[206:209], v[26:29]
	v_mfma_f32_16x16x32_bf16 v[18:21], v[134:137], v[214:217], v[18:21]
	v_mfma_f32_16x16x32_bf16 v[10:13], v[142:145], v[214:217], v[10:13]
	v_mfma_f32_16x16x32_bf16 v[54:57], v[146:149], v[176:179], v[54:57]
	v_mfma_f32_16x16x32_bf16 v[46:49], v[168:171], v[176:179], v[46:49]
	v_mfma_f32_16x16x32_bf16 v[38:41], v[146:149], v[184:187], v[38:41]
	v_mfma_f32_16x16x32_bf16 v[30:33], v[168:171], v[184:187], v[30:33]
	v_mfma_f32_16x16x32_bf16 v[22:25], v[146:149], v[202:205], v[22:25]
	v_mfma_f32_16x16x32_bf16 v[14:17], v[168:171], v[202:205], v[14:17]
	v_mfma_f32_16x16x32_bf16 v[6:9], v[146:149], v[210:213], v[6:9]
	v_mfma_f32_16x16x32_bf16 v[2:5], v[168:171], v[210:213], v[2:5]
	v_mfma_f32_16x16x32_bf16 v[54:57], v[164:167], v[180:183], v[54:57]
	v_mfma_f32_16x16x32_bf16 v[46:49], v[172:175], v[180:183], v[46:49]
	v_mfma_f32_16x16x32_bf16 v[38:41], v[164:167], v[190:193], v[38:41]
	v_mfma_f32_16x16x32_bf16 v[30:33], v[172:175], v[190:193], v[30:33]
	v_mfma_f32_16x16x32_bf16 v[22:25], v[164:167], v[206:209], v[22:25]
	v_mfma_f32_16x16x32_bf16 v[14:17], v[172:175], v[206:209], v[14:17]
	v_mfma_f32_16x16x32_bf16 v[6:9], v[164:167], v[214:217], v[6:9]
	v_mfma_f32_16x16x32_bf16 v[2:5], v[172:175], v[214:217], v[2:5]
	s_barrier
	s_setprio 0
	s_add_u32 s70, s70, 0x100
	s_addc_u32 s71, s71, 0
	s_cmp_ge_i32 s72, s69
	s_mov_b64 s[48:49], s[8:9]
	s_mov_b32 s50, s72
	s_cbranch_scc0 .LBB0_987
	s_and_b64 vcc, exec, s[38:39]
	s_cbranch_vccz .LBB0_990
	s_barrier

.LBB0_993:
	s_and_b64 vcc, exec, s[42:43]
	s_mov_b64 s[8:9], -1
	s_cbranch_vccnz .LBB0_972
	s_andn2_b64 vcc, exec, s[4:5]
	s_cbranch_vccnz .LBB0_971
	s_mov_b32 s100, 1
	s_branch .LBB0_971

.LBB0_1134:
	s_ashr_i32 s47, s46, 31
	s_lshl_b64 s[50:51], s[46:47], 20
	s_add_u32 s0, s2, s50
	s_addc_u32 s1, s3, s51
	s_ashr_i32 s43, s42, 31
	s_lshl_b64 s[52:53], s[42:43], 1
	s_add_u32 s50, s0, s52
	s_addc_u32 s51, s1, s53
	s_and_b64 s[62:63], s[48:49], exec
	s_cselect_b32 s43, s51, s9
	s_cselect_b32 s47, s50, s8
	s_ashr_i32 s45, s44, 31
	s_lshl_b64 s[62:63], s[44:45], 20
	s_add_u32 s0, s10, s62
	s_addc_u32 s1, s11, s63
	s_add_u32 s52, s0, s52
	s_addc_u32 s53, s1, s53
	s_and_b64 s[62:63], s[48:49], exec
	s_cselect_b32 s45, s53, s59
	s_cselect_b32 s67, s52, s58
	s_add_i32 s68, s64, -2
	s_add_u32 s69, s58, 0x100
	s_addc_u32 s70, s59, 0
	s_add_u32 s58, s8, 0x80080
	v_mov_b32_e32 v2, 0
	s_addc_u32 s59, s9, 0
	s_mov_b32 s8, 0
	v_mov_b32_e32 v3, v2
	v_mov_b32_e32 v4, v2
	v_mov_b32_e32 v5, v2
	v_mov_b32_e32 v6, v2
	v_mov_b32_e32 v7, v2
	v_mov_b32_e32 v8, v2
	v_mov_b32_e32 v9, v2
	v_mov_b32_e32 v10, v2
	v_mov_b32_e32 v11, v2
	v_mov_b32_e32 v12, v2
	v_mov_b32_e32 v13, v2
	v_mov_b32_e32 v18, v2
	v_mov_b32_e32 v19, v2
	v_mov_b32_e32 v20, v2
	v_mov_b32_e32 v21, v2
	v_mov_b32_e32 v26, v2
	v_mov_b32_e32 v27, v2
	v_mov_b32_e32 v28, v2
	v_mov_b32_e32 v29, v2
	v_mov_b32_e32 v34, v2
	v_mov_b32_e32 v35, v2
	v_mov_b32_e32 v36, v2
	v_mov_b32_e32 v37, v2
	v_mov_b32_e32 v42, v2
	v_mov_b32_e32 v43, v2
	v_mov_b32_e32 v44, v2
	v_mov_b32_e32 v45, v2
	v_mov_b32_e32 v50, v2
	v_mov_b32_e32 v51, v2
	v_mov_b32_e32 v52, v2
	v_mov_b32_e32 v53, v2
	v_mov_b32_e32 v14, v2
	v_mov_b32_e32 v15, v2
	v_mov_b32_e32 v16, v2
	v_mov_b32_e32 v17, v2
	v_mov_b32_e32 v22, v2
	v_mov_b32_e32 v23, v2
	v_mov_b32_e32 v24, v2
	v_mov_b32_e32 v25, v2
	v_mov_b32_e32 v30, v2
	v_mov_b32_e32 v31, v2
	v_mov_b32_e32 v32, v2
	v_mov_b32_e32 v33, v2
	v_mov_b32_e32 v38, v2
	v_mov_b32_e32 v39, v2
	v_mov_b32_e32 v40, v2
	v_mov_b32_e32 v41, v2
	s_nop 0
	v_mov_b32_e32 v46, v2
	v_mov_b32_e32 v47, v2
	v_mov_b32_e32 v48, v2
	v_mov_b32_e32 v49, v2
	v_mov_b32_e32 v54, v2
	v_mov_b32_e32 v55, v2
	v_mov_b32_e32 v56, v2
	v_mov_b32_e32 v57, v2
	v_mov_b32_e32 v58, v2
	v_mov_b32_e32 v59, v2
	v_mov_b32_e32 v60, v2
	v_mov_b32_e32 v61, v2
	v_mov_b32_e32 v62, v2
	v_mov_b32_e32 v63, v2
	v_mov_b32_e32 v64, v2
	v_mov_b32_e32 v65, v2
	v_mov_b32_e32 v66, v2
	v_mov_b32_e32 v67, v2
	v_mov_b32_e32 v68, v2
	v_mov_b32_e32 v69, v2
	v_mov_b32_e32 v70, v2
	v_mov_b32_e32 v71, v2
	v_mov_b32_e32 v72, v2
	v_mov_b32_e32 v73, v2
	v_mov_b32_e32 v74, v2
	v_mov_b32_e32 v75, v2
	v_mov_b32_e32 v76, v2
	v_mov_b32_e32 v77, v2
	v_mov_b32_e32 v82, v2
	v_mov_b32_e32 v83, v2
	v_mov_b32_e32 v84, v2
	v_mov_b32_e32 v85, v2
	v_mov_b32_e32 v90, v2
	v_mov_b32_e32 v91, v2
	v_mov_b32_e32 v92, v2
	v_mov_b32_e32 v93, v2
	v_mov_b32_e32 v98, v2
	v_mov_b32_e32 v99, v2
	v_mov_b32_e32 v100, v2
	v_mov_b32_e32 v101, v2
	v_mov_b32_e32 v106, v2
	v_mov_b32_e32 v107, v2
	v_mov_b32_e32 v108, v2
	v_mov_b32_e32 v109, v2
	v_mov_b32_e32 v114, v2
	v_mov_b32_e32 v115, v2
	v_mov_b32_e32 v116, v2
	v_mov_b32_e32 v117, v2
	v_mov_b32_e32 v78, v2
	v_mov_b32_e32 v79, v2
	v_mov_b32_e32 v80, v2
	v_mov_b32_e32 v81, v2
	v_mov_b32_e32 v86, v2
	v_mov_b32_e32 v87, v2
	v_mov_b32_e32 v88, v2
	v_mov_b32_e32 v89, v2
	v_mov_b32_e32 v94, v2
	v_mov_b32_e32 v95, v2
	v_mov_b32_e32 v96, v2
	v_mov_b32_e32 v97, v2
	v_mov_b32_e32 v102, v2
	v_mov_b32_e32 v103, v2
	v_mov_b32_e32 v104, v2
	v_mov_b32_e32 v105, v2
	v_mov_b32_e32 v110, v2
	v_mov_b32_e32 v111, v2
	v_mov_b32_e32 v112, v2
	v_mov_b32_e32 v113, v2
	v_mov_b32_e32 v118, v2
	v_mov_b32_e32 v119, v2
	v_mov_b32_e32 v120, v2
	v_mov_b32_e32 v121, v2
	v_mov_b32_e32 v122, v2
	v_mov_b32_e32 v123, v2
	v_mov_b32_e32 v124, v2
	v_mov_b32_e32 v125, v2
	v_mov_b32_e32 v126, v2
	v_mov_b32_e32 v127, v2
	v_mov_b32_e32 v128, v2
	v_mov_b32_e32 v129, v2
	s_cmp_eq_u32 s100, 1
	s_cbranch_scc0 .Ldefbar_skip_2
	s_mov_b32 s100, 0
	s_barrier
.Ldefbar_skip_2:
.LBB0_1135:
	s_add_i32 s71, s8, 2
	s_add_u32 s0, s58, 0xfff80080
	s_addc_u32 s1, s59, -1
	s_add_i32 s72, 0, 0x10000
	s_cmp_eq_u32 s68, s8
	s_cselect_b32 s63, s43, s1
	s_cselect_b32 s62, s47, s0
	v_add_u32_e32 v146, s72, v149
	s_cselect_b32 s9, s45, s70
	s_cselect_b32 s8, s67, s69
	s_add_i32 s0, 0, 0x14000
	ds_read_b128 v[142:145], v146
	ds_read_b128 v[152:155], v146 offset:1024
	ds_read_b128 v[156:159], v146 offset:2048
	ds_read_b128 v[160:163], v146 offset:3072
	v_add_u32_e32 v146, s0, v149
	ds_read_b128 v[164:167], v146
	ds_read_b128 v[168:171], v146 offset:1024
	ds_read_b128 v[172:175], v146 offset:2048
	ds_read_b128 v[176:179], v146 offset:3072
	v_lshl_add_u64 v[146:147], s[58:59], 0, v[140:141]
	s_add_i32 m0, s27, 0xc000
	ds_read_b128 v[180:183], v151
	ds_read_b128 v[184:187], v151 offset:1024
	ds_read_b128 v[188:191], v151 offset:2048
	ds_read_b128 v[192:195], v151 offset:3072
	ds_read_b128 v[202:205], v151 offset:4096
	ds_read_b128 v[206:209], v151 offset:5120
	ds_read_b128 v[210:213], v151 offset:6144
	ds_read_b128 v[214:217], v151 offset:7168
	global_load_lds_dwordx4 v[146:147], off
	v_lshl_add_u64 v[146:147], s[58:59], 0, v[138:139]
	s_add_i32 m0, s27, 0xe000
	s_nop 0
	global_load_lds_dwordx4 v[146:147], off
	s_waitcnt vmcnt(8)
	s_waitcnt lgkmcnt(0)
	s_setprio 1
	s_barrier
	v_mfma_f32_16x16x32_bf16 v[126:129], v[142:145], v[180:183], v[126:129]
	v_mfma_f32_16x16x32_bf16 v[122:125], v[156:159], v[180:183], v[122:125]
	v_mfma_f32_16x16x32_bf16 v[118:121], v[142:145], v[188:191], v[118:121]
	v_mfma_f32_16x16x32_bf16 v[110:113], v[156:159], v[188:191], v[110:113]
	v_mfma_f32_16x16x32_bf16 v[102:105], v[142:145], v[202:205], v[102:105]
	v_mfma_f32_16x16x32_bf16 v[94:97], v[156:159], v[202:205], v[94:97]
	v_mfma_f32_16x16x32_bf16 v[86:89], v[142:145], v[210:213], v[86:89]
	v_mfma_f32_16x16x32_bf16 v[78:81], v[156:159], v[210:213], v[78:81]
	v_mfma_f32_16x16x32_bf16 v[126:129], v[152:155], v[184:187], v[126:129]
	v_mfma_f32_16x16x32_bf16 v[122:125], v[160:163], v[184:187], v[122:125]
	v_mfma_f32_16x16x32_bf16 v[118:121], v[152:155], v[192:195], v[118:121]
	v_mfma_f32_16x16x32_bf16 v[110:113], v[160:163], v[192:195], v[110:113]
	v_mfma_f32_16x16x32_bf16 v[102:105], v[152:155], v[206:209], v[102:105]
	v_mfma_f32_16x16x32_bf16 v[94:97], v[160:163], v[206:209], v[94:97]
	v_mfma_f32_16x16x32_bf16 v[86:89], v[152:155], v[214:217], v[86:89]
	v_mfma_f32_16x16x32_bf16 v[78:81], v[160:163], v[214:217], v[78:81]
	v_mfma_f32_16x16x32_bf16 v[114:117], v[164:167], v[180:183], v[114:117]
	v_mfma_f32_16x16x32_bf16 v[106:109], v[172:175], v[180:183], v[106:109]
	v_mfma_f32_16x16x32_bf16 v[98:101], v[164:167], v[188:191], v[98:101]
	v_mfma_f32_16x16x32_bf16 v[90:93], v[172:175], v[188:191], v[90:93]
	v_mfma_f32_16x16x32_bf16 v[82:85], v[164:167], v[202:205], v[82:85]
	v_mfma_f32_16x16x32_bf16 v[74:77], v[172:175], v[202:205], v[74:77]
	v_mfma_f32_16x16x32_bf16 v[70:73], v[164:167], v[210:213], v[70:73]
	v_mfma_f32_16x16x32_bf16 v[66:69], v[172:175], v[210:213], v[66:69]
	v_mfma_f32_16x16x32_bf16 v[114:117], v[168:171], v[184:187], v[114:117]
	v_mfma_f32_16x16x32_bf16 v[106:109], v[176:179], v[184:187], v[106:109]
	v_mfma_f32_16x16x32_bf16 v[98:101], v[168:171], v[192:195], v[98:101]
	v_mfma_f32_16x16x32_bf16 v[90:93], v[176:179], v[192:195], v[90:93]
	v_mfma_f32_16x16x32_bf16 v[82:85], v[168:171], v[206:209], v[82:85]
	v_mfma_f32_16x16x32_bf16 v[74:77], v[176:179], v[206:209], v[74:77]
	v_mfma_f32_16x16x32_bf16 v[70:73], v[168:171], v[214:217], v[70:73]
	v_mfma_f32_16x16x32_bf16 v[66:69], v[176:179], v[214:217], v[66:69]
	s_barrier
	s_setprio 0
	s_add_i32 s1, s72, s26
	v_lshl_add_u64 v[146:147], s[8:9], 0, v[196:197]
	s_mov_b32 m0, s1
	ds_read_b128 v[180:183], v151 offset:16384
	ds_read_b128 v[184:187], v151 offset:17408
	ds_read_b128 v[188:191], v151 offset:18432
	ds_read_b128 v[192:195], v151 offset:19456
	ds_read_b128 v[202:205], v151 offset:20480
	ds_read_b128 v[206:209], v151 offset:21504
	ds_read_b128 v[210:213], v151 offset:22528
	ds_read_b128 v[214:217], v151 offset:23552
	global_load_lds_dwordx4 v[146:147], off
	s_add_i32 m0, s1, 0x2000
	s_add_u32 s72, s8, 0x80000
	v_lshl_add_u64 v[218:219], s[8:9], 0, v[130:131]
	s_addc_u32 s73, s9, 0
	s_add_i32 s0, s0, s26
	global_load_lds_dwordx4 v[218:219], off
	v_lshl_add_u64 v[220:221], s[72:73], 0, v[196:197]
	s_mov_b32 m0, s0
	v_lshl_add_u64 v[222:223], s[62:63], 0, v[132:133]
	global_load_lds_dwordx4 v[220:221], off
	v_lshl_add_u64 v[220:221], s[72:73], 0, v[130:131]
	s_add_i32 m0, s0, 0x2000
	s_nop 0
	global_load_lds_dwordx4 v[220:221], off
	v_lshl_add_u64 v[220:221], s[62:63], 0, v[134:135]
	s_mov_b32 m0, s27
	s_nop 0
	global_load_lds_dwordx4 v[220:221], off
	s_mov_b32 m0, s28
	s_nop 0
	global_load_lds_dwordx4 v[222:223], off
	s_waitcnt vmcnt(8)
	s_waitcnt lgkmcnt(0)
	s_setprio 1
	s_barrier
	v_mfma_f32_16x16x32_bf16 v[62:65], v[142:145], v[180:183], v[62:65]
	v_mfma_f32_16x16x32_bf16 v[58:61], v[156:159], v[180:183], v[58:61]
	v_mfma_f32_16x16x32_bf16 v[54:57], v[142:145], v[188:191], v[54:57]
	v_mfma_f32_16x16x32_bf16 v[46:49], v[156:159], v[188:191], v[46:49]
	v_mfma_f32_16x16x32_bf16 v[38:41], v[142:145], v[202:205], v[38:41]
	v_mfma_f32_16x16x32_bf16 v[30:33], v[156:159], v[202:205], v[30:33]
	v_mfma_f32_16x16x32_bf16 v[22:25], v[142:145], v[210:213], v[22:25]
	v_mfma_f32_16x16x32_bf16 v[14:17], v[156:159], v[210:213], v[14:17]
	v_mfma_f32_16x16x32_bf16 v[62:65], v[152:155], v[184:187], v[62:65]
	v_mfma_f32_16x16x32_bf16 v[58:61], v[160:163], v[184:187], v[58:61]
	v_mfma_f32_16x16x32_bf16 v[54:57], v[152:155], v[192:195], v[54:57]
	v_mfma_f32_16x16x32_bf16 v[46:49], v[160:163], v[192:195], v[46:49]
	v_mfma_f32_16x16x32_bf16 v[38:41], v[152:155], v[206:209], v[38:41]
	v_mfma_f32_16x16x32_bf16 v[30:33], v[160:163], v[206:209], v[30:33]
	v_mfma_f32_16x16x32_bf16 v[22:25], v[152:155], v[214:217], v[22:25]
	v_mfma_f32_16x16x32_bf16 v[14:17], v[160:163], v[214:217], v[14:17]
	v_mfma_f32_16x16x32_bf16 v[50:53], v[164:167], v[180:183], v[50:53]
	v_mfma_f32_16x16x32_bf16 v[42:45], v[172:175], v[180:183], v[42:45]
	v_mfma_f32_16x16x32_bf16 v[34:37], v[164:167], v[188:191], v[34:37]
	v_mfma_f32_16x16x32_bf16 v[26:29], v[172:175], v[188:191], v[26:29]
	v_mfma_f32_16x16x32_bf16 v[18:21], v[164:167], v[202:205], v[18:21]
	v_mfma_f32_16x16x32_bf16 v[10:13], v[172:175], v[202:205], v[10:13]
	v_mfma_f32_16x16x32_bf16 v[6:9], v[164:167], v[210:213], v[6:9]
	v_mfma_f32_16x16x32_bf16 v[2:5], v[172:175], v[210:213], v[2:5]
	v_mfma_f32_16x16x32_bf16 v[50:53], v[168:171], v[184:187], v[50:53]
	v_mfma_f32_16x16x32_bf16 v[42:45], v[176:179], v[184:187], v[42:45]
	v_mfma_f32_16x16x32_bf16 v[34:37], v[168:171], v[192:195], v[34:37]
	v_mfma_f32_16x16x32_bf16 v[26:29], v[176:179], v[192:195], v[26:29]
	v_mfma_f32_16x16x32_bf16 v[18:21], v[168:171], v[206:209], v[18:21]
	v_mfma_f32_16x16x32_bf16 v[10:13], v[176:179], v[206:209], v[10:13]
	v_mfma_f32_16x16x32_bf16 v[6:9], v[168:171], v[214:217], v[6:9]
	v_mfma_f32_16x16x32_bf16 v[2:5], v[176:179], v[214:217], v[2:5]
	s_barrier
	s_setprio 0
	s_add_i32 s0, 0, 0x18000
	s_add_i32 s1, 0, 0x1c000
	v_add_u32_e32 v160, s0, v149
	v_add_u32_e32 v176, s1, v149
	ds_read_b128 v[142:145], v160
	ds_read_b128 v[152:155], v160 offset:1024
	ds_read_b128 v[156:159], v160 offset:2048
	ds_read_b128 v[160:163], v160 offset:3072
	ds_read_b128 v[164:167], v176
	ds_read_b128 v[168:171], v176 offset:1024
	ds_read_b128 v[172:175], v176 offset:2048
	ds_read_b128 v[176:179], v176 offset:3072
	s_add_u32 s62, s62, 0x80000
	s_addc_u32 s63, s63, 0
	s_mov_b32 m0, s29
	v_lshl_add_u64 v[224:225], s[62:63], 0, v[134:135]
	ds_read_b128 v[180:183], v151 offset:32768
	ds_read_b128 v[184:187], v151 offset:33792
	ds_read_b128 v[188:191], v151 offset:34816
	ds_read_b128 v[192:195], v151 offset:35840
	ds_read_b128 v[202:205], v151 offset:36864
	ds_read_b128 v[206:209], v151 offset:37888
	ds_read_b128 v[210:213], v151 offset:38912
	ds_read_b128 v[214:217], v151 offset:39936
	global_load_lds_dwordx4 v[224:225], off
	v_lshl_add_u64 v[224:225], s[62:63], 0, v[132:133]
	s_mov_b32 m0, s30
	s_nop 0
	global_load_lds_dwordx4 v[224:225], off
	s_waitcnt vmcnt(8)
	s_waitcnt lgkmcnt(0)
	s_setprio 1
	s_barrier
	v_mfma_f32_16x16x32_bf16 v[126:129], v[142:145], v[180:183], v[126:129]
	v_mfma_f32_16x16x32_bf16 v[122:125], v[156:159], v[180:183], v[122:125]
	v_mfma_f32_16x16x32_bf16 v[118:121], v[142:145], v[188:191], v[118:121]
	v_mfma_f32_16x16x32_bf16 v[110:113], v[156:159], v[188:191], v[110:113]
	v_mfma_f32_16x16x32_bf16 v[102:105], v[142:145], v[202:205], v[102:105]
	v_mfma_f32_16x16x32_bf16 v[94:97], v[156:159], v[202:205], v[94:97]
	v_mfma_f32_16x16x32_bf16 v[86:89], v[142:145], v[210:213], v[86:89]
	v_mfma_f32_16x16x32_bf16 v[78:81], v[156:159], v[210:213], v[78:81]
	v_mfma_f32_16x16x32_bf16 v[126:129], v[152:155], v[184:187], v[126:129]
	v_mfma_f32_16x16x32_bf16 v[122:125], v[160:163], v[184:187], v[122:125]
	v_mfma_f32_16x16x32_bf16 v[118:121], v[152:155], v[192:195], v[118:121]
	v_mfma_f32_16x16x32_bf16 v[110:113], v[160:163], v[192:195], v[110:113]
	v_mfma_f32_16x16x32_bf16 v[102:105], v[152:155], v[206:209], v[102:105]
	v_mfma_f32_16x16x32_bf16 v[94:97], v[160:163], v[206:209], v[94:97]
	v_mfma_f32_16x16x32_bf16 v[86:89], v[152:155], v[214:217], v[86:89]
	v_mfma_f32_16x16x32_bf16 v[78:81], v[160:163], v[214:217], v[78:81]
	v_mfma_f32_16x16x32_bf16 v[114:117], v[164:167], v[180:183], v[114:117]
	v_mfma_f32_16x16x32_bf16 v[106:109], v[172:175], v[180:183], v[106:109]
	v_mfma_f32_16x16x32_bf16 v[98:101], v[164:167], v[188:191], v[98:101]
	v_mfma_f32_16x16x32_bf16 v[90:93], v[172:175], v[188:191], v[90:93]
	v_mfma_f32_16x16x32_bf16 v[82:85], v[164:167], v[202:205], v[82:85]
	v_mfma_f32_16x16x32_bf16 v[74:77], v[172:175], v[202:205], v[74:77]
	v_mfma_f32_16x16x32_bf16 v[70:73], v[164:167], v[210:213], v[70:73]
	v_mfma_f32_16x16x32_bf16 v[66:69], v[172:175], v[210:213], v[66:69]
	v_mfma_f32_16x16x32_bf16 v[114:117], v[168:171], v[184:187], v[114:117]
	v_mfma_f32_16x16x32_bf16 v[106:109], v[176:179], v[184:187], v[106:109]
	v_mfma_f32_16x16x32_bf16 v[98:101], v[168:171], v[192:195], v[98:101]
	v_mfma_f32_16x16x32_bf16 v[90:93], v[176:179], v[192:195], v[90:93]
	v_mfma_f32_16x16x32_bf16 v[82:85], v[168:171], v[206:209], v[82:85]
	v_mfma_f32_16x16x32_bf16 v[74:77], v[176:179], v[206:209], v[74:77]
	v_mfma_f32_16x16x32_bf16 v[70:73], v[168:171], v[214:217], v[70:73]
	v_mfma_f32_16x16x32_bf16 v[66:69], v[176:179], v[214:217], v[66:69]
	s_barrier
	s_setprio 0
	s_add_i32 s0, s0, s26
	v_lshl_add_u64 v[146:147], v[146:147], 0, s[16:17]
	s_mov_b32 m0, s0
	ds_read_b128 v[180:183], v151 offset:49152
	ds_read_b128 v[184:187], v151 offset:50176
	ds_read_b128 v[188:191], v151 offset:51200
	ds_read_b128 v[192:195], v151 offset:52224
	ds_read_b128 v[202:205], v151 offset:53248
	ds_read_b128 v[206:209], v151 offset:54272
	ds_read_b128 v[210:213], v151 offset:55296
	ds_read_b128 v[214:217], v151 offset:56320
	global_load_lds_dwordx4 v[146:147], off
	s_add_i32 m0, s0, 0x2000
	s_add_u32 s8, s8, 0x80080
	v_lshl_add_u64 v[146:147], v[218:219], 0, s[16:17]
	s_addc_u32 s9, s9, 0
	s_add_i32 s0, s1, s26
	global_load_lds_dwordx4 v[146:147], off
	v_lshl_add_u64 v[146:147], s[8:9], 0, v[196:197]
	s_mov_b32 m0, s0
	s_nop 0
	global_load_lds_dwordx4 v[146:147], off
	v_lshl_add_u64 v[146:147], s[8:9], 0, v[130:131]
	s_add_i32 m0, s0, 0x2000
	s_nop 0
	global_load_lds_dwordx4 v[146:147], off
	v_lshl_add_u64 v[146:147], v[220:221], 0, s[16:17]
	s_mov_b32 m0, s31
	s_nop 0
	global_load_lds_dwordx4 v[146:147], off
	v_lshl_add_u64 v[146:147], v[222:223], 0, s[16:17]
	s_mov_b32 m0, s34
	s_nop 0
	global_load_lds_dwordx4 v[146:147], off
	s_waitcnt vmcnt(8)
	s_waitcnt lgkmcnt(0)
	s_setprio 1
	s_barrier
	v_mfma_f32_16x16x32_bf16 v[62:65], v[142:145], v[180:183], v[62:65]
	v_mfma_f32_16x16x32_bf16 v[58:61], v[156:159], v[180:183], v[58:61]
	v_mfma_f32_16x16x32_bf16 v[54:57], v[142:145], v[188:191], v[54:57]
	v_mfma_f32_16x16x32_bf16 v[46:49], v[156:159], v[188:191], v[46:49]
	v_mfma_f32_16x16x32_bf16 v[38:41], v[142:145], v[202:205], v[38:41]
	v_mfma_f32_16x16x32_bf16 v[30:33], v[156:159], v[202:205], v[30:33]
	v_mfma_f32_16x16x32_bf16 v[22:25], v[142:145], v[210:213], v[22:25]
	v_mfma_f32_16x16x32_bf16 v[14:17], v[156:159], v[210:213], v[14:17]
	v_mfma_f32_16x16x32_bf16 v[62:65], v[152:155], v[184:187], v[62:65]
	v_mfma_f32_16x16x32_bf16 v[58:61], v[160:163], v[184:187], v[58:61]
	v_mfma_f32_16x16x32_bf16 v[54:57], v[152:155], v[192:195], v[54:57]
	v_mfma_f32_16x16x32_bf16 v[46:49], v[160:163], v[192:195], v[46:49]
	v_mfma_f32_16x16x32_bf16 v[38:41], v[152:155], v[206:209], v[38:41]
	v_mfma_f32_16x16x32_bf16 v[30:33], v[160:163], v[206:209], v[30:33]
	v_mfma_f32_16x16x32_bf16 v[22:25], v[152:155], v[214:217], v[22:25]
	v_mfma_f32_16x16x32_bf16 v[14:17], v[160:163], v[214:217], v[14:17]
	v_mfma_f32_16x16x32_bf16 v[50:53], v[164:167], v[180:183], v[50:53]
	v_mfma_f32_16x16x32_bf16 v[42:45], v[172:175], v[180:183], v[42:45]
	v_mfma_f32_16x16x32_bf16 v[34:37], v[164:167], v[188:191], v[34:37]
	v_mfma_f32_16x16x32_bf16 v[26:29], v[172:175], v[188:191], v[26:29]
	v_mfma_f32_16x16x32_bf16 v[18:21], v[164:167], v[202:205], v[18:21]
	v_mfma_f32_16x16x32_bf16 v[10:13], v[172:175], v[202:205], v[10:13]
	v_mfma_f32_16x16x32_bf16 v[6:9], v[164:167], v[210:213], v[6:9]
	v_mfma_f32_16x16x32_bf16 v[2:5], v[172:175], v[210:213], v[2:5]
	v_mfma_f32_16x16x32_bf16 v[50:53], v[168:171], v[184:187], v[50:53]
	v_mfma_f32_16x16x32_bf16 v[42:45], v[176:179], v[184:187], v[42:45]
	v_mfma_f32_16x16x32_bf16 v[34:37], v[168:171], v[192:195], v[34:37]
	v_mfma_f32_16x16x32_bf16 v[26:29], v[176:179], v[192:195], v[26:29]
	v_mfma_f32_16x16x32_bf16 v[18:21], v[168:171], v[206:209], v[18:21]
	v_mfma_f32_16x16x32_bf16 v[10:13], v[176:179], v[206:209], v[10:13]
	v_mfma_f32_16x16x32_bf16 v[6:9], v[168:171], v[214:217], v[6:9]
	v_mfma_f32_16x16x32_bf16 v[2:5], v[176:179], v[214:217], v[2:5]
	s_barrier
	s_setprio 0
	s_add_u32 s69, s69, 0x100
	s_addc_u32 s70, s70, 0
	s_add_u32 s58, s58, 0x100
	s_addc_u32 s59, s59, 0
	s_cmp_ge_i32 s71, s64
	s_mov_b32 s8, s71
	s_cbranch_scc0 .LBB0_1135
	s_and_b64 vcc, exec, s[38:39]
	s_cbranch_vccz .LBB0_1138
	s_barrier

.LBB0_1145:
	s_andn2_b64 vcc, exec, s[4:5]
	s_cbranch_vccnz .LBB0_1124
	s_mov_b32 s100, 1
	s_branch .LBB0_1124

.LBB0_2238:
	s_ashr_i32 s53, s52, 31
	s_lshl_b64 s[0:1], s[52:53], 21
	s_add_u32 s49, s38, s0
	s_addc_u32 s53, s39, s1
	s_ashr_i32 s51, s50, 31
	s_lshl_b64 s[0:1], s[50:51], 1
	s_add_u32 s62, s49, s0
	s_addc_u32 s63, s53, s1
	s_and_b64 s[64:65], s[58:59], exec
	s_cselect_b32 s51, s63, s9
	s_cselect_b32 s53, s62, s8
	s_ashr_i32 s49, s48, 31
	s_lshl_b64 s[64:65], s[48:49], 21
	s_add_u32 s49, s40, s64
	s_addc_u32 s65, s41, s65
	s_add_u32 s64, s49, s0
	s_addc_u32 s65, s65, s1
	s_and_b64 s[0:1], s[58:59], exec
	s_cselect_b32 s49, s65, s45
	s_cselect_b32 s69, s64, s44
	s_add_i32 s70, s35, -2
	s_add_u32 s71, s44, 0x100
	s_addc_u32 s72, s45, 0
	s_add_u32 s44, s8, 0x100080
	v_mov_b32_e32 v2, 0
	s_addc_u32 s45, s9, 0
	s_mov_b32 s8, 0
	v_mov_b32_e32 v3, v2
	v_mov_b32_e32 v4, v2
	v_mov_b32_e32 v5, v2
	v_mov_b32_e32 v6, v2
	v_mov_b32_e32 v7, v2
	v_mov_b32_e32 v8, v2
	v_mov_b32_e32 v9, v2
	v_mov_b32_e32 v18, v2
	v_mov_b32_e32 v19, v2
	v_mov_b32_e32 v20, v2
	v_mov_b32_e32 v21, v2
	v_mov_b32_e32 v22, v2
	v_mov_b32_e32 v23, v2
	v_mov_b32_e32 v24, v2
	v_mov_b32_e32 v25, v2
	v_mov_b32_e32 v34, v2
	v_mov_b32_e32 v35, v2
	v_mov_b32_e32 v36, v2
	v_mov_b32_e32 v37, v2
	v_mov_b32_e32 v38, v2
	v_mov_b32_e32 v39, v2
	v_mov_b32_e32 v40, v2
	v_mov_b32_e32 v41, v2
	v_mov_b32_e32 v50, v2
	v_mov_b32_e32 v51, v2
	v_mov_b32_e32 v52, v2
	v_mov_b32_e32 v53, v2
	v_mov_b32_e32 v54, v2
	v_mov_b32_e32 v55, v2
	v_mov_b32_e32 v56, v2
	v_mov_b32_e32 v57, v2
	v_mov_b32_e32 v10, v2
	v_mov_b32_e32 v11, v2
	v_mov_b32_e32 v12, v2
	v_mov_b32_e32 v13, v2
	v_mov_b32_e32 v14, v2
	v_mov_b32_e32 v15, v2
	v_mov_b32_e32 v16, v2
	v_mov_b32_e32 v17, v2
	v_mov_b32_e32 v26, v2
	v_mov_b32_e32 v27, v2
	v_mov_b32_e32 v28, v2
	v_mov_b32_e32 v29, v2
	v_mov_b32_e32 v30, v2
	v_mov_b32_e32 v31, v2
	v_mov_b32_e32 v32, v2
	v_mov_b32_e32 v33, v2
	v_mov_b32_e32 v42, v2
	v_mov_b32_e32 v43, v2
	v_mov_b32_e32 v44, v2
	v_mov_b32_e32 v45, v2
	s_nop 0
	v_mov_b32_e32 v46, v2
	v_mov_b32_e32 v47, v2
	v_mov_b32_e32 v48, v2
	v_mov_b32_e32 v49, v2
	v_mov_b32_e32 v58, v2
	v_mov_b32_e32 v59, v2
	v_mov_b32_e32 v60, v2
	v_mov_b32_e32 v61, v2
	v_mov_b32_e32 v62, v2
	v_mov_b32_e32 v63, v2
	v_mov_b32_e32 v64, v2
	v_mov_b32_e32 v65, v2
	v_mov_b32_e32 v66, v2
	v_mov_b32_e32 v67, v2
	v_mov_b32_e32 v68, v2
	v_mov_b32_e32 v69, v2
	v_mov_b32_e32 v70, v2
	v_mov_b32_e32 v71, v2
	v_mov_b32_e32 v72, v2
	v_mov_b32_e32 v73, v2
	v_mov_b32_e32 v82, v2
	v_mov_b32_e32 v83, v2
	v_mov_b32_e32 v84, v2
	v_mov_b32_e32 v85, v2
	v_mov_b32_e32 v86, v2
	v_mov_b32_e32 v87, v2
	v_mov_b32_e32 v88, v2
	v_mov_b32_e32 v89, v2
	v_mov_b32_e32 v98, v2
	v_mov_b32_e32 v99, v2
	v_mov_b32_e32 v100, v2
	v_mov_b32_e32 v101, v2
	v_mov_b32_e32 v102, v2
	v_mov_b32_e32 v103, v2
	v_mov_b32_e32 v104, v2
	v_mov_b32_e32 v105, v2
	v_mov_b32_e32 v114, v2
	v_mov_b32_e32 v115, v2
	v_mov_b32_e32 v116, v2
	v_mov_b32_e32 v117, v2
	v_mov_b32_e32 v118, v2
	v_mov_b32_e32 v119, v2
	v_mov_b32_e32 v120, v2
	v_mov_b32_e32 v121, v2
	v_mov_b32_e32 v74, v2
	v_mov_b32_e32 v75, v2
	v_mov_b32_e32 v76, v2
	v_mov_b32_e32 v77, v2
	v_mov_b32_e32 v78, v2
	v_mov_b32_e32 v79, v2
	v_mov_b32_e32 v80, v2
	v_mov_b32_e32 v81, v2
	v_mov_b32_e32 v90, v2
	v_mov_b32_e32 v91, v2
	v_mov_b32_e32 v92, v2
	v_mov_b32_e32 v93, v2
	v_mov_b32_e32 v94, v2
	v_mov_b32_e32 v95, v2
	v_mov_b32_e32 v96, v2
	v_mov_b32_e32 v97, v2
	v_mov_b32_e32 v106, v2
	v_mov_b32_e32 v107, v2
	v_mov_b32_e32 v108, v2
	v_mov_b32_e32 v109, v2
	v_mov_b32_e32 v110, v2
	v_mov_b32_e32 v111, v2
	v_mov_b32_e32 v112, v2
	v_mov_b32_e32 v113, v2
	v_mov_b32_e32 v122, v2
	v_mov_b32_e32 v123, v2
	v_mov_b32_e32 v124, v2
	v_mov_b32_e32 v125, v2
	v_mov_b32_e32 v126, v2
	v_mov_b32_e32 v127, v2
	v_mov_b32_e32 v128, v2
	v_mov_b32_e32 v129, v2
	s_cmp_eq_u32 s100, 1
	s_cbranch_scc0 .Ldefbar_skip_3
	s_mov_b32 s100, 0
	s_barrier
.Ldefbar_skip_3:
.LBB0_2239:
	s_add_i32 s73, s8, 2
	s_add_u32 s0, s44, 0xfff00080
	s_addc_u32 s1, s45, -1
	s_add_i32 s77, 0, 0x10000
	s_cmp_eq_u32 s70, s8
	s_cselect_b32 s67, s51, s1
	s_cselect_b32 s66, s53, s0
	s_cselect_b32 s9, s49, s72
	s_cselect_b32 s8, s69, s71
	s_add_i32 s78, 0, 0x14000
	v_add_u32_e32 v142, s77, v244
	v_add_u32_e32 v158, s78, v244
	ds_read_b128 v[130:133], v142
	ds_read_b128 v[134:137], v142 offset:1024
	ds_read_b128 v[138:141], v142 offset:2048
	ds_read_b128 v[142:145], v142 offset:3072
	ds_read_b128 v[146:149], v158
	ds_read_b128 v[150:153], v158 offset:1024
	ds_read_b128 v[154:157], v158 offset:2048
	ds_read_b128 v[158:161], v158 offset:3072
	v_lshl_add_u64 v[194:195], s[44:45], 0, v[210:211]
	s_add_i32 m0, s3, 0xc000
	ds_read_b128 v[162:165], v246
	ds_read_b128 v[166:169], v246 offset:1024
	ds_read_b128 v[170:173], v246 offset:2048
	ds_read_b128 v[174:177], v246 offset:3072
	ds_read_b128 v[178:181], v246 offset:4096
	ds_read_b128 v[182:185], v246 offset:5120
	ds_read_b128 v[186:189], v246 offset:6144
	ds_read_b128 v[190:193], v246 offset:7168
	global_load_lds_dwordx4 v[194:195], off
	v_lshl_add_u64 v[194:195], s[44:45], 0, v[208:209]
	s_add_i32 m0, s3, 0xe000
	s_nop 0
	global_load_lds_dwordx4 v[194:195], off
	s_waitcnt vmcnt(8)
	s_waitcnt lgkmcnt(0)
	s_setprio 1
	s_barrier
	v_mfma_f32_16x16x32_bf16 v[126:129], v[130:133], v[162:165], v[126:129]
	v_mfma_f32_16x16x32_bf16 v[122:125], v[138:141], v[162:165], v[122:125]
	v_mfma_f32_16x16x32_bf16 v[110:113], v[130:133], v[170:173], v[110:113]
	v_mfma_f32_16x16x32_bf16 v[106:109], v[138:141], v[170:173], v[106:109]
	v_mfma_f32_16x16x32_bf16 v[94:97], v[130:133], v[178:181], v[94:97]
	v_mfma_f32_16x16x32_bf16 v[90:93], v[138:141], v[178:181], v[90:93]
	v_mfma_f32_16x16x32_bf16 v[78:81], v[130:133], v[186:189], v[78:81]
	v_mfma_f32_16x16x32_bf16 v[74:77], v[138:141], v[186:189], v[74:77]
	v_mfma_f32_16x16x32_bf16 v[126:129], v[134:137], v[166:169], v[126:129]
	v_mfma_f32_16x16x32_bf16 v[122:125], v[142:145], v[166:169], v[122:125]
	v_mfma_f32_16x16x32_bf16 v[110:113], v[134:137], v[174:177], v[110:113]
	v_mfma_f32_16x16x32_bf16 v[106:109], v[142:145], v[174:177], v[106:109]
	v_mfma_f32_16x16x32_bf16 v[94:97], v[134:137], v[182:185], v[94:97]
	v_mfma_f32_16x16x32_bf16 v[90:93], v[142:145], v[182:185], v[90:93]
	v_mfma_f32_16x16x32_bf16 v[78:81], v[134:137], v[190:193], v[78:81]
	v_mfma_f32_16x16x32_bf16 v[74:77], v[142:145], v[190:193], v[74:77]
	v_mfma_f32_16x16x32_bf16 v[118:121], v[146:149], v[162:165], v[118:121]
	v_mfma_f32_16x16x32_bf16 v[114:117], v[154:157], v[162:165], v[114:117]
	v_mfma_f32_16x16x32_bf16 v[102:105], v[146:149], v[170:173], v[102:105]
	v_mfma_f32_16x16x32_bf16 v[98:101], v[154:157], v[170:173], v[98:101]
	v_mfma_f32_16x16x32_bf16 v[86:89], v[146:149], v[178:181], v[86:89]
	v_mfma_f32_16x16x32_bf16 v[82:85], v[154:157], v[178:181], v[82:85]
	v_mfma_f32_16x16x32_bf16 v[70:73], v[146:149], v[186:189], v[70:73]
	v_mfma_f32_16x16x32_bf16 v[66:69], v[154:157], v[186:189], v[66:69]
	v_mfma_f32_16x16x32_bf16 v[118:121], v[150:153], v[166:169], v[118:121]
	v_mfma_f32_16x16x32_bf16 v[114:117], v[158:161], v[166:169], v[114:117]
	v_mfma_f32_16x16x32_bf16 v[102:105], v[150:153], v[174:177], v[102:105]
	v_mfma_f32_16x16x32_bf16 v[98:101], v[158:161], v[174:177], v[98:101]
	v_mfma_f32_16x16x32_bf16 v[86:89], v[150:153], v[182:185], v[86:89]
	v_mfma_f32_16x16x32_bf16 v[82:85], v[158:161], v[182:185], v[82:85]
	v_mfma_f32_16x16x32_bf16 v[70:73], v[150:153], v[190:193], v[70:73]
	v_mfma_f32_16x16x32_bf16 v[66:69], v[158:161], v[190:193], v[66:69]
	s_barrier
	s_setprio 0
	s_add_i32 s0, s77, s2
	v_lshl_add_u64 v[194:195], s[8:9], 0, v[196:197]
	s_mov_b32 m0, s0
	ds_read_b128 v[162:165], v246 offset:16384
	ds_read_b128 v[166:169], v246 offset:17408
	ds_read_b128 v[170:173], v246 offset:18432
	ds_read_b128 v[174:177], v246 offset:19456
	ds_read_b128 v[178:181], v246 offset:20480
	ds_read_b128 v[182:185], v246 offset:21504
	ds_read_b128 v[186:189], v246 offset:22528
	ds_read_b128 v[190:193], v246 offset:23552
	global_load_lds_dwordx4 v[194:195], off
	s_add_i32 m0, s0, 0x2000
	s_add_u32 s0, s8, 0x100000
	v_lshl_add_u64 v[212:213], s[8:9], 0, v[202:203]
	s_addc_u32 s1, s9, 0
	s_add_i32 s77, s78, s2
	global_load_lds_dwordx4 v[212:213], off
	v_lshl_add_u64 v[214:215], s[0:1], 0, v[196:197]
	s_mov_b32 m0, s77
	v_lshl_add_u64 v[216:217], s[66:67], 0, v[204:205]
	global_load_lds_dwordx4 v[214:215], off
	v_lshl_add_u64 v[214:215], s[0:1], 0, v[202:203]
	s_add_i32 m0, s77, 0x2000
	s_nop 0
	global_load_lds_dwordx4 v[214:215], off
	v_lshl_add_u64 v[214:215], s[66:67], 0, v[206:207]
	s_mov_b32 m0, s3
	s_nop 0
	global_load_lds_dwordx4 v[214:215], off
	s_mov_b32 m0, s10
	s_nop 0
	global_load_lds_dwordx4 v[216:217], off
	s_waitcnt vmcnt(8)
	s_waitcnt lgkmcnt(0)
	s_setprio 1
	s_barrier
	v_mfma_f32_16x16x32_bf16 v[62:65], v[130:133], v[162:165], v[62:65]
	v_mfma_f32_16x16x32_bf16 v[58:61], v[138:141], v[162:165], v[58:61]
	v_mfma_f32_16x16x32_bf16 v[46:49], v[130:133], v[170:173], v[46:49]
	v_mfma_f32_16x16x32_bf16 v[42:45], v[138:141], v[170:173], v[42:45]
	v_mfma_f32_16x16x32_bf16 v[30:33], v[130:133], v[178:181], v[30:33]
	v_mfma_f32_16x16x32_bf16 v[26:29], v[138:141], v[178:181], v[26:29]
	v_mfma_f32_16x16x32_bf16 v[14:17], v[130:133], v[186:189], v[14:17]
	v_mfma_f32_16x16x32_bf16 v[10:13], v[138:141], v[186:189], v[10:13]
	v_mfma_f32_16x16x32_bf16 v[62:65], v[134:137], v[166:169], v[62:65]
	v_mfma_f32_16x16x32_bf16 v[58:61], v[142:145], v[166:169], v[58:61]
	v_mfma_f32_16x16x32_bf16 v[46:49], v[134:137], v[174:177], v[46:49]
	v_mfma_f32_16x16x32_bf16 v[42:45], v[142:145], v[174:177], v[42:45]
	v_mfma_f32_16x16x32_bf16 v[30:33], v[134:137], v[182:185], v[30:33]
	v_mfma_f32_16x16x32_bf16 v[26:29], v[142:145], v[182:185], v[26:29]
	v_mfma_f32_16x16x32_bf16 v[14:17], v[134:137], v[190:193], v[14:17]
	v_mfma_f32_16x16x32_bf16 v[10:13], v[142:145], v[190:193], v[10:13]
	v_mfma_f32_16x16x32_bf16 v[54:57], v[146:149], v[162:165], v[54:57]
	v_mfma_f32_16x16x32_bf16 v[50:53], v[154:157], v[162:165], v[50:53]
	v_mfma_f32_16x16x32_bf16 v[38:41], v[146:149], v[170:173], v[38:41]
	v_mfma_f32_16x16x32_bf16 v[34:37], v[154:157], v[170:173], v[34:37]
	v_mfma_f32_16x16x32_bf16 v[22:25], v[146:149], v[178:181], v[22:25]
	v_mfma_f32_16x16x32_bf16 v[18:21], v[154:157], v[178:181], v[18:21]
	v_mfma_f32_16x16x32_bf16 v[6:9], v[146:149], v[186:189], v[6:9]
	v_mfma_f32_16x16x32_bf16 v[2:5], v[154:157], v[186:189], v[2:5]
	v_mfma_f32_16x16x32_bf16 v[54:57], v[150:153], v[166:169], v[54:57]
	v_mfma_f32_16x16x32_bf16 v[50:53], v[158:161], v[166:169], v[50:53]
	v_mfma_f32_16x16x32_bf16 v[38:41], v[150:153], v[174:177], v[38:41]
	v_mfma_f32_16x16x32_bf16 v[34:37], v[158:161], v[174:177], v[34:37]
	v_mfma_f32_16x16x32_bf16 v[22:25], v[150:153], v[182:185], v[22:25]
	v_mfma_f32_16x16x32_bf16 v[18:21], v[158:161], v[182:185], v[18:21]
	v_mfma_f32_16x16x32_bf16 v[6:9], v[150:153], v[190:193], v[6:9]
	v_mfma_f32_16x16x32_bf16 v[2:5], v[158:161], v[190:193], v[2:5]
	s_barrier
	s_setprio 0
	s_add_i32 s77, 0, 0x18000
	s_add_i32 s78, 0, 0x1c000
	v_add_u32_e32 v142, s77, v244
	v_add_u32_e32 v158, s78, v244
	ds_read_b128 v[130:133], v142
	ds_read_b128 v[134:137], v142 offset:1024
	ds_read_b128 v[138:141], v142 offset:2048
	ds_read_b128 v[142:145], v142 offset:3072
	ds_read_b128 v[146:149], v158
	ds_read_b128 v[150:153], v158 offset:1024
	ds_read_b128 v[154:157], v158 offset:2048
	ds_read_b128 v[158:161], v158 offset:3072
	s_add_u32 s0, s66, 0x100000
	s_addc_u32 s1, s67, 0
	s_mov_b32 m0, s11
	v_lshl_add_u64 v[218:219], s[0:1], 0, v[206:207]
	ds_read_b128 v[162:165], v246 offset:32768
	ds_read_b128 v[166:169], v246 offset:33792
	ds_read_b128 v[170:173], v246 offset:34816
	ds_read_b128 v[174:177], v246 offset:35840
	ds_read_b128 v[178:181], v246 offset:36864
	ds_read_b128 v[182:185], v246 offset:37888
	ds_read_b128 v[186:189], v246 offset:38912
	ds_read_b128 v[190:193], v246 offset:39936
	global_load_lds_dwordx4 v[218:219], off
	v_lshl_add_u64 v[218:219], s[0:1], 0, v[204:205]
	s_mov_b32 m0, s26
	s_nop 0
	global_load_lds_dwordx4 v[218:219], off
	s_waitcnt vmcnt(8)
	s_waitcnt lgkmcnt(0)
	s_setprio 1
	s_barrier
	v_mfma_f32_16x16x32_bf16 v[126:129], v[130:133], v[162:165], v[126:129]
	v_mfma_f32_16x16x32_bf16 v[122:125], v[138:141], v[162:165], v[122:125]
	v_mfma_f32_16x16x32_bf16 v[110:113], v[130:133], v[170:173], v[110:113]
	v_mfma_f32_16x16x32_bf16 v[106:109], v[138:141], v[170:173], v[106:109]
	v_mfma_f32_16x16x32_bf16 v[94:97], v[130:133], v[178:181], v[94:97]
	v_mfma_f32_16x16x32_bf16 v[90:93], v[138:141], v[178:181], v[90:93]
	v_mfma_f32_16x16x32_bf16 v[78:81], v[130:133], v[186:189], v[78:81]
	v_mfma_f32_16x16x32_bf16 v[74:77], v[138:141], v[186:189], v[74:77]
	v_mfma_f32_16x16x32_bf16 v[126:129], v[134:137], v[166:169], v[126:129]
	v_mfma_f32_16x16x32_bf16 v[122:125], v[142:145], v[166:169], v[122:125]
	v_mfma_f32_16x16x32_bf16 v[110:113], v[134:137], v[174:177], v[110:113]
	v_mfma_f32_16x16x32_bf16 v[106:109], v[142:145], v[174:177], v[106:109]
	v_mfma_f32_16x16x32_bf16 v[94:97], v[134:137], v[182:185], v[94:97]
	v_mfma_f32_16x16x32_bf16 v[90:93], v[142:145], v[182:185], v[90:93]
	v_mfma_f32_16x16x32_bf16 v[78:81], v[134:137], v[190:193], v[78:81]
	v_mfma_f32_16x16x32_bf16 v[74:77], v[142:145], v[190:193], v[74:77]
	v_mfma_f32_16x16x32_bf16 v[118:121], v[146:149], v[162:165], v[118:121]
	v_mfma_f32_16x16x32_bf16 v[114:117], v[154:157], v[162:165], v[114:117]
	v_mfma_f32_16x16x32_bf16 v[102:105], v[146:149], v[170:173], v[102:105]
	v_mfma_f32_16x16x32_bf16 v[98:101], v[154:157], v[170:173], v[98:101]
	v_mfma_f32_16x16x32_bf16 v[86:89], v[146:149], v[178:181], v[86:89]
	v_mfma_f32_16x16x32_bf16 v[82:85], v[154:157], v[178:181], v[82:85]
	v_mfma_f32_16x16x32_bf16 v[70:73], v[146:149], v[186:189], v[70:73]
	v_mfma_f32_16x16x32_bf16 v[66:69], v[154:157], v[186:189], v[66:69]
	v_mfma_f32_16x16x32_bf16 v[118:121], v[150:153], v[166:169], v[118:121]
	v_mfma_f32_16x16x32_bf16 v[114:117], v[158:161], v[166:169], v[114:117]
	v_mfma_f32_16x16x32_bf16 v[102:105], v[150:153], v[174:177], v[102:105]
	v_mfma_f32_16x16x32_bf16 v[98:101], v[158:161], v[174:177], v[98:101]
	v_mfma_f32_16x16x32_bf16 v[86:89], v[150:153], v[182:185], v[86:89]
	v_mfma_f32_16x16x32_bf16 v[82:85], v[158:161], v[182:185], v[82:85]
	v_mfma_f32_16x16x32_bf16 v[70:73], v[150:153], v[190:193], v[70:73]
	v_mfma_f32_16x16x32_bf16 v[66:69], v[158:161], v[190:193], v[66:69]
	s_barrier
	s_setprio 0
	s_add_i32 s0, s77, s2
	v_lshl_add_u64 v[194:195], v[194:195], 0, s[16:17]
	s_mov_b32 m0, s0
	ds_read_b128 v[162:165], v246 offset:49152
	ds_read_b128 v[166:169], v246 offset:50176
	ds_read_b128 v[170:173], v246 offset:51200
	ds_read_b128 v[174:177], v246 offset:52224
	ds_read_b128 v[178:181], v246 offset:53248
	ds_read_b128 v[182:185], v246 offset:54272
	ds_read_b128 v[186:189], v246 offset:55296
	ds_read_b128 v[190:193], v246 offset:56320
	global_load_lds_dwordx4 v[194:195], off
	s_add_i32 m0, s0, 0x2000
	s_add_u32 s0, s8, 0x100080
	v_lshl_add_u64 v[194:195], v[212:213], 0, s[16:17]
	s_addc_u32 s1, s9, 0
	s_add_i32 s8, s78, s2
	global_load_lds_dwordx4 v[194:195], off
	v_lshl_add_u64 v[194:195], s[0:1], 0, v[196:197]
	s_mov_b32 m0, s8
	s_nop 0
	global_load_lds_dwordx4 v[194:195], off
	v_lshl_add_u64 v[194:195], s[0:1], 0, v[202:203]
	s_add_i32 m0, s8, 0x2000
	s_nop 0
	global_load_lds_dwordx4 v[194:195], off
	v_lshl_add_u64 v[194:195], v[214:215], 0, s[16:17]
	s_mov_b32 m0, s27
	s_nop 0
	global_load_lds_dwordx4 v[194:195], off
	v_lshl_add_u64 v[194:195], v[216:217], 0, s[16:17]
	s_mov_b32 m0, s28
	s_nop 0
	global_load_lds_dwordx4 v[194:195], off
	s_waitcnt vmcnt(8)
	s_waitcnt lgkmcnt(0)
	s_setprio 1
	s_barrier
	v_mfma_f32_16x16x32_bf16 v[62:65], v[130:133], v[162:165], v[62:65]
	v_mfma_f32_16x16x32_bf16 v[58:61], v[138:141], v[162:165], v[58:61]
	v_mfma_f32_16x16x32_bf16 v[46:49], v[130:133], v[170:173], v[46:49]
	v_mfma_f32_16x16x32_bf16 v[42:45], v[138:141], v[170:173], v[42:45]
	v_mfma_f32_16x16x32_bf16 v[30:33], v[130:133], v[178:181], v[30:33]
	v_mfma_f32_16x16x32_bf16 v[26:29], v[138:141], v[178:181], v[26:29]
	v_mfma_f32_16x16x32_bf16 v[14:17], v[130:133], v[186:189], v[14:17]
	v_mfma_f32_16x16x32_bf16 v[10:13], v[138:141], v[186:189], v[10:13]
	v_mfma_f32_16x16x32_bf16 v[62:65], v[134:137], v[166:169], v[62:65]
	v_mfma_f32_16x16x32_bf16 v[58:61], v[142:145], v[166:169], v[58:61]
	v_mfma_f32_16x16x32_bf16 v[46:49], v[134:137], v[174:177], v[46:49]
	v_mfma_f32_16x16x32_bf16 v[42:45], v[142:145], v[174:177], v[42:45]
	v_mfma_f32_16x16x32_bf16 v[30:33], v[134:137], v[182:185], v[30:33]
	v_mfma_f32_16x16x32_bf16 v[26:29], v[142:145], v[182:185], v[26:29]
	v_mfma_f32_16x16x32_bf16 v[14:17], v[134:137], v[190:193], v[14:17]
	v_mfma_f32_16x16x32_bf16 v[10:13], v[142:145], v[190:193], v[10:13]
	v_mfma_f32_16x16x32_bf16 v[54:57], v[146:149], v[162:165], v[54:57]
	v_mfma_f32_16x16x32_bf16 v[50:53], v[154:157], v[162:165], v[50:53]
	v_mfma_f32_16x16x32_bf16 v[38:41], v[146:149], v[170:173], v[38:41]
	v_mfma_f32_16x16x32_bf16 v[34:37], v[154:157], v[170:173], v[34:37]
	v_mfma_f32_16x16x32_bf16 v[22:25], v[146:149], v[178:181], v[22:25]
	v_mfma_f32_16x16x32_bf16 v[18:21], v[154:157], v[178:181], v[18:21]
	v_mfma_f32_16x16x32_bf16 v[6:9], v[146:149], v[186:189], v[6:9]
	v_mfma_f32_16x16x32_bf16 v[2:5], v[154:157], v[186:189], v[2:5]
	v_mfma_f32_16x16x32_bf16 v[54:57], v[150:153], v[166:169], v[54:57]
	v_mfma_f32_16x16x32_bf16 v[50:53], v[158:161], v[166:169], v[50:53]
	v_mfma_f32_16x16x32_bf16 v[38:41], v[150:153], v[174:177], v[38:41]
	v_mfma_f32_16x16x32_bf16 v[34:37], v[158:161], v[174:177], v[34:37]
	v_mfma_f32_16x16x32_bf16 v[22:25], v[150:153], v[182:185], v[22:25]
	v_mfma_f32_16x16x32_bf16 v[18:21], v[158:161], v[182:185], v[18:21]
	v_mfma_f32_16x16x32_bf16 v[6:9], v[150:153], v[190:193], v[6:9]
	v_mfma_f32_16x16x32_bf16 v[2:5], v[158:161], v[190:193], v[2:5]
	s_barrier
	s_setprio 0
	s_add_u32 s71, s71, 0x100
	s_addc_u32 s72, s72, 0
	s_add_u32 s44, s44, 0x100
	s_addc_u32 s45, s45, 0
	s_cmp_ge_i32 s73, s35
	s_mov_b32 s8, s73
	s_cbranch_scc0 .LBB0_2239
	s_and_b64 vcc, exec, s[46:47]
	s_cbranch_vccz .LBB0_2242
	s_barrier

.LBB0_2276:
	s_waitcnt vmcnt(7)
	v_lshlrev_b32_e32 v140, 16, v122
	v_and_b32_e32 v122, 0xffff0000, v122
	v_lshlrev_b32_e32 v142, 16, v124
	v_mul_f32_e32 v140, 0xbfb8aa3b, v140
	v_mul_f32_e32 v142, 0xbfb8aa3b, v142
	v_mul_f32_e32 v122, 0xbfb8aa3b, v122
	v_exp_f32_e32 v140, v140
	v_exp_f32_e32 v142, v142
	v_exp_f32_e32 v122, v122
	v_and_b32_e32 v124, 0xffff0000, v124
	v_add_f32_e32 v140, 1.0, v140
	v_add_f32_e32 v142, 1.0, v142
	v_add_f32_e32 v122, 1.0, v122
	v_mul_f32_e32 v124, 0xbfb8aa3b, v124
	v_rcp_f32_e32 v140, v140
	v_rcp_f32_e32 v142, v142
	v_rcp_f32_e32 v122, v122
	v_exp_f32_e32 v124, v124
	v_lshlrev_b32_e32 v141, 16, v123
	v_lshlrev_b32_e32 v143, 16, v125
	v_lshlrev_b32_e32 v144, 16, v130
	v_and_b32_e32 v130, 0xffff0000, v130
	v_lshlrev_b32_e32 v146, 16, v132
	v_fmac_f32_e32 v144, v62, v140
	v_fmac_f32_e32 v146, v58, v142
	v_fmac_f32_e32 v130, v63, v122
	v_add_f32_e32 v58, 1.0, v124
	v_mul_f32_e32 v62, 0xbfb8aa3b, v141
	v_mul_f32_e32 v63, 0xbfb8aa3b, v143
	v_rcp_f32_e32 v58, v58
	v_exp_f32_e32 v62, v62
	v_exp_f32_e32 v63, v63
	v_and_b32_e32 v123, 0xffff0000, v123
	v_and_b32_e32 v125, 0xffff0000, v125
	v_and_b32_e32 v132, 0xffff0000, v132
	v_fmac_f32_e32 v132, v59, v58
	v_add_f32_e32 v58, 1.0, v62
	v_add_f32_e32 v59, 1.0, v63
	v_mul_f32_e32 v62, 0xbfb8aa3b, v123
	v_mul_f32_e32 v63, 0xbfb8aa3b, v125
	v_exp_f32_e32 v62, v62
	v_exp_f32_e32 v63, v63
	v_rcp_f32_e32 v58, v58
	v_rcp_f32_e32 v59, v59
	v_add_f32_e32 v62, 1.0, v62
	v_add_f32_e32 v63, 1.0, v63
	v_rcp_f32_e32 v62, v62
	v_rcp_f32_e32 v63, v63
	v_lshlrev_b32_e32 v145, 16, v131
	v_and_b32_e32 v131, 0xffff0000, v131
	v_lshlrev_b32_e32 v147, 16, v133
	v_and_b32_e32 v133, 0xffff0000, v133
	v_fmac_f32_e32 v145, v64, v58
	v_fmac_f32_e32 v131, v65, v62
	v_fmac_f32_e32 v133, v61, v63
	v_cvt_pk_bf16_f32 v58, v144, v130
	v_lshl_add_u64 v[62:63], v[138:139], 0, v[126:127]
	v_fmac_f32_e32 v147, v60, v59
	v_cvt_pk_bf16_f32 v59, v145, v131
	v_cvt_pk_bf16_f32 v60, v146, v132
	v_cvt_pk_bf16_f32 v61, v147, v133
	global_store_dwordx4 v[62:63], v[58:61], off
	s_waitcnt vmcnt(7)
	v_lshlrev_b32_e32 v64, 16, v120
	v_mul_f32_e32 v64, 0xbfb8aa3b, v64
	v_lshlrev_b32_e32 v58, 16, v118
	v_and_b32_e32 v59, 0xffff0000, v118
	v_mul_f32_e32 v58, 0xbfb8aa3b, v58
	v_exp_f32_e32 v58, v58
	v_exp_f32_e32 v64, v64
	v_mul_f32_e32 v59, 0xbfb8aa3b, v59
	v_exp_f32_e32 v59, v59
	v_and_b32_e32 v65, 0xffff0000, v120
	v_add_f32_e32 v58, 1.0, v58
	v_add_f32_e32 v64, 1.0, v64
	v_mul_f32_e32 v65, 0xbfb8aa3b, v65
	v_rcp_f32_e32 v58, v58
	v_rcp_f32_e32 v64, v64
	v_add_f32_e32 v59, 1.0, v59
	v_exp_f32_e32 v65, v65
	v_rcp_f32_e32 v59, v59
	v_lshlrev_b32_e32 v60, 16, v119
	v_lshlrev_b32_e32 v120, 16, v114
	v_lshlrev_b32_e32 v122, 16, v116
	v_lshlrev_b32_e32 v118, 16, v121
	v_and_b32_e32 v114, 0xffff0000, v114
	v_fmac_f32_e32 v120, v54, v58
	v_fmac_f32_e32 v122, v50, v64
	v_add_f32_e32 v50, 1.0, v65
	v_mul_f32_e32 v54, 0xbfb8aa3b, v60
	v_fmac_f32_e32 v114, v55, v59
	v_rcp_f32_e32 v50, v50
	v_exp_f32_e32 v54, v54
	v_mul_f32_e32 v55, 0xbfb8aa3b, v118
	v_exp_f32_e32 v55, v55
	v_and_b32_e32 v61, 0xffff0000, v119
	v_and_b32_e32 v116, 0xffff0000, v116
	v_and_b32_e32 v119, 0xffff0000, v121
	v_fmac_f32_e32 v116, v51, v50
	v_add_f32_e32 v50, 1.0, v54
	v_mul_f32_e32 v54, 0xbfb8aa3b, v61
	v_add_f32_e32 v51, 1.0, v55
	v_exp_f32_e32 v54, v54
	v_mul_f32_e32 v55, 0xbfb8aa3b, v119
	v_exp_f32_e32 v55, v55
	v_rcp_f32_e32 v50, v50
	v_add_f32_e32 v54, 1.0, v54
	v_rcp_f32_e32 v51, v51
	v_rcp_f32_e32 v54, v54
	v_add_f32_e32 v55, 1.0, v55
	v_rcp_f32_e32 v55, v55
	v_lshlrev_b32_e32 v121, 16, v115
	v_and_b32_e32 v115, 0xffff0000, v115
	v_lshlrev_b32_e32 v123, 16, v117
	v_and_b32_e32 v117, 0xffff0000, v117
	v_fmac_f32_e32 v121, v56, v50
	v_fmac_f32_e32 v123, v52, v51
	v_fmac_f32_e32 v115, v57, v54
	v_cvt_pk_bf16_f32 v50, v120, v114
	v_cvt_pk_bf16_f32 v51, v121, v115
	v_fmac_f32_e32 v117, v53, v55
	v_cvt_pk_bf16_f32 v52, v122, v116
	v_cvt_pk_bf16_f32 v53, v123, v117
	global_store_dwordx4 v[62:63], v[50:53], off offset:256
	s_waitcnt vmcnt(7)
	v_lshlrev_b32_e32 v54, 16, v112
	v_mul_f32_e32 v54, 0xbfb8aa3b, v54
	v_lshlrev_b32_e32 v50, 16, v110
	v_and_b32_e32 v51, 0xffff0000, v110
	v_mul_f32_e32 v50, 0xbfb8aa3b, v50
	v_mul_f32_e32 v51, 0xbfb8aa3b, v51
	v_exp_f32_e32 v50, v50
	v_exp_f32_e32 v54, v54
	v_exp_f32_e32 v51, v51
	v_and_b32_e32 v55, 0xffff0000, v112
	v_add_f32_e32 v50, 1.0, v50
	v_add_f32_e32 v54, 1.0, v54
	v_add_f32_e32 v51, 1.0, v51
	v_mul_f32_e32 v55, 0xbfb8aa3b, v55
	v_rcp_f32_e32 v50, v50
	v_rcp_f32_e32 v54, v54
	v_rcp_f32_e32 v51, v51
	v_exp_f32_e32 v55, v55
	v_lshlrev_b32_e32 v52, 16, v111
	v_lshlrev_b32_e32 v56, 16, v113
	v_lshlrev_b32_e32 v58, 16, v106
	v_and_b32_e32 v59, 0xffff0000, v106
	v_lshlrev_b32_e32 v62, 16, v108
	v_fmac_f32_e32 v58, v46, v50
	v_fmac_f32_e32 v62, v42, v54
	v_fmac_f32_e32 v59, v47, v51
	v_add_f32_e32 v42, 1.0, v55
	v_mul_f32_e32 v46, 0xbfb8aa3b, v52
	v_mul_f32_e32 v47, 0xbfb8aa3b, v56
	v_rcp_f32_e32 v42, v42
	v_exp_f32_e32 v46, v46
	v_exp_f32_e32 v47, v47
	v_and_b32_e32 v53, 0xffff0000, v111
	v_and_b32_e32 v57, 0xffff0000, v113
	v_and_b32_e32 v63, 0xffff0000, v108
	v_fmac_f32_e32 v63, v43, v42
	v_add_f32_e32 v42, 1.0, v46
	v_add_f32_e32 v43, 1.0, v47
	v_mul_f32_e32 v46, 0xbfb8aa3b, v53
	v_mul_f32_e32 v47, 0xbfb8aa3b, v57
	v_exp_f32_e32 v46, v46
	v_exp_f32_e32 v47, v47
	v_rcp_f32_e32 v42, v42
	v_rcp_f32_e32 v43, v43
	v_add_f32_e32 v46, 1.0, v46
	v_add_f32_e32 v47, 1.0, v47
	v_rcp_f32_e32 v46, v46
	v_rcp_f32_e32 v47, v47
	v_lshlrev_b32_e32 v60, 16, v107
	v_and_b32_e32 v61, 0xffff0000, v107
	v_and_b32_e32 v65, 0xffff0000, v109
	v_lshlrev_b32_e32 v64, 16, v109
	v_fmac_f32_e32 v60, v48, v42
	v_fmac_f32_e32 v61, v49, v46
	v_fmac_f32_e32 v65, v45, v47
	v_cvt_pk_bf16_f32 v42, v58, v59
	v_lshl_add_u64 v[46:47], v[136:137], 0, v[126:127]
	v_fmac_f32_e32 v64, v44, v43
	v_cvt_pk_bf16_f32 v43, v60, v61
	v_cvt_pk_bf16_f32 v44, v62, v63
	v_cvt_pk_bf16_f32 v45, v64, v65
	global_store_dwordx4 v[46:47], v[42:45], off
	s_waitcnt vmcnt(7)
	v_lshlrev_b32_e32 v48, 16, v104
	v_mul_f32_e32 v48, 0xbfb8aa3b, v48
	v_lshlrev_b32_e32 v42, 16, v102
	v_and_b32_e32 v43, 0xffff0000, v102
	v_mul_f32_e32 v42, 0xbfb8aa3b, v42
	v_exp_f32_e32 v42, v42
	v_exp_f32_e32 v48, v48
	v_mul_f32_e32 v43, 0xbfb8aa3b, v43
	v_exp_f32_e32 v43, v43
	v_and_b32_e32 v49, 0xffff0000, v104
	v_add_f32_e32 v42, 1.0, v42
	v_add_f32_e32 v48, 1.0, v48
	v_mul_f32_e32 v49, 0xbfb8aa3b, v49
	v_rcp_f32_e32 v42, v42
	v_rcp_f32_e32 v48, v48
	v_add_f32_e32 v43, 1.0, v43
	v_exp_f32_e32 v49, v49
	v_rcp_f32_e32 v43, v43
	v_lshlrev_b32_e32 v44, 16, v103
	v_lshlrev_b32_e32 v52, 16, v98
	v_lshlrev_b32_e32 v56, 16, v100
	v_lshlrev_b32_e32 v50, 16, v105
	v_and_b32_e32 v53, 0xffff0000, v98
	v_fmac_f32_e32 v52, v38, v42
	v_fmac_f32_e32 v56, v34, v48
	v_add_f32_e32 v34, 1.0, v49
	v_mul_f32_e32 v38, 0xbfb8aa3b, v44
	v_fmac_f32_e32 v53, v39, v43
	v_rcp_f32_e32 v34, v34
	v_exp_f32_e32 v38, v38
	v_mul_f32_e32 v39, 0xbfb8aa3b, v50
	v_exp_f32_e32 v39, v39
	v_and_b32_e32 v45, 0xffff0000, v103
	v_and_b32_e32 v57, 0xffff0000, v100
	v_and_b32_e32 v51, 0xffff0000, v105
	v_fmac_f32_e32 v57, v35, v34
	v_add_f32_e32 v34, 1.0, v38
	v_mul_f32_e32 v38, 0xbfb8aa3b, v45
	v_add_f32_e32 v35, 1.0, v39
	v_exp_f32_e32 v38, v38
	v_mul_f32_e32 v39, 0xbfb8aa3b, v51
	v_exp_f32_e32 v39, v39
	v_rcp_f32_e32 v34, v34
	v_add_f32_e32 v38, 1.0, v38
	v_rcp_f32_e32 v35, v35
	v_rcp_f32_e32 v38, v38
	v_add_f32_e32 v39, 1.0, v39
	v_rcp_f32_e32 v39, v39
	v_lshlrev_b32_e32 v54, 16, v99
	v_and_b32_e32 v55, 0xffff0000, v99
	v_lshlrev_b32_e32 v58, 16, v101
	v_and_b32_e32 v59, 0xffff0000, v101
	v_fmac_f32_e32 v54, v40, v34
	v_fmac_f32_e32 v58, v36, v35
	v_fmac_f32_e32 v55, v41, v38
	v_cvt_pk_bf16_f32 v34, v52, v53
	v_cvt_pk_bf16_f32 v35, v54, v55
	v_fmac_f32_e32 v59, v37, v39
	v_cvt_pk_bf16_f32 v36, v56, v57
	v_cvt_pk_bf16_f32 v37, v58, v59
	global_store_dwordx4 v[46:47], v[34:37], off offset:256
	s_waitcnt vmcnt(7)
	v_lshlrev_b32_e32 v38, 16, v96
	v_mul_f32_e32 v38, 0xbfb8aa3b, v38
	v_lshlrev_b32_e32 v34, 16, v94
	v_and_b32_e32 v35, 0xffff0000, v94
	v_mul_f32_e32 v34, 0xbfb8aa3b, v34
	v_mul_f32_e32 v35, 0xbfb8aa3b, v35
	v_exp_f32_e32 v34, v34
	v_exp_f32_e32 v38, v38
	v_exp_f32_e32 v35, v35
	v_and_b32_e32 v39, 0xffff0000, v96
	v_add_f32_e32 v34, 1.0, v34
	v_add_f32_e32 v38, 1.0, v38
	v_add_f32_e32 v35, 1.0, v35
	v_mul_f32_e32 v39, 0xbfb8aa3b, v39
	v_rcp_f32_e32 v34, v34
	v_rcp_f32_e32 v38, v38
	v_rcp_f32_e32 v35, v35
	v_exp_f32_e32 v39, v39
	v_lshlrev_b32_e32 v36, 16, v95
	v_lshlrev_b32_e32 v40, 16, v97
	v_lshlrev_b32_e32 v42, 16, v90
	v_and_b32_e32 v43, 0xffff0000, v90
	v_lshlrev_b32_e32 v46, 16, v92
	v_fmac_f32_e32 v42, v30, v34
	v_fmac_f32_e32 v46, v26, v38
	v_fmac_f32_e32 v43, v31, v35
	v_add_f32_e32 v26, 1.0, v39
	v_mul_f32_e32 v30, 0xbfb8aa3b, v36
	v_mul_f32_e32 v31, 0xbfb8aa3b, v40
	v_rcp_f32_e32 v26, v26
	v_exp_f32_e32 v30, v30
	v_exp_f32_e32 v31, v31
	v_and_b32_e32 v37, 0xffff0000, v95
	v_and_b32_e32 v41, 0xffff0000, v97
	v_and_b32_e32 v47, 0xffff0000, v92
	v_fmac_f32_e32 v47, v27, v26
	v_add_f32_e32 v26, 1.0, v30
	v_add_f32_e32 v27, 1.0, v31
	v_mul_f32_e32 v30, 0xbfb8aa3b, v37
	v_mul_f32_e32 v31, 0xbfb8aa3b, v41
	v_exp_f32_e32 v30, v30
	v_exp_f32_e32 v31, v31
	v_rcp_f32_e32 v26, v26
	v_rcp_f32_e32 v27, v27
	v_add_f32_e32 v30, 1.0, v30
	v_add_f32_e32 v31, 1.0, v31
	v_rcp_f32_e32 v30, v30
	v_rcp_f32_e32 v31, v31
	v_lshlrev_b32_e32 v44, 16, v91
	v_and_b32_e32 v45, 0xffff0000, v91
	v_and_b32_e32 v49, 0xffff0000, v93
	v_lshlrev_b32_e32 v48, 16, v93
	v_fmac_f32_e32 v44, v32, v26
	v_fmac_f32_e32 v45, v33, v30
	v_fmac_f32_e32 v49, v29, v31
	v_cvt_pk_bf16_f32 v26, v42, v43
	v_lshl_add_u64 v[30:31], v[134:135], 0, v[126:127]
	v_fmac_f32_e32 v48, v28, v27
	v_cvt_pk_bf16_f32 v27, v44, v45
	v_cvt_pk_bf16_f32 v28, v46, v47
	v_cvt_pk_bf16_f32 v29, v48, v49
	global_store_dwordx4 v[30:31], v[26:29], off
	s_waitcnt vmcnt(7)
	v_lshlrev_b32_e32 v32, 16, v88
	v_mul_f32_e32 v32, 0xbfb8aa3b, v32
	v_lshlrev_b32_e32 v26, 16, v86
	v_and_b32_e32 v27, 0xffff0000, v86
	v_mul_f32_e32 v26, 0xbfb8aa3b, v26
	v_exp_f32_e32 v26, v26
	v_exp_f32_e32 v32, v32
	v_mul_f32_e32 v27, 0xbfb8aa3b, v27
	v_exp_f32_e32 v27, v27
	v_and_b32_e32 v33, 0xffff0000, v88
	v_add_f32_e32 v26, 1.0, v26
	v_add_f32_e32 v32, 1.0, v32
	v_mul_f32_e32 v33, 0xbfb8aa3b, v33
	v_rcp_f32_e32 v26, v26
	v_rcp_f32_e32 v32, v32
	v_add_f32_e32 v27, 1.0, v27
	v_exp_f32_e32 v33, v33
	v_rcp_f32_e32 v27, v27
	v_lshlrev_b32_e32 v28, 16, v87
	v_lshlrev_b32_e32 v36, 16, v82
	v_lshlrev_b32_e32 v40, 16, v84
	v_lshlrev_b32_e32 v34, 16, v89
	v_and_b32_e32 v37, 0xffff0000, v82
	v_fmac_f32_e32 v36, v22, v26
	v_fmac_f32_e32 v40, v18, v32
	v_add_f32_e32 v18, 1.0, v33
	v_mul_f32_e32 v22, 0xbfb8aa3b, v28
	v_fmac_f32_e32 v37, v23, v27
	v_rcp_f32_e32 v18, v18
	v_exp_f32_e32 v22, v22
	v_mul_f32_e32 v23, 0xbfb8aa3b, v34
	v_exp_f32_e32 v23, v23
	v_and_b32_e32 v29, 0xffff0000, v87
	v_and_b32_e32 v41, 0xffff0000, v84
	v_and_b32_e32 v35, 0xffff0000, v89
	v_fmac_f32_e32 v41, v19, v18
	v_add_f32_e32 v18, 1.0, v22
	v_mul_f32_e32 v22, 0xbfb8aa3b, v29
	v_add_f32_e32 v19, 1.0, v23
	v_exp_f32_e32 v22, v22
	v_mul_f32_e32 v23, 0xbfb8aa3b, v35
	v_exp_f32_e32 v23, v23
	v_rcp_f32_e32 v18, v18
	v_add_f32_e32 v22, 1.0, v22
	v_rcp_f32_e32 v19, v19
	v_rcp_f32_e32 v22, v22
	v_add_f32_e32 v23, 1.0, v23
	v_rcp_f32_e32 v23, v23
	v_lshlrev_b32_e32 v38, 16, v83
	v_and_b32_e32 v39, 0xffff0000, v83
	v_lshlrev_b32_e32 v42, 16, v85
	v_and_b32_e32 v43, 0xffff0000, v85
	v_fmac_f32_e32 v38, v24, v18
	v_fmac_f32_e32 v42, v20, v19
	v_fmac_f32_e32 v39, v25, v22
	v_cvt_pk_bf16_f32 v18, v36, v37
	v_cvt_pk_bf16_f32 v19, v38, v39
	v_fmac_f32_e32 v43, v21, v23
	v_cvt_pk_bf16_f32 v20, v40, v41
	v_cvt_pk_bf16_f32 v21, v42, v43
	global_store_dwordx4 v[30:31], v[18:21], off offset:256
	s_waitcnt vmcnt(7)
	v_lshlrev_b32_e32 v22, 16, v80
	v_mul_f32_e32 v22, 0xbfb8aa3b, v22
	v_lshlrev_b32_e32 v18, 16, v78
	v_and_b32_e32 v19, 0xffff0000, v78
	v_mul_f32_e32 v18, 0xbfb8aa3b, v18
	v_mul_f32_e32 v19, 0xbfb8aa3b, v19
	v_exp_f32_e32 v18, v18
	v_exp_f32_e32 v22, v22
	v_exp_f32_e32 v19, v19
	v_and_b32_e32 v23, 0xffff0000, v80
	v_add_f32_e32 v18, 1.0, v18
	v_add_f32_e32 v22, 1.0, v22
	v_add_f32_e32 v19, 1.0, v19
	v_mul_f32_e32 v23, 0xbfb8aa3b, v23
	v_rcp_f32_e32 v18, v18
	v_rcp_f32_e32 v22, v22
	v_rcp_f32_e32 v19, v19
	v_exp_f32_e32 v23, v23
	v_lshlrev_b32_e32 v20, 16, v79
	v_lshlrev_b32_e32 v24, 16, v81
	v_lshlrev_b32_e32 v26, 16, v74
	v_and_b32_e32 v27, 0xffff0000, v74
	v_lshlrev_b32_e32 v30, 16, v76
	v_fmac_f32_e32 v26, v14, v18
	v_fmac_f32_e32 v30, v10, v22
	v_fmac_f32_e32 v27, v15, v19
	v_add_f32_e32 v10, 1.0, v23
	v_mul_f32_e32 v14, 0xbfb8aa3b, v20
	v_mul_f32_e32 v15, 0xbfb8aa3b, v24
	v_rcp_f32_e32 v10, v10
	v_exp_f32_e32 v14, v14
	v_exp_f32_e32 v15, v15
	v_and_b32_e32 v21, 0xffff0000, v79
	v_and_b32_e32 v25, 0xffff0000, v81
	v_and_b32_e32 v31, 0xffff0000, v76
	v_fmac_f32_e32 v31, v11, v10
	v_add_f32_e32 v10, 1.0, v14
	v_add_f32_e32 v11, 1.0, v15
	v_mul_f32_e32 v14, 0xbfb8aa3b, v21
	v_mul_f32_e32 v15, 0xbfb8aa3b, v25
	v_exp_f32_e32 v14, v14
	v_exp_f32_e32 v15, v15
	v_rcp_f32_e32 v10, v10
	v_rcp_f32_e32 v11, v11
	v_add_f32_e32 v14, 1.0, v14
	v_add_f32_e32 v15, 1.0, v15
	v_rcp_f32_e32 v14, v14
	v_rcp_f32_e32 v15, v15
	v_lshlrev_b32_e32 v28, 16, v75
	v_and_b32_e32 v29, 0xffff0000, v75
	v_lshlrev_b32_e32 v32, 16, v77
	v_and_b32_e32 v33, 0xffff0000, v77
	v_fmac_f32_e32 v28, v16, v10
	v_fmac_f32_e32 v32, v12, v11
	v_fmac_f32_e32 v29, v17, v14
	v_fmac_f32_e32 v33, v13, v15
	v_cvt_pk_bf16_f32 v10, v26, v27
	v_cvt_pk_bf16_f32 v11, v28, v29
	v_lshl_add_u64 v[14:15], v[128:129], 0, v[126:127]
	v_cvt_pk_bf16_f32 v12, v30, v31
	v_cvt_pk_bf16_f32 v13, v32, v33
	global_store_dwordx4 v[14:15], v[10:13], off
	s_waitcnt vmcnt(7)
	v_lshlrev_b32_e32 v16, 16, v72
	v_mul_f32_e32 v16, 0xbfb8aa3b, v16
	v_lshlrev_b32_e32 v10, 16, v70
	v_and_b32_e32 v11, 0xffff0000, v70
	v_mul_f32_e32 v10, 0xbfb8aa3b, v10
	v_mul_f32_e32 v11, 0xbfb8aa3b, v11
	v_exp_f32_e32 v10, v10
	v_exp_f32_e32 v16, v16
	v_exp_f32_e32 v11, v11
	v_and_b32_e32 v17, 0xffff0000, v72
	v_add_f32_e32 v10, 1.0, v10
	v_add_f32_e32 v16, 1.0, v16
	v_add_f32_e32 v11, 1.0, v11
	v_mul_f32_e32 v17, 0xbfb8aa3b, v17
	v_rcp_f32_e32 v10, v10
	v_rcp_f32_e32 v16, v16
	v_rcp_f32_e32 v11, v11
	v_exp_f32_e32 v17, v17
	v_lshlrev_b32_e32 v12, 16, v71
	v_lshlrev_b32_e32 v18, 16, v73
	v_lshlrev_b32_e32 v20, 16, v66
	v_and_b32_e32 v21, 0xffff0000, v66
	v_lshlrev_b32_e32 v24, 16, v68
	v_fmac_f32_e32 v20, v6, v10
	v_fmac_f32_e32 v24, v2, v16
	v_fmac_f32_e32 v21, v7, v11
	v_add_f32_e32 v2, 1.0, v17
	v_mul_f32_e32 v6, 0xbfb8aa3b, v12
	v_mul_f32_e32 v7, 0xbfb8aa3b, v18
	v_rcp_f32_e32 v2, v2
	v_exp_f32_e32 v6, v6
	v_exp_f32_e32 v7, v7
	v_and_b32_e32 v13, 0xffff0000, v71
	v_and_b32_e32 v19, 0xffff0000, v73
	v_and_b32_e32 v25, 0xffff0000, v68
	v_fmac_f32_e32 v25, v3, v2
	v_add_f32_e32 v2, 1.0, v6
	v_add_f32_e32 v3, 1.0, v7
	v_mul_f32_e32 v6, 0xbfb8aa3b, v13
	v_mul_f32_e32 v7, 0xbfb8aa3b, v19
	v_exp_f32_e32 v6, v6
	v_exp_f32_e32 v7, v7
	v_rcp_f32_e32 v2, v2
	v_rcp_f32_e32 v3, v3
	v_add_f32_e32 v6, 1.0, v6
	v_add_f32_e32 v7, 1.0, v7
	v_rcp_f32_e32 v6, v6
	v_rcp_f32_e32 v7, v7
	v_lshlrev_b32_e32 v22, 16, v67
	v_and_b32_e32 v23, 0xffff0000, v67
	v_lshlrev_b32_e32 v26, 16, v69
	v_and_b32_e32 v27, 0xffff0000, v69
	v_fmac_f32_e32 v22, v8, v2
	v_fmac_f32_e32 v26, v4, v3
	v_fmac_f32_e32 v23, v9, v6
	v_fmac_f32_e32 v27, v5, v7
	v_cvt_pk_bf16_f32 v2, v20, v21
	v_cvt_pk_bf16_f32 v3, v22, v23
	v_cvt_pk_bf16_f32 v4, v24, v25
	v_cvt_pk_bf16_f32 v5, v26, v27
	global_store_dwordx4 v[14:15], v[2:5], off offset:256
	s_andn2_b64 vcc, exec, s[58:59]
	s_mov_b64 s[8:9], -1
	s_cbranch_vccnz .LBB0_2229
	s_andn2_b64 vcc, exec, s[42:43]
	s_cbranch_vccnz .LBB0_2228
	s_mov_b32 s100, 1
	s_branch .LBB0_2228

.LBB0_2356:
	s_ashr_i32 s45, s44, 31
	s_lshl_b64 s[0:1], s[44:45], 20
	s_add_u32 s43, s2, s0
	s_addc_u32 s45, s3, s1
	s_ashr_i32 s41, s40, 31
	s_lshl_b64 s[0:1], s[40:41], 1
	s_add_u32 s48, s43, s0
	s_addc_u32 s49, s45, s1
	s_and_b64 s[50:51], s[46:47], exec
	s_cselect_b32 s41, s49, s63
	s_cselect_b32 s45, s48, s62
	s_ashr_i32 s43, s42, 31
	s_lshl_b64 s[50:51], s[42:43], 20
	s_add_u32 s43, s10, s50
	s_addc_u32 s51, s11, s51
	s_add_u32 s50, s43, s0
	s_addc_u32 s51, s51, s1
	s_and_b64 s[0:1], s[46:47], exec
	s_cselect_b32 s43, s51, s9
	s_cselect_b32 s70, s50, s8
	s_add_i32 s71, s69, -2
	s_add_u32 s72, s8, 0x100
	s_addc_u32 s73, s9, 0
	s_add_u32 s62, s62, 0x80080
	v_mov_b32_e32 v2, 0
	s_addc_u32 s63, s63, 0
	s_mov_b32 s8, 0
	v_mov_b32_e32 v3, v2
	v_mov_b32_e32 v4, v2
	v_mov_b32_e32 v5, v2
	v_mov_b32_e32 v6, v2
	v_mov_b32_e32 v7, v2
	v_mov_b32_e32 v8, v2
	v_mov_b32_e32 v9, v2
	v_mov_b32_e32 v14, v2
	v_mov_b32_e32 v15, v2
	v_mov_b32_e32 v16, v2
	v_mov_b32_e32 v17, v2
	v_mov_b32_e32 v22, v2
	v_mov_b32_e32 v23, v2
	v_mov_b32_e32 v24, v2
	v_mov_b32_e32 v25, v2
	v_mov_b32_e32 v30, v2
	v_mov_b32_e32 v31, v2
	v_mov_b32_e32 v32, v2
	v_mov_b32_e32 v33, v2
	v_mov_b32_e32 v38, v2
	v_mov_b32_e32 v39, v2
	v_mov_b32_e32 v40, v2
	v_mov_b32_e32 v41, v2
	s_nop 0
	v_mov_b32_e32 v46, v2
	v_mov_b32_e32 v47, v2
	v_mov_b32_e32 v48, v2
	v_mov_b32_e32 v49, v2
	v_mov_b32_e32 v54, v2
	v_mov_b32_e32 v55, v2
	v_mov_b32_e32 v56, v2
	v_mov_b32_e32 v57, v2
	v_mov_b32_e32 v10, v2
	v_mov_b32_e32 v11, v2
	v_mov_b32_e32 v12, v2
	v_mov_b32_e32 v13, v2
	v_mov_b32_e32 v18, v2
	v_mov_b32_e32 v19, v2
	v_mov_b32_e32 v20, v2
	v_mov_b32_e32 v21, v2
	v_mov_b32_e32 v26, v2
	v_mov_b32_e32 v27, v2
	v_mov_b32_e32 v28, v2
	v_mov_b32_e32 v29, v2
	v_mov_b32_e32 v34, v2
	v_mov_b32_e32 v35, v2
	v_mov_b32_e32 v36, v2
	v_mov_b32_e32 v37, v2
	v_mov_b32_e32 v42, v2
	v_mov_b32_e32 v43, v2
	v_mov_b32_e32 v44, v2
	v_mov_b32_e32 v45, v2
	v_mov_b32_e32 v50, v2
	v_mov_b32_e32 v51, v2
	v_mov_b32_e32 v52, v2
	v_mov_b32_e32 v53, v2
	v_mov_b32_e32 v58, v2
	v_mov_b32_e32 v59, v2
	v_mov_b32_e32 v60, v2
	v_mov_b32_e32 v61, v2
	v_mov_b32_e32 v62, v2
	v_mov_b32_e32 v63, v2
	v_mov_b32_e32 v64, v2
	v_mov_b32_e32 v65, v2
	v_mov_b32_e32 v66, v2
	v_mov_b32_e32 v67, v2
	v_mov_b32_e32 v68, v2
	v_mov_b32_e32 v69, v2
	v_mov_b32_e32 v70, v2
	v_mov_b32_e32 v71, v2
	v_mov_b32_e32 v72, v2
	v_mov_b32_e32 v73, v2
	v_mov_b32_e32 v78, v2
	v_mov_b32_e32 v79, v2
	v_mov_b32_e32 v80, v2
	v_mov_b32_e32 v81, v2
	v_mov_b32_e32 v86, v2
	v_mov_b32_e32 v87, v2
	v_mov_b32_e32 v88, v2
	v_mov_b32_e32 v89, v2
	v_mov_b32_e32 v94, v2
	v_mov_b32_e32 v95, v2
	v_mov_b32_e32 v96, v2
	v_mov_b32_e32 v97, v2
	v_mov_b32_e32 v102, v2
	v_mov_b32_e32 v103, v2
	v_mov_b32_e32 v104, v2
	v_mov_b32_e32 v105, v2
	v_mov_b32_e32 v114, v2
	v_mov_b32_e32 v115, v2
	v_mov_b32_e32 v116, v2
	v_mov_b32_e32 v117, v2
	v_mov_b32_e32 v118, v2
	v_mov_b32_e32 v119, v2
	v_mov_b32_e32 v120, v2
	v_mov_b32_e32 v121, v2
	v_mov_b32_e32 v74, v2
	v_mov_b32_e32 v75, v2
	v_mov_b32_e32 v76, v2
	v_mov_b32_e32 v77, v2
	v_mov_b32_e32 v82, v2
	v_mov_b32_e32 v83, v2
	v_mov_b32_e32 v84, v2
	v_mov_b32_e32 v85, v2
	v_mov_b32_e32 v90, v2
	v_mov_b32_e32 v91, v2
	v_mov_b32_e32 v92, v2
	v_mov_b32_e32 v93, v2
	v_mov_b32_e32 v98, v2
	v_mov_b32_e32 v99, v2
	v_mov_b32_e32 v100, v2
	v_mov_b32_e32 v101, v2
	v_mov_b32_e32 v106, v2
	v_mov_b32_e32 v107, v2
	v_mov_b32_e32 v108, v2
	v_mov_b32_e32 v109, v2
	v_mov_b32_e32 v110, v2
	v_mov_b32_e32 v111, v2
	v_mov_b32_e32 v112, v2
	v_mov_b32_e32 v113, v2
	v_mov_b32_e32 v122, v2
	v_mov_b32_e32 v123, v2
	v_mov_b32_e32 v124, v2
	v_mov_b32_e32 v125, v2
	v_mov_b32_e32 v126, v2
	v_mov_b32_e32 v127, v2
	v_mov_b32_e32 v128, v2
	v_mov_b32_e32 v129, v2
	s_cmp_eq_u32 s100, 1
	s_cbranch_scc0 .Ldefbar_skip_4
	s_mov_b32 s100, 0
	s_barrier
.Ldefbar_skip_4:
.LBB0_2357:
	s_add_i32 s77, s8, 2
	s_add_u32 s0, s62, 0xfff80080
	s_addc_u32 s1, s63, -1
	s_add_i32 s78, 0, 0x10000
	s_cmp_eq_u32 s71, s8
	s_cselect_b32 s65, s41, s1
	s_cselect_b32 s64, s45, s0
	s_cselect_b32 s9, s43, s73
	s_cselect_b32 s8, s70, s72
	s_add_i32 s79, 0, 0x14000
	v_add_u32_e32 v142, s78, v188
	v_add_u32_e32 v158, s79, v188
	ds_read_b128 v[130:133], v142
	ds_read_b128 v[134:137], v142 offset:1024
	ds_read_b128 v[138:141], v142 offset:2048
	ds_read_b128 v[142:145], v142 offset:3072
	ds_read_b128 v[146:149], v158
	ds_read_b128 v[150:153], v158 offset:1024
	ds_read_b128 v[154:157], v158 offset:2048
	ds_read_b128 v[158:161], v158 offset:3072
	v_lshl_add_u64 v[194:195], s[62:63], 0, v[178:179]
	s_add_i32 m0, s27, 0xc000
	ds_read_b128 v[162:165], v189
	ds_read_b128 v[180:183], v189 offset:1024
	ds_read_b128 v[184:187], v189 offset:2048
	ds_read_b128 v[190:193], v189 offset:3072
	ds_read_b128 v[202:205], v189 offset:4096
	ds_read_b128 v[206:209], v189 offset:5120
	ds_read_b128 v[210:213], v189 offset:6144
	ds_read_b128 v[214:217], v189 offset:7168
	global_load_lds_dwordx4 v[194:195], off
	v_lshl_add_u64 v[194:195], s[62:63], 0, v[176:177]
	s_add_i32 m0, s27, 0xe000
	s_nop 0
	global_load_lds_dwordx4 v[194:195], off
	s_waitcnt vmcnt(8)
	s_waitcnt lgkmcnt(0)
	s_setprio 1
	s_barrier
	v_mfma_f32_16x16x32_bf16 v[126:129], v[130:133], v[162:165], v[126:129]
	v_mfma_f32_16x16x32_bf16 v[122:125], v[138:141], v[162:165], v[122:125]
	v_mfma_f32_16x16x32_bf16 v[110:113], v[130:133], v[184:187], v[110:113]
	v_mfma_f32_16x16x32_bf16 v[106:109], v[138:141], v[184:187], v[106:109]
	v_mfma_f32_16x16x32_bf16 v[98:101], v[130:133], v[202:205], v[98:101]
	v_mfma_f32_16x16x32_bf16 v[90:93], v[138:141], v[202:205], v[90:93]
	v_mfma_f32_16x16x32_bf16 v[82:85], v[130:133], v[210:213], v[82:85]
	v_mfma_f32_16x16x32_bf16 v[74:77], v[138:141], v[210:213], v[74:77]
	v_mfma_f32_16x16x32_bf16 v[126:129], v[134:137], v[180:183], v[126:129]
	v_mfma_f32_16x16x32_bf16 v[122:125], v[142:145], v[180:183], v[122:125]
	v_mfma_f32_16x16x32_bf16 v[110:113], v[134:137], v[190:193], v[110:113]
	v_mfma_f32_16x16x32_bf16 v[106:109], v[142:145], v[190:193], v[106:109]
	v_mfma_f32_16x16x32_bf16 v[98:101], v[134:137], v[206:209], v[98:101]
	v_mfma_f32_16x16x32_bf16 v[90:93], v[142:145], v[206:209], v[90:93]
	v_mfma_f32_16x16x32_bf16 v[82:85], v[134:137], v[214:217], v[82:85]
	v_mfma_f32_16x16x32_bf16 v[74:77], v[142:145], v[214:217], v[74:77]
	v_mfma_f32_16x16x32_bf16 v[118:121], v[146:149], v[162:165], v[118:121]
	v_mfma_f32_16x16x32_bf16 v[114:117], v[154:157], v[162:165], v[114:117]
	v_mfma_f32_16x16x32_bf16 v[102:105], v[146:149], v[184:187], v[102:105]
	v_mfma_f32_16x16x32_bf16 v[94:97], v[154:157], v[184:187], v[94:97]
	v_mfma_f32_16x16x32_bf16 v[86:89], v[146:149], v[202:205], v[86:89]
	v_mfma_f32_16x16x32_bf16 v[78:81], v[154:157], v[202:205], v[78:81]
	v_mfma_f32_16x16x32_bf16 v[70:73], v[146:149], v[210:213], v[70:73]
	v_mfma_f32_16x16x32_bf16 v[66:69], v[154:157], v[210:213], v[66:69]
	v_mfma_f32_16x16x32_bf16 v[118:121], v[150:153], v[180:183], v[118:121]
	v_mfma_f32_16x16x32_bf16 v[114:117], v[158:161], v[180:183], v[114:117]
	v_mfma_f32_16x16x32_bf16 v[102:105], v[150:153], v[190:193], v[102:105]
	v_mfma_f32_16x16x32_bf16 v[94:97], v[158:161], v[190:193], v[94:97]
	v_mfma_f32_16x16x32_bf16 v[86:89], v[150:153], v[206:209], v[86:89]
	v_mfma_f32_16x16x32_bf16 v[78:81], v[158:161], v[206:209], v[78:81]
	v_mfma_f32_16x16x32_bf16 v[70:73], v[150:153], v[214:217], v[70:73]
	v_mfma_f32_16x16x32_bf16 v[66:69], v[158:161], v[214:217], v[66:69]
	s_barrier
	s_setprio 0
	s_add_i32 s0, s78, s26
	v_lshl_add_u64 v[194:195], s[8:9], 0, v[196:197]
	s_mov_b32 m0, s0
	ds_read_b128 v[162:165], v189 offset:16384
	ds_read_b128 v[180:183], v189 offset:17408
	ds_read_b128 v[184:187], v189 offset:18432
	ds_read_b128 v[190:193], v189 offset:19456
	ds_read_b128 v[202:205], v189 offset:20480
	ds_read_b128 v[206:209], v189 offset:21504
	ds_read_b128 v[210:213], v189 offset:22528
	ds_read_b128 v[214:217], v189 offset:23552
	global_load_lds_dwordx4 v[194:195], off
	s_add_i32 m0, s0, 0x2000
	s_add_u32 s0, s8, 0x80000
	v_lshl_add_u64 v[218:219], s[8:9], 0, v[170:171]
	s_addc_u32 s1, s9, 0
	s_add_i32 s78, s79, s26
	global_load_lds_dwordx4 v[218:219], off
	v_lshl_add_u64 v[220:221], s[0:1], 0, v[196:197]
	s_mov_b32 m0, s78
	v_lshl_add_u64 v[222:223], s[64:65], 0, v[168:169]
	global_load_lds_dwordx4 v[220:221], off
	v_lshl_add_u64 v[220:221], s[0:1], 0, v[170:171]
	s_add_i32 m0, s78, 0x2000
	s_nop 0
	global_load_lds_dwordx4 v[220:221], off
	v_lshl_add_u64 v[220:221], s[64:65], 0, v[166:167]
	s_mov_b32 m0, s27
	s_nop 0
	global_load_lds_dwordx4 v[220:221], off
	s_mov_b32 m0, s28
	s_nop 0
	global_load_lds_dwordx4 v[222:223], off
	s_waitcnt vmcnt(8)
	s_waitcnt lgkmcnt(0)
	s_setprio 1
	s_barrier
	v_mfma_f32_16x16x32_bf16 v[62:65], v[130:133], v[162:165], v[62:65]
	v_mfma_f32_16x16x32_bf16 v[58:61], v[138:141], v[162:165], v[58:61]
	v_mfma_f32_16x16x32_bf16 v[50:53], v[130:133], v[184:187], v[50:53]
	v_mfma_f32_16x16x32_bf16 v[42:45], v[138:141], v[184:187], v[42:45]
	v_mfma_f32_16x16x32_bf16 v[34:37], v[130:133], v[202:205], v[34:37]
	v_mfma_f32_16x16x32_bf16 v[26:29], v[138:141], v[202:205], v[26:29]
	v_mfma_f32_16x16x32_bf16 v[18:21], v[130:133], v[210:213], v[18:21]
	v_mfma_f32_16x16x32_bf16 v[10:13], v[138:141], v[210:213], v[10:13]
	v_mfma_f32_16x16x32_bf16 v[62:65], v[134:137], v[180:183], v[62:65]
	v_mfma_f32_16x16x32_bf16 v[58:61], v[142:145], v[180:183], v[58:61]
	v_mfma_f32_16x16x32_bf16 v[50:53], v[134:137], v[190:193], v[50:53]
	v_mfma_f32_16x16x32_bf16 v[42:45], v[142:145], v[190:193], v[42:45]
	v_mfma_f32_16x16x32_bf16 v[34:37], v[134:137], v[206:209], v[34:37]
	v_mfma_f32_16x16x32_bf16 v[26:29], v[142:145], v[206:209], v[26:29]
	v_mfma_f32_16x16x32_bf16 v[18:21], v[134:137], v[214:217], v[18:21]
	v_mfma_f32_16x16x32_bf16 v[10:13], v[142:145], v[214:217], v[10:13]
	v_mfma_f32_16x16x32_bf16 v[54:57], v[146:149], v[162:165], v[54:57]
	v_mfma_f32_16x16x32_bf16 v[46:49], v[154:157], v[162:165], v[46:49]
	v_mfma_f32_16x16x32_bf16 v[38:41], v[146:149], v[184:187], v[38:41]
	v_mfma_f32_16x16x32_bf16 v[30:33], v[154:157], v[184:187], v[30:33]
	v_mfma_f32_16x16x32_bf16 v[22:25], v[146:149], v[202:205], v[22:25]
	v_mfma_f32_16x16x32_bf16 v[14:17], v[154:157], v[202:205], v[14:17]
	v_mfma_f32_16x16x32_bf16 v[6:9], v[146:149], v[210:213], v[6:9]
	v_mfma_f32_16x16x32_bf16 v[2:5], v[154:157], v[210:213], v[2:5]
	v_mfma_f32_16x16x32_bf16 v[54:57], v[150:153], v[180:183], v[54:57]
	v_mfma_f32_16x16x32_bf16 v[46:49], v[158:161], v[180:183], v[46:49]
	v_mfma_f32_16x16x32_bf16 v[38:41], v[150:153], v[190:193], v[38:41]
	v_mfma_f32_16x16x32_bf16 v[30:33], v[158:161], v[190:193], v[30:33]
	v_mfma_f32_16x16x32_bf16 v[22:25], v[150:153], v[206:209], v[22:25]
	v_mfma_f32_16x16x32_bf16 v[14:17], v[158:161], v[206:209], v[14:17]
	v_mfma_f32_16x16x32_bf16 v[6:9], v[150:153], v[214:217], v[6:9]
	v_mfma_f32_16x16x32_bf16 v[2:5], v[158:161], v[214:217], v[2:5]
	s_barrier
	s_setprio 0
	s_add_i32 s78, 0, 0x18000
	s_add_i32 s79, 0, 0x1c000
	v_add_u32_e32 v142, s78, v188
	v_add_u32_e32 v158, s79, v188
	ds_read_b128 v[130:133], v142
	ds_read_b128 v[134:137], v142 offset:1024
	ds_read_b128 v[138:141], v142 offset:2048
	ds_read_b128 v[142:145], v142 offset:3072
	ds_read_b128 v[146:149], v158
	ds_read_b128 v[150:153], v158 offset:1024
	ds_read_b128 v[154:157], v158 offset:2048
	ds_read_b128 v[158:161], v158 offset:3072
	s_add_u32 s0, s64, 0x80000
	s_addc_u32 s1, s65, 0
	s_mov_b32 m0, s29
	v_lshl_add_u64 v[224:225], s[0:1], 0, v[166:167]
	ds_read_b128 v[162:165], v189 offset:32768
	ds_read_b128 v[180:183], v189 offset:33792
	ds_read_b128 v[184:187], v189 offset:34816
	ds_read_b128 v[190:193], v189 offset:35840
	ds_read_b128 v[202:205], v189 offset:36864
	ds_read_b128 v[206:209], v189 offset:37888
	ds_read_b128 v[210:213], v189 offset:38912
	ds_read_b128 v[214:217], v189 offset:39936
	global_load_lds_dwordx4 v[224:225], off
	v_lshl_add_u64 v[224:225], s[0:1], 0, v[168:169]
	s_mov_b32 m0, s30
	s_nop 0
	global_load_lds_dwordx4 v[224:225], off
	s_waitcnt vmcnt(8)
	s_waitcnt lgkmcnt(0)
	s_setprio 1
	s_barrier
	v_mfma_f32_16x16x32_bf16 v[126:129], v[130:133], v[162:165], v[126:129]
	v_mfma_f32_16x16x32_bf16 v[122:125], v[138:141], v[162:165], v[122:125]
	v_mfma_f32_16x16x32_bf16 v[110:113], v[130:133], v[184:187], v[110:113]
	v_mfma_f32_16x16x32_bf16 v[106:109], v[138:141], v[184:187], v[106:109]
	v_mfma_f32_16x16x32_bf16 v[98:101], v[130:133], v[202:205], v[98:101]
	v_mfma_f32_16x16x32_bf16 v[90:93], v[138:141], v[202:205], v[90:93]
	v_mfma_f32_16x16x32_bf16 v[82:85], v[130:133], v[210:213], v[82:85]
	v_mfma_f32_16x16x32_bf16 v[74:77], v[138:141], v[210:213], v[74:77]
	v_mfma_f32_16x16x32_bf16 v[126:129], v[134:137], v[180:183], v[126:129]
	v_mfma_f32_16x16x32_bf16 v[122:125], v[142:145], v[180:183], v[122:125]
	v_mfma_f32_16x16x32_bf16 v[110:113], v[134:137], v[190:193], v[110:113]
	v_mfma_f32_16x16x32_bf16 v[106:109], v[142:145], v[190:193], v[106:109]
	v_mfma_f32_16x16x32_bf16 v[98:101], v[134:137], v[206:209], v[98:101]
	v_mfma_f32_16x16x32_bf16 v[90:93], v[142:145], v[206:209], v[90:93]
	v_mfma_f32_16x16x32_bf16 v[82:85], v[134:137], v[214:217], v[82:85]
	v_mfma_f32_16x16x32_bf16 v[74:77], v[142:145], v[214:217], v[74:77]
	v_mfma_f32_16x16x32_bf16 v[118:121], v[146:149], v[162:165], v[118:121]
	v_mfma_f32_16x16x32_bf16 v[114:117], v[154:157], v[162:165], v[114:117]
	v_mfma_f32_16x16x32_bf16 v[102:105], v[146:149], v[184:187], v[102:105]
	v_mfma_f32_16x16x32_bf16 v[94:97], v[154:157], v[184:187], v[94:97]
	v_mfma_f32_16x16x32_bf16 v[86:89], v[146:149], v[202:205], v[86:89]
	v_mfma_f32_16x16x32_bf16 v[78:81], v[154:157], v[202:205], v[78:81]
	v_mfma_f32_16x16x32_bf16 v[70:73], v[146:149], v[210:213], v[70:73]
	v_mfma_f32_16x16x32_bf16 v[66:69], v[154:157], v[210:213], v[66:69]
	v_mfma_f32_16x16x32_bf16 v[118:121], v[150:153], v[180:183], v[118:121]
	v_mfma_f32_16x16x32_bf16 v[114:117], v[158:161], v[180:183], v[114:117]
	v_mfma_f32_16x16x32_bf16 v[102:105], v[150:153], v[190:193], v[102:105]
	v_mfma_f32_16x16x32_bf16 v[94:97], v[158:161], v[190:193], v[94:97]
	v_mfma_f32_16x16x32_bf16 v[86:89], v[150:153], v[206:209], v[86:89]
	v_mfma_f32_16x16x32_bf16 v[78:81], v[158:161], v[206:209], v[78:81]
	v_mfma_f32_16x16x32_bf16 v[70:73], v[150:153], v[214:217], v[70:73]
	v_mfma_f32_16x16x32_bf16 v[66:69], v[158:161], v[214:217], v[66:69]
	s_barrier
	s_setprio 0
	s_add_i32 s0, s78, s26
	v_lshl_add_u64 v[194:195], v[194:195], 0, s[16:17]
	s_mov_b32 m0, s0
	ds_read_b128 v[162:165], v189 offset:49152
	ds_read_b128 v[180:183], v189 offset:50176
	ds_read_b128 v[184:187], v189 offset:51200
	ds_read_b128 v[190:193], v189 offset:52224
	ds_read_b128 v[202:205], v189 offset:53248
	ds_read_b128 v[206:209], v189 offset:54272
	ds_read_b128 v[210:213], v189 offset:55296
	ds_read_b128 v[214:217], v189 offset:56320
	global_load_lds_dwordx4 v[194:195], off
	s_add_i32 m0, s0, 0x2000
	s_add_u32 s0, s8, 0x80080
	v_lshl_add_u64 v[194:195], v[218:219], 0, s[16:17]
	s_addc_u32 s1, s9, 0
	s_add_i32 s8, s79, s26
	global_load_lds_dwordx4 v[194:195], off
	v_lshl_add_u64 v[194:195], s[0:1], 0, v[196:197]
	s_mov_b32 m0, s8
	s_nop 0
	global_load_lds_dwordx4 v[194:195], off
	v_lshl_add_u64 v[194:195], s[0:1], 0, v[170:171]
	s_add_i32 m0, s8, 0x2000
	s_nop 0
	global_load_lds_dwordx4 v[194:195], off
	v_lshl_add_u64 v[194:195], v[220:221], 0, s[16:17]
	s_mov_b32 m0, s35
	s_nop 0
	global_load_lds_dwordx4 v[194:195], off
	v_lshl_add_u64 v[194:195], v[222:223], 0, s[16:17]
	s_mov_b32 m0, s53
	s_nop 0
	global_load_lds_dwordx4 v[194:195], off
	s_waitcnt vmcnt(8)
	s_waitcnt lgkmcnt(0)
	s_setprio 1
	s_barrier
	v_mfma_f32_16x16x32_bf16 v[62:65], v[130:133], v[162:165], v[62:65]
	v_mfma_f32_16x16x32_bf16 v[58:61], v[138:141], v[162:165], v[58:61]
	v_mfma_f32_16x16x32_bf16 v[50:53], v[130:133], v[184:187], v[50:53]
	v_mfma_f32_16x16x32_bf16 v[42:45], v[138:141], v[184:187], v[42:45]
	v_mfma_f32_16x16x32_bf16 v[34:37], v[130:133], v[202:205], v[34:37]
	v_mfma_f32_16x16x32_bf16 v[26:29], v[138:141], v[202:205], v[26:29]
	v_mfma_f32_16x16x32_bf16 v[18:21], v[130:133], v[210:213], v[18:21]
	v_mfma_f32_16x16x32_bf16 v[10:13], v[138:141], v[210:213], v[10:13]
	v_mfma_f32_16x16x32_bf16 v[62:65], v[134:137], v[180:183], v[62:65]
	v_mfma_f32_16x16x32_bf16 v[58:61], v[142:145], v[180:183], v[58:61]
	v_mfma_f32_16x16x32_bf16 v[50:53], v[134:137], v[190:193], v[50:53]
	v_mfma_f32_16x16x32_bf16 v[42:45], v[142:145], v[190:193], v[42:45]
	v_mfma_f32_16x16x32_bf16 v[34:37], v[134:137], v[206:209], v[34:37]
	v_mfma_f32_16x16x32_bf16 v[26:29], v[142:145], v[206:209], v[26:29]
	v_mfma_f32_16x16x32_bf16 v[18:21], v[134:137], v[214:217], v[18:21]
	v_mfma_f32_16x16x32_bf16 v[10:13], v[142:145], v[214:217], v[10:13]
	v_mfma_f32_16x16x32_bf16 v[54:57], v[146:149], v[162:165], v[54:57]
	v_mfma_f32_16x16x32_bf16 v[46:49], v[154:157], v[162:165], v[46:49]
	v_mfma_f32_16x16x32_bf16 v[38:41], v[146:149], v[184:187], v[38:41]
	v_mfma_f32_16x16x32_bf16 v[30:33], v[154:157], v[184:187], v[30:33]
	v_mfma_f32_16x16x32_bf16 v[22:25], v[146:149], v[202:205], v[22:25]
	v_mfma_f32_16x16x32_bf16 v[14:17], v[154:157], v[202:205], v[14:17]
	v_mfma_f32_16x16x32_bf16 v[6:9], v[146:149], v[210:213], v[6:9]
	v_mfma_f32_16x16x32_bf16 v[2:5], v[154:157], v[210:213], v[2:5]
	v_mfma_f32_16x16x32_bf16 v[54:57], v[150:153], v[180:183], v[54:57]
	v_mfma_f32_16x16x32_bf16 v[46:49], v[158:161], v[180:183], v[46:49]
	v_mfma_f32_16x16x32_bf16 v[38:41], v[150:153], v[190:193], v[38:41]
	v_mfma_f32_16x16x32_bf16 v[30:33], v[158:161], v[190:193], v[30:33]
	v_mfma_f32_16x16x32_bf16 v[22:25], v[150:153], v[206:209], v[22:25]
	v_mfma_f32_16x16x32_bf16 v[14:17], v[158:161], v[206:209], v[14:17]
	v_mfma_f32_16x16x32_bf16 v[6:9], v[150:153], v[214:217], v[6:9]
	v_mfma_f32_16x16x32_bf16 v[2:5], v[158:161], v[214:217], v[2:5]
	s_barrier
	s_setprio 0
	s_add_u32 s72, s72, 0x100
	s_addc_u32 s73, s73, 0
	s_add_u32 s62, s62, 0x100
	s_addc_u32 s63, s63, 0
	s_cmp_ge_i32 s77, s69
	s_mov_b32 s8, s77
	s_cbranch_scc0 .LBB0_2357
	s_and_b64 vcc, exec, s[38:39]
	s_cbranch_vccz .LBB0_2360
	s_barrier

.LBB0_2363:
	s_andn2_b64 vcc, exec, s[46:47]
	s_mov_b64 s[8:9], -1
	s_cbranch_vccnz .LBB0_2346
	s_andn2_b64 vcc, exec, s[4:5]
	s_cbranch_vccnz .LBB0_2345
	s_mov_b32 s100, 1
	s_branch .LBB0_2345

.LBB0_2506:
	s_ashr_i32 s45, s44, 31
	s_lshl_b64 s[0:1], s[44:45], 20
	s_add_u32 s43, s2, s0
	s_addc_u32 s45, s3, s1
	s_ashr_i32 s41, s40, 31
	s_lshl_b64 s[0:1], s[40:41], 1
	s_add_u32 s48, s43, s0
	s_addc_u32 s49, s45, s1
	s_and_b64 s[50:51], s[46:47], exec
	s_cselect_b32 s41, s49, s9
	s_cselect_b32 s45, s48, s8
	s_ashr_i32 s43, s42, 31
	s_lshl_b64 s[50:51], s[42:43], 20
	s_add_u32 s43, s10, s50
	s_addc_u32 s51, s11, s51
	s_add_u32 s50, s43, s0
	s_addc_u32 s51, s51, s1
	s_and_b64 s[0:1], s[46:47], exec
	s_cselect_b32 s43, s51, s53
	s_cselect_b32 s65, s50, s52
	s_add_i32 s66, s62, -2
	s_add_u32 s67, s52, 0x100
	s_addc_u32 s68, s53, 0
	s_add_u32 s52, s8, 0x80080
	v_mov_b32_e32 v2, 0
	s_addc_u32 s53, s9, 0
	s_mov_b32 s8, 0
	v_mov_b32_e32 v3, v2
	v_mov_b32_e32 v4, v2
	v_mov_b32_e32 v5, v2
	v_mov_b32_e32 v10, v2
	v_mov_b32_e32 v11, v2
	v_mov_b32_e32 v12, v2
	v_mov_b32_e32 v13, v2
	v_mov_b32_e32 v18, v2
	v_mov_b32_e32 v19, v2
	v_mov_b32_e32 v20, v2
	v_mov_b32_e32 v21, v2
	v_mov_b32_e32 v26, v2
	v_mov_b32_e32 v27, v2
	v_mov_b32_e32 v28, v2
	v_mov_b32_e32 v29, v2
	v_mov_b32_e32 v34, v2
	v_mov_b32_e32 v35, v2
	v_mov_b32_e32 v36, v2
	v_mov_b32_e32 v37, v2
	v_mov_b32_e32 v42, v2
	v_mov_b32_e32 v43, v2
	v_mov_b32_e32 v44, v2
	v_mov_b32_e32 v45, v2
	v_mov_b32_e32 v50, v2
	v_mov_b32_e32 v51, v2
	v_mov_b32_e32 v52, v2
	v_mov_b32_e32 v53, v2
	v_mov_b32_e32 v58, v2
	v_mov_b32_e32 v59, v2
	v_mov_b32_e32 v60, v2
	v_mov_b32_e32 v61, v2
	v_mov_b32_e32 v6, v2
	v_mov_b32_e32 v7, v2
	v_mov_b32_e32 v8, v2
	v_mov_b32_e32 v9, v2
	v_mov_b32_e32 v14, v2
	v_mov_b32_e32 v15, v2
	v_mov_b32_e32 v16, v2
	v_mov_b32_e32 v17, v2
	v_mov_b32_e32 v22, v2
	v_mov_b32_e32 v23, v2
	v_mov_b32_e32 v24, v2
	v_mov_b32_e32 v25, v2
	v_mov_b32_e32 v30, v2
	v_mov_b32_e32 v31, v2
	v_mov_b32_e32 v32, v2
	v_mov_b32_e32 v33, v2
	v_mov_b32_e32 v38, v2
	v_mov_b32_e32 v39, v2
	v_mov_b32_e32 v40, v2
	v_mov_b32_e32 v41, v2
	v_mov_b32_e32 v46, v2
	v_mov_b32_e32 v47, v2
	v_mov_b32_e32 v48, v2
	v_mov_b32_e32 v49, v2
	v_mov_b32_e32 v54, v2
	v_mov_b32_e32 v55, v2
	v_mov_b32_e32 v56, v2
	v_mov_b32_e32 v57, v2
	v_mov_b32_e32 v62, v2
	v_mov_b32_e32 v63, v2
	v_mov_b32_e32 v64, v2
	v_mov_b32_e32 v65, v2
	v_mov_b32_e32 v66, v2
	v_mov_b32_e32 v67, v2
	v_mov_b32_e32 v68, v2
	v_mov_b32_e32 v69, v2
	v_mov_b32_e32 v74, v2
	v_mov_b32_e32 v75, v2
	v_mov_b32_e32 v76, v2
	v_mov_b32_e32 v77, v2
	v_mov_b32_e32 v82, v2
	v_mov_b32_e32 v83, v2
	v_mov_b32_e32 v84, v2
	v_mov_b32_e32 v85, v2
	v_mov_b32_e32 v90, v2
	v_mov_b32_e32 v91, v2
	v_mov_b32_e32 v92, v2
	v_mov_b32_e32 v93, v2
	v_mov_b32_e32 v98, v2
	v_mov_b32_e32 v99, v2
	v_mov_b32_e32 v100, v2
	v_mov_b32_e32 v101, v2
	v_mov_b32_e32 v106, v2
	v_mov_b32_e32 v107, v2
	v_mov_b32_e32 v108, v2
	v_mov_b32_e32 v109, v2
	v_mov_b32_e32 v114, v2
	v_mov_b32_e32 v115, v2
	v_mov_b32_e32 v116, v2
	v_mov_b32_e32 v117, v2
	v_mov_b32_e32 v122, v2
	v_mov_b32_e32 v123, v2
	v_mov_b32_e32 v124, v2
	v_mov_b32_e32 v125, v2
	v_mov_b32_e32 v70, v2
	v_mov_b32_e32 v71, v2
	v_mov_b32_e32 v72, v2
	v_mov_b32_e32 v73, v2
	v_mov_b32_e32 v78, v2
	v_mov_b32_e32 v79, v2
	v_mov_b32_e32 v80, v2
	v_mov_b32_e32 v81, v2
	v_mov_b32_e32 v86, v2
	v_mov_b32_e32 v87, v2
	v_mov_b32_e32 v88, v2
	v_mov_b32_e32 v89, v2
	v_mov_b32_e32 v94, v2
	v_mov_b32_e32 v95, v2
	v_mov_b32_e32 v96, v2
	v_mov_b32_e32 v97, v2
	v_mov_b32_e32 v102, v2
	v_mov_b32_e32 v103, v2
	v_mov_b32_e32 v104, v2
	v_mov_b32_e32 v105, v2
	v_mov_b32_e32 v110, v2
	v_mov_b32_e32 v111, v2
	v_mov_b32_e32 v112, v2
	v_mov_b32_e32 v113, v2
	v_mov_b32_e32 v118, v2
	v_mov_b32_e32 v119, v2
	v_mov_b32_e32 v120, v2
	v_mov_b32_e32 v121, v2
	v_mov_b32_e32 v126, v2
	v_mov_b32_e32 v127, v2
	v_mov_b32_e32 v128, v2
	v_mov_b32_e32 v129, v2
	s_cmp_eq_u32 s100, 1
	s_cbranch_scc0 .Ldefbar_skip_5
	s_mov_b32 s100, 0
	s_barrier
.Ldefbar_skip_5:
.LBB0_2507:
	s_add_i32 s69, s8, 2
	s_add_u32 s0, s52, 0xfff80080
	s_addc_u32 s1, s53, -1
	s_add_i32 s70, 0, 0x10000
	s_cmp_eq_u32 s66, s8
	s_cselect_b32 s59, s41, s1
	s_cselect_b32 s58, s45, s0
	s_cselect_b32 s9, s43, s68
	s_cselect_b32 s8, s65, s67
	s_add_i32 s71, 0, 0x14000
	v_add_u32_e32 v156, s70, v141
	v_add_u32_e32 v172, s71, v141
	ds_read_b128 v[144:147], v156
	ds_read_b128 v[148:151], v156 offset:1024
	ds_read_b128 v[152:155], v156 offset:2048
	ds_read_b128 v[156:159], v156 offset:3072
	ds_read_b128 v[160:163], v172
	ds_read_b128 v[164:167], v172 offset:1024
	ds_read_b128 v[168:171], v172 offset:2048
	ds_read_b128 v[172:175], v172 offset:3072
	v_lshl_add_u64 v[214:215], s[52:53], 0, v[138:139]
	s_add_i32 m0, s27, 0xc000
	ds_read_b128 v[176:179], v143
	ds_read_b128 v[180:183], v143 offset:1024
	ds_read_b128 v[184:187], v143 offset:2048
	ds_read_b128 v[188:191], v143 offset:3072
	ds_read_b128 v[192:195], v143 offset:4096
	ds_read_b128 v[202:205], v143 offset:5120
	ds_read_b128 v[206:209], v143 offset:6144
	ds_read_b128 v[210:213], v143 offset:7168
	global_load_lds_dwordx4 v[214:215], off
	v_lshl_add_u64 v[214:215], s[52:53], 0, v[136:137]
	s_add_i32 m0, s27, 0xe000
	s_nop 0
	global_load_lds_dwordx4 v[214:215], off
	s_waitcnt vmcnt(8)
	s_waitcnt lgkmcnt(0)
	s_setprio 1
	s_barrier
	v_mfma_f32_16x16x32_bf16 v[126:129], v[144:147], v[176:179], v[126:129]
	v_mfma_f32_16x16x32_bf16 v[118:121], v[152:155], v[176:179], v[118:121]
	v_mfma_f32_16x16x32_bf16 v[110:113], v[144:147], v[184:187], v[110:113]
	v_mfma_f32_16x16x32_bf16 v[102:105], v[152:155], v[184:187], v[102:105]
	v_mfma_f32_16x16x32_bf16 v[94:97], v[144:147], v[192:195], v[94:97]
	v_mfma_f32_16x16x32_bf16 v[86:89], v[152:155], v[192:195], v[86:89]
	v_mfma_f32_16x16x32_bf16 v[78:81], v[144:147], v[206:209], v[78:81]
	v_mfma_f32_16x16x32_bf16 v[70:73], v[152:155], v[206:209], v[70:73]
	v_mfma_f32_16x16x32_bf16 v[126:129], v[148:151], v[180:183], v[126:129]
	v_mfma_f32_16x16x32_bf16 v[118:121], v[156:159], v[180:183], v[118:121]
	v_mfma_f32_16x16x32_bf16 v[110:113], v[148:151], v[188:191], v[110:113]
	v_mfma_f32_16x16x32_bf16 v[102:105], v[156:159], v[188:191], v[102:105]
	v_mfma_f32_16x16x32_bf16 v[94:97], v[148:151], v[202:205], v[94:97]
	v_mfma_f32_16x16x32_bf16 v[86:89], v[156:159], v[202:205], v[86:89]
	v_mfma_f32_16x16x32_bf16 v[78:81], v[148:151], v[210:213], v[78:81]
	v_mfma_f32_16x16x32_bf16 v[70:73], v[156:159], v[210:213], v[70:73]
	v_mfma_f32_16x16x32_bf16 v[122:125], v[160:163], v[176:179], v[122:125]
	v_mfma_f32_16x16x32_bf16 v[114:117], v[168:171], v[176:179], v[114:117]
	v_mfma_f32_16x16x32_bf16 v[106:109], v[160:163], v[184:187], v[106:109]
	v_mfma_f32_16x16x32_bf16 v[98:101], v[168:171], v[184:187], v[98:101]
	v_mfma_f32_16x16x32_bf16 v[90:93], v[160:163], v[192:195], v[90:93]
	v_mfma_f32_16x16x32_bf16 v[82:85], v[168:171], v[192:195], v[82:85]
	v_mfma_f32_16x16x32_bf16 v[74:77], v[160:163], v[206:209], v[74:77]
	v_mfma_f32_16x16x32_bf16 v[66:69], v[168:171], v[206:209], v[66:69]
	v_mfma_f32_16x16x32_bf16 v[122:125], v[164:167], v[180:183], v[122:125]
	v_mfma_f32_16x16x32_bf16 v[114:117], v[172:175], v[180:183], v[114:117]
	v_mfma_f32_16x16x32_bf16 v[106:109], v[164:167], v[188:191], v[106:109]
	v_mfma_f32_16x16x32_bf16 v[98:101], v[172:175], v[188:191], v[98:101]
	v_mfma_f32_16x16x32_bf16 v[90:93], v[164:167], v[202:205], v[90:93]
	v_mfma_f32_16x16x32_bf16 v[82:85], v[172:175], v[202:205], v[82:85]
	v_mfma_f32_16x16x32_bf16 v[74:77], v[164:167], v[210:213], v[74:77]
	v_mfma_f32_16x16x32_bf16 v[66:69], v[172:175], v[210:213], v[66:69]
	s_barrier
	s_setprio 0
	s_add_i32 s0, s70, s26
	v_lshl_add_u64 v[214:215], s[8:9], 0, v[196:197]
	s_mov_b32 m0, s0
	ds_read_b128 v[176:179], v143 offset:16384
	ds_read_b128 v[180:183], v143 offset:17408
	ds_read_b128 v[184:187], v143 offset:18432
	ds_read_b128 v[188:191], v143 offset:19456
	ds_read_b128 v[192:195], v143 offset:20480
	ds_read_b128 v[202:205], v143 offset:21504
	ds_read_b128 v[206:209], v143 offset:22528
	ds_read_b128 v[210:213], v143 offset:23552
	global_load_lds_dwordx4 v[214:215], off
	s_add_i32 m0, s0, 0x2000
	s_add_u32 s0, s8, 0x80000
	v_lshl_add_u64 v[216:217], s[8:9], 0, v[130:131]
	s_addc_u32 s1, s9, 0
	s_add_i32 s70, s71, s26
	global_load_lds_dwordx4 v[216:217], off
	v_lshl_add_u64 v[218:219], s[0:1], 0, v[196:197]
	s_mov_b32 m0, s70
	v_lshl_add_u64 v[220:221], s[58:59], 0, v[132:133]
	global_load_lds_dwordx4 v[218:219], off
	v_lshl_add_u64 v[218:219], s[0:1], 0, v[130:131]
	s_add_i32 m0, s70, 0x2000
	s_nop 0
	global_load_lds_dwordx4 v[218:219], off
	v_lshl_add_u64 v[218:219], s[58:59], 0, v[134:135]
	s_mov_b32 m0, s27
	s_nop 0
	global_load_lds_dwordx4 v[218:219], off
	s_mov_b32 m0, s28
	s_nop 0
	global_load_lds_dwordx4 v[220:221], off
	s_waitcnt vmcnt(8)
	s_waitcnt lgkmcnt(0)
	s_setprio 1
	s_barrier
	v_mfma_f32_16x16x32_bf16 v[62:65], v[144:147], v[176:179], v[62:65]
	v_mfma_f32_16x16x32_bf16 v[54:57], v[152:155], v[176:179], v[54:57]
	v_mfma_f32_16x16x32_bf16 v[46:49], v[144:147], v[184:187], v[46:49]
	v_mfma_f32_16x16x32_bf16 v[38:41], v[152:155], v[184:187], v[38:41]
	v_mfma_f32_16x16x32_bf16 v[30:33], v[144:147], v[192:195], v[30:33]
	v_mfma_f32_16x16x32_bf16 v[22:25], v[152:155], v[192:195], v[22:25]
	v_mfma_f32_16x16x32_bf16 v[14:17], v[144:147], v[206:209], v[14:17]
	v_mfma_f32_16x16x32_bf16 v[6:9], v[152:155], v[206:209], v[6:9]
	v_mfma_f32_16x16x32_bf16 v[62:65], v[148:151], v[180:183], v[62:65]
	v_mfma_f32_16x16x32_bf16 v[54:57], v[156:159], v[180:183], v[54:57]
	v_mfma_f32_16x16x32_bf16 v[46:49], v[148:151], v[188:191], v[46:49]
	v_mfma_f32_16x16x32_bf16 v[38:41], v[156:159], v[188:191], v[38:41]
	v_mfma_f32_16x16x32_bf16 v[30:33], v[148:151], v[202:205], v[30:33]
	v_mfma_f32_16x16x32_bf16 v[22:25], v[156:159], v[202:205], v[22:25]
	v_mfma_f32_16x16x32_bf16 v[14:17], v[148:151], v[210:213], v[14:17]
	v_mfma_f32_16x16x32_bf16 v[6:9], v[156:159], v[210:213], v[6:9]
	v_mfma_f32_16x16x32_bf16 v[58:61], v[160:163], v[176:179], v[58:61]
	v_mfma_f32_16x16x32_bf16 v[50:53], v[168:171], v[176:179], v[50:53]
	v_mfma_f32_16x16x32_bf16 v[42:45], v[160:163], v[184:187], v[42:45]
	v_mfma_f32_16x16x32_bf16 v[34:37], v[168:171], v[184:187], v[34:37]
	v_mfma_f32_16x16x32_bf16 v[26:29], v[160:163], v[192:195], v[26:29]
	v_mfma_f32_16x16x32_bf16 v[18:21], v[168:171], v[192:195], v[18:21]
	v_mfma_f32_16x16x32_bf16 v[10:13], v[160:163], v[206:209], v[10:13]
	v_mfma_f32_16x16x32_bf16 v[2:5], v[168:171], v[206:209], v[2:5]
	v_mfma_f32_16x16x32_bf16 v[58:61], v[164:167], v[180:183], v[58:61]
	v_mfma_f32_16x16x32_bf16 v[50:53], v[172:175], v[180:183], v[50:53]
	v_mfma_f32_16x16x32_bf16 v[42:45], v[164:167], v[188:191], v[42:45]
	v_mfma_f32_16x16x32_bf16 v[34:37], v[172:175], v[188:191], v[34:37]
	v_mfma_f32_16x16x32_bf16 v[26:29], v[164:167], v[202:205], v[26:29]
	v_mfma_f32_16x16x32_bf16 v[18:21], v[172:175], v[202:205], v[18:21]
	v_mfma_f32_16x16x32_bf16 v[10:13], v[164:167], v[210:213], v[10:13]
	v_mfma_f32_16x16x32_bf16 v[2:5], v[172:175], v[210:213], v[2:5]
	s_barrier
	s_setprio 0
	s_add_i32 s70, 0, 0x18000
	s_add_i32 s71, 0, 0x1c000
	v_add_u32_e32 v156, s70, v141
	v_add_u32_e32 v172, s71, v141
	ds_read_b128 v[144:147], v156
	ds_read_b128 v[148:151], v156 offset:1024
	ds_read_b128 v[152:155], v156 offset:2048
	ds_read_b128 v[156:159], v156 offset:3072
	ds_read_b128 v[160:163], v172
	ds_read_b128 v[164:167], v172 offset:1024
	ds_read_b128 v[168:171], v172 offset:2048
	ds_read_b128 v[172:175], v172 offset:3072
	s_add_u32 s0, s58, 0x80000
	s_addc_u32 s1, s59, 0
	s_mov_b32 m0, s29
	v_lshl_add_u64 v[222:223], s[0:1], 0, v[134:135]
	ds_read_b128 v[176:179], v143 offset:32768
	ds_read_b128 v[180:183], v143 offset:33792
	ds_read_b128 v[184:187], v143 offset:34816
	ds_read_b128 v[188:191], v143 offset:35840
	ds_read_b128 v[192:195], v143 offset:36864
	ds_read_b128 v[202:205], v143 offset:37888
	ds_read_b128 v[206:209], v143 offset:38912
	ds_read_b128 v[210:213], v143 offset:39936
	global_load_lds_dwordx4 v[222:223], off
	v_lshl_add_u64 v[222:223], s[0:1], 0, v[132:133]
	s_mov_b32 m0, s30
	s_nop 0
	global_load_lds_dwordx4 v[222:223], off
	s_waitcnt vmcnt(8)
	s_waitcnt lgkmcnt(0)
	s_setprio 1
	s_barrier
	v_mfma_f32_16x16x32_bf16 v[126:129], v[144:147], v[176:179], v[126:129]
	v_mfma_f32_16x16x32_bf16 v[118:121], v[152:155], v[176:179], v[118:121]
	v_mfma_f32_16x16x32_bf16 v[110:113], v[144:147], v[184:187], v[110:113]
	v_mfma_f32_16x16x32_bf16 v[102:105], v[152:155], v[184:187], v[102:105]
	v_mfma_f32_16x16x32_bf16 v[94:97], v[144:147], v[192:195], v[94:97]
	v_mfma_f32_16x16x32_bf16 v[86:89], v[152:155], v[192:195], v[86:89]
	v_mfma_f32_16x16x32_bf16 v[78:81], v[144:147], v[206:209], v[78:81]
	v_mfma_f32_16x16x32_bf16 v[70:73], v[152:155], v[206:209], v[70:73]
	v_mfma_f32_16x16x32_bf16 v[126:129], v[148:151], v[180:183], v[126:129]
	v_mfma_f32_16x16x32_bf16 v[118:121], v[156:159], v[180:183], v[118:121]
	v_mfma_f32_16x16x32_bf16 v[110:113], v[148:151], v[188:191], v[110:113]
	v_mfma_f32_16x16x32_bf16 v[102:105], v[156:159], v[188:191], v[102:105]
	v_mfma_f32_16x16x32_bf16 v[94:97], v[148:151], v[202:205], v[94:97]
	v_mfma_f32_16x16x32_bf16 v[86:89], v[156:159], v[202:205], v[86:89]
	v_mfma_f32_16x16x32_bf16 v[78:81], v[148:151], v[210:213], v[78:81]
	v_mfma_f32_16x16x32_bf16 v[70:73], v[156:159], v[210:213], v[70:73]
	v_mfma_f32_16x16x32_bf16 v[122:125], v[160:163], v[176:179], v[122:125]
	v_mfma_f32_16x16x32_bf16 v[114:117], v[168:171], v[176:179], v[114:117]
	v_mfma_f32_16x16x32_bf16 v[106:109], v[160:163], v[184:187], v[106:109]
	v_mfma_f32_16x16x32_bf16 v[98:101], v[168:171], v[184:187], v[98:101]
	v_mfma_f32_16x16x32_bf16 v[90:93], v[160:163], v[192:195], v[90:93]
	v_mfma_f32_16x16x32_bf16 v[82:85], v[168:171], v[192:195], v[82:85]
	v_mfma_f32_16x16x32_bf16 v[74:77], v[160:163], v[206:209], v[74:77]
	v_mfma_f32_16x16x32_bf16 v[66:69], v[168:171], v[206:209], v[66:69]
	v_mfma_f32_16x16x32_bf16 v[122:125], v[164:167], v[180:183], v[122:125]
	v_mfma_f32_16x16x32_bf16 v[114:117], v[172:175], v[180:183], v[114:117]
	v_mfma_f32_16x16x32_bf16 v[106:109], v[164:167], v[188:191], v[106:109]
	v_mfma_f32_16x16x32_bf16 v[98:101], v[172:175], v[188:191], v[98:101]
	v_mfma_f32_16x16x32_bf16 v[90:93], v[164:167], v[202:205], v[90:93]
	v_mfma_f32_16x16x32_bf16 v[82:85], v[172:175], v[202:205], v[82:85]
	v_mfma_f32_16x16x32_bf16 v[74:77], v[164:167], v[210:213], v[74:77]
	v_mfma_f32_16x16x32_bf16 v[66:69], v[172:175], v[210:213], v[66:69]
	s_barrier
	s_setprio 0
	s_add_i32 s0, s70, s26
	v_lshl_add_u64 v[214:215], v[214:215], 0, s[16:17]
	s_mov_b32 m0, s0
	ds_read_b128 v[176:179], v143 offset:49152
	ds_read_b128 v[180:183], v143 offset:50176
	ds_read_b128 v[184:187], v143 offset:51200
	ds_read_b128 v[188:191], v143 offset:52224
	ds_read_b128 v[192:195], v143 offset:53248
	ds_read_b128 v[202:205], v143 offset:54272
	ds_read_b128 v[206:209], v143 offset:55296
	ds_read_b128 v[210:213], v143 offset:56320
	global_load_lds_dwordx4 v[214:215], off
	s_add_i32 m0, s0, 0x2000
	s_add_u32 s0, s8, 0x80080
	v_lshl_add_u64 v[214:215], v[216:217], 0, s[16:17]
	s_addc_u32 s1, s9, 0
	s_add_i32 s8, s71, s26
	global_load_lds_dwordx4 v[214:215], off
	v_lshl_add_u64 v[214:215], s[0:1], 0, v[196:197]
	s_mov_b32 m0, s8
	s_nop 0
	global_load_lds_dwordx4 v[214:215], off
	v_lshl_add_u64 v[214:215], s[0:1], 0, v[130:131]
	s_add_i32 m0, s8, 0x2000
	s_nop 0
	global_load_lds_dwordx4 v[214:215], off
	v_lshl_add_u64 v[214:215], v[218:219], 0, s[16:17]
	s_mov_b32 m0, s31
	s_nop 0
	global_load_lds_dwordx4 v[214:215], off
	v_lshl_add_u64 v[214:215], v[220:221], 0, s[16:17]
	s_mov_b32 m0, s34
	s_nop 0
	global_load_lds_dwordx4 v[214:215], off
	s_waitcnt vmcnt(8)
	s_waitcnt lgkmcnt(0)
	s_setprio 1
	s_barrier
	v_mfma_f32_16x16x32_bf16 v[62:65], v[144:147], v[176:179], v[62:65]
	v_mfma_f32_16x16x32_bf16 v[54:57], v[152:155], v[176:179], v[54:57]
	v_mfma_f32_16x16x32_bf16 v[46:49], v[144:147], v[184:187], v[46:49]
	v_mfma_f32_16x16x32_bf16 v[38:41], v[152:155], v[184:187], v[38:41]
	v_mfma_f32_16x16x32_bf16 v[30:33], v[144:147], v[192:195], v[30:33]
	v_mfma_f32_16x16x32_bf16 v[22:25], v[152:155], v[192:195], v[22:25]
	v_mfma_f32_16x16x32_bf16 v[14:17], v[144:147], v[206:209], v[14:17]
	v_mfma_f32_16x16x32_bf16 v[6:9], v[152:155], v[206:209], v[6:9]
	v_mfma_f32_16x16x32_bf16 v[62:65], v[148:151], v[180:183], v[62:65]
	v_mfma_f32_16x16x32_bf16 v[54:57], v[156:159], v[180:183], v[54:57]
	v_mfma_f32_16x16x32_bf16 v[46:49], v[148:151], v[188:191], v[46:49]
	v_mfma_f32_16x16x32_bf16 v[38:41], v[156:159], v[188:191], v[38:41]
	v_mfma_f32_16x16x32_bf16 v[30:33], v[148:151], v[202:205], v[30:33]
	v_mfma_f32_16x16x32_bf16 v[22:25], v[156:159], v[202:205], v[22:25]
	v_mfma_f32_16x16x32_bf16 v[14:17], v[148:151], v[210:213], v[14:17]
	v_mfma_f32_16x16x32_bf16 v[6:9], v[156:159], v[210:213], v[6:9]
	v_mfma_f32_16x16x32_bf16 v[58:61], v[160:163], v[176:179], v[58:61]
	v_mfma_f32_16x16x32_bf16 v[50:53], v[168:171], v[176:179], v[50:53]
	v_mfma_f32_16x16x32_bf16 v[42:45], v[160:163], v[184:187], v[42:45]
	v_mfma_f32_16x16x32_bf16 v[34:37], v[168:171], v[184:187], v[34:37]
	v_mfma_f32_16x16x32_bf16 v[26:29], v[160:163], v[192:195], v[26:29]
	v_mfma_f32_16x16x32_bf16 v[18:21], v[168:171], v[192:195], v[18:21]
	v_mfma_f32_16x16x32_bf16 v[10:13], v[160:163], v[206:209], v[10:13]
	v_mfma_f32_16x16x32_bf16 v[2:5], v[168:171], v[206:209], v[2:5]
	v_mfma_f32_16x16x32_bf16 v[58:61], v[164:167], v[180:183], v[58:61]
	v_mfma_f32_16x16x32_bf16 v[50:53], v[172:175], v[180:183], v[50:53]
	v_mfma_f32_16x16x32_bf16 v[42:45], v[164:167], v[188:191], v[42:45]
	v_mfma_f32_16x16x32_bf16 v[34:37], v[172:175], v[188:191], v[34:37]
	v_mfma_f32_16x16x32_bf16 v[26:29], v[164:167], v[202:205], v[26:29]
	v_mfma_f32_16x16x32_bf16 v[18:21], v[172:175], v[202:205], v[18:21]
	v_mfma_f32_16x16x32_bf16 v[10:13], v[164:167], v[210:213], v[10:13]
	v_mfma_f32_16x16x32_bf16 v[2:5], v[172:175], v[210:213], v[2:5]
	s_barrier
	s_setprio 0
	s_add_u32 s67, s67, 0x100
	s_addc_u32 s68, s68, 0
	s_add_u32 s52, s52, 0x100
	s_addc_u32 s53, s53, 0
	s_cmp_ge_i32 s69, s62
	s_mov_b32 s8, s69
	s_cbranch_scc0 .LBB0_2507
	s_and_b64 vcc, exec, s[38:39]
	s_cbranch_vccz .LBB0_2510
	s_barrier
.LBB0_2510:
	v_mul_f32_e32 v145, 0xbfb8aa3b, v126
	v_exp_f32_e32 v145, v145
	v_lshl_or_b32 v146, s63, 7, v142
	v_lshl_add_u32 v144, s64, 8, v140
	v_ashrrev_i32_e32 v147, 31, v146
	v_add_f32_e32 v145, 1.0, v145
	v_rcp_f32_e32 v145, v145
	s_movk_i32 s8, 0x2b00
	s_andn2_b64 vcc, exec, s[46:47]
	s_mov_b64 s[66:67], 0x3000
	v_mul_f32_e32 v126, v126, v145
	v_mul_f32_e32 v122, v126, v122
	v_mul_f32_e32 v126, 0xbfb8aa3b, v118
	v_exp_f32_e32 v126, v126
	s_nop 0
	v_add_f32_e32 v126, 1.0, v126
	v_rcp_f32_e32 v126, v126
	s_nop 0
	v_mul_f32_e32 v118, v118, v126
	v_mul_f32_e32 v114, v118, v114
	v_mul_f32_e32 v118, 0xbfb8aa3b, v127
	v_exp_f32_e32 v118, v118
	s_nop 0
	v_add_f32_e32 v118, 1.0, v118
	v_rcp_f32_e32 v118, v118
	s_nop 0
	v_mul_f32_e32 v118, v127, v118
	v_mul_f32_e32 v118, v118, v123
	v_mul_f32_e32 v123, 0xbfb8aa3b, v119
	v_exp_f32_e32 v123, v123
	v_cvt_pk_bf16_f32 v118, v122, v118
	s_nop 0
	v_add_f32_e32 v123, 1.0, v123
	v_rcp_f32_e32 v123, v123
	s_nop 0
	v_mul_f32_e32 v119, v119, v123
	v_mul_f32_e32 v123, 0xbfb8aa3b, v120
	v_exp_f32_e32 v123, v123
	v_mul_f32_e32 v115, v119, v115
	v_mul_f32_e32 v119, 0xbfb8aa3b, v128
	v_exp_f32_e32 v119, v119
	v_add_f32_e32 v123, 1.0, v123
	v_rcp_f32_e32 v123, v123
	v_add_f32_e32 v119, 1.0, v119
	v_rcp_f32_e32 v119, v119
	v_mul_f32_e32 v120, v120, v123
	v_mul_f32_e32 v116, v120, v116
	v_mul_f32_e32 v120, 0xbfb8aa3b, v129
	v_exp_f32_e32 v120, v120
	v_mul_f32_e32 v123, 0xbfb8aa3b, v121
	v_exp_f32_e32 v123, v123
	v_mul_f32_e32 v119, v128, v119
	v_add_f32_e32 v120, 1.0, v120
	v_rcp_f32_e32 v120, v120
	v_add_f32_e32 v123, 1.0, v123
	v_rcp_f32_e32 v123, v123
	v_mul_f32_e32 v119, v119, v124
	v_mul_f32_e32 v120, v129, v120
	v_mul_f32_e32 v120, v120, v125
	v_mul_f32_e32 v121, v121, v123
	v_mul_f32_e32 v117, v121, v117
	v_cvt_pk_bf16_f32 v119, v119, v120
	v_cvt_pk_bf16_f32 v120, v114, v115
	v_mov_b64_e32 v[114:115], s[6:7]
	v_cvt_pk_bf16_f32 v121, v116, v117
	v_mad_i64_i32 v[122:123], s[0:1], v144, s8, v[114:115]
	v_lshlrev_b64 v[116:117], 1, v[146:147]
	v_lshl_add_u64 v[122:123], v[122:123], 0, v[116:117]
	global_store_dwordx4 v[122:123], v[118:121], off
	s_nop 1
	v_mul_f32_e32 v118, 0xbfb8aa3b, v110
	v_exp_f32_e32 v118, v118
	s_nop 0
	v_add_f32_e32 v118, 1.0, v118
	v_rcp_f32_e32 v118, v118
	s_nop 0
	v_mul_f32_e32 v110, v110, v118
	v_mul_f32_e32 v106, v110, v106
	v_mul_f32_e32 v110, 0xbfb8aa3b, v102
	v_exp_f32_e32 v110, v110
	s_nop 0
	v_add_f32_e32 v110, 1.0, v110
	v_rcp_f32_e32 v110, v110
	s_nop 0
	v_mul_f32_e32 v102, v102, v110
	v_mul_f32_e32 v102, v102, v98
	v_mul_f32_e32 v98, 0xbfb8aa3b, v111
	v_exp_f32_e32 v98, v98
	s_nop 0
	v_add_f32_e32 v98, 1.0, v98
	v_rcp_f32_e32 v98, v98
	s_nop 0
	v_mul_f32_e32 v98, v111, v98
	v_mul_f32_e32 v98, v98, v107
	v_mul_f32_e32 v107, 0xbfb8aa3b, v103
	v_exp_f32_e32 v107, v107
	v_cvt_pk_bf16_f32 v98, v106, v98
	s_nop 0
	v_add_f32_e32 v107, 1.0, v107
	v_rcp_f32_e32 v107, v107
	s_nop 0
	v_mul_f32_e32 v103, v103, v107
	v_mul_f32_e32 v107, 0xbfb8aa3b, v104
	v_exp_f32_e32 v107, v107
	v_mul_f32_e32 v103, v103, v99
	v_mul_f32_e32 v99, 0xbfb8aa3b, v112
	v_exp_f32_e32 v99, v99
	v_add_f32_e32 v107, 1.0, v107
	v_rcp_f32_e32 v107, v107
	v_add_f32_e32 v99, 1.0, v99
	v_rcp_f32_e32 v99, v99
	v_mul_f32_e32 v104, v104, v107
	v_mul_f32_e32 v104, v104, v100
	v_mul_f32_e32 v100, 0xbfb8aa3b, v113
	v_exp_f32_e32 v100, v100
	v_mul_f32_e32 v107, 0xbfb8aa3b, v105
	v_exp_f32_e32 v107, v107
	v_mul_f32_e32 v99, v112, v99
	v_add_f32_e32 v100, 1.0, v100
	v_rcp_f32_e32 v100, v100
	v_add_f32_e32 v107, 1.0, v107
	v_rcp_f32_e32 v107, v107
	v_mul_f32_e32 v99, v99, v108
	v_mul_f32_e32 v100, v113, v100
	v_mul_f32_e32 v100, v100, v109
	v_cvt_pk_bf16_f32 v99, v99, v100
	v_cvt_pk_bf16_f32 v100, v102, v103
	v_or_b32_e32 v102, 16, v144
	v_mul_f32_e32 v105, v105, v107
	v_mad_i64_i32 v[102:103], s[0:1], v102, s8, v[114:115]
	v_mul_f32_e32 v101, v105, v101
	v_lshl_add_u64 v[102:103], v[102:103], 0, v[116:117]
	v_cvt_pk_bf16_f32 v101, v104, v101
	global_store_dwordx4 v[102:103], v[98:101], off
	s_nop 1
	v_mul_f32_e32 v98, 0xbfb8aa3b, v94
	v_exp_f32_e32 v98, v98
	s_nop 0
	v_add_f32_e32 v98, 1.0, v98
	v_rcp_f32_e32 v98, v98
	s_nop 0
	v_mul_f32_e32 v94, v94, v98
	v_mul_f32_e32 v90, v94, v90
	v_mul_f32_e32 v94, 0xbfb8aa3b, v86
	v_exp_f32_e32 v94, v94
	s_nop 0
	v_add_f32_e32 v94, 1.0, v94
	v_rcp_f32_e32 v94, v94
	s_nop 0
	v_mul_f32_e32 v86, v86, v94
	v_mul_f32_e32 v86, v86, v82
	v_mul_f32_e32 v82, 0xbfb8aa3b, v95
	v_exp_f32_e32 v82, v82
	s_nop 0
	v_add_f32_e32 v82, 1.0, v82
	v_rcp_f32_e32 v82, v82
	s_nop 0
	v_mul_f32_e32 v82, v95, v82
	v_mul_f32_e32 v82, v82, v91
	v_mul_f32_e32 v91, 0xbfb8aa3b, v87
	v_exp_f32_e32 v91, v91
	v_cvt_pk_bf16_f32 v82, v90, v82
	s_nop 0
	v_add_f32_e32 v91, 1.0, v91
	v_rcp_f32_e32 v91, v91
	s_nop 0
	v_mul_f32_e32 v87, v87, v91
	v_mul_f32_e32 v91, 0xbfb8aa3b, v88
	v_exp_f32_e32 v91, v91
	v_mul_f32_e32 v87, v87, v83
	v_mul_f32_e32 v83, 0xbfb8aa3b, v96
	v_exp_f32_e32 v83, v83
	v_add_f32_e32 v91, 1.0, v91
	v_rcp_f32_e32 v91, v91
	v_add_f32_e32 v83, 1.0, v83
	v_rcp_f32_e32 v83, v83
	v_mul_f32_e32 v88, v88, v91
	v_mul_f32_e32 v88, v88, v84
	v_mul_f32_e32 v84, 0xbfb8aa3b, v97
	v_exp_f32_e32 v84, v84
	v_mul_f32_e32 v91, 0xbfb8aa3b, v89
	v_exp_f32_e32 v91, v91
	v_mul_f32_e32 v83, v96, v83
	v_add_f32_e32 v84, 1.0, v84
	v_rcp_f32_e32 v84, v84
	v_add_f32_e32 v91, 1.0, v91
	v_rcp_f32_e32 v91, v91
	v_mul_f32_e32 v83, v83, v92
	v_mul_f32_e32 v84, v97, v84
	v_mul_f32_e32 v84, v84, v93
	v_cvt_pk_bf16_f32 v83, v83, v84
	v_cvt_pk_bf16_f32 v84, v86, v87
	v_or_b32_e32 v86, 32, v144
	v_mul_f32_e32 v89, v89, v91
	v_mad_i64_i32 v[86:87], s[0:1], v86, s8, v[114:115]
	v_mul_f32_e32 v85, v89, v85
	v_lshl_add_u64 v[86:87], v[86:87], 0, v[116:117]
	v_cvt_pk_bf16_f32 v85, v88, v85
	global_store_dwordx4 v[86:87], v[82:85], off
	s_nop 1
	v_mul_f32_e32 v82, 0xbfb8aa3b, v78
	v_exp_f32_e32 v82, v82
	s_nop 0
	v_add_f32_e32 v82, 1.0, v82
	v_rcp_f32_e32 v82, v82
	s_nop 0
	v_mul_f32_e32 v78, v78, v82
	v_mul_f32_e32 v74, v78, v74
	v_mul_f32_e32 v78, 0xbfb8aa3b, v70
	v_exp_f32_e32 v78, v78
	s_nop 0
	v_add_f32_e32 v78, 1.0, v78
	v_rcp_f32_e32 v78, v78
	s_nop 0
	v_mul_f32_e32 v70, v70, v78
	v_mul_f32_e32 v70, v70, v66
	v_mul_f32_e32 v66, 0xbfb8aa3b, v79
	v_exp_f32_e32 v66, v66
	s_nop 0
	v_add_f32_e32 v66, 1.0, v66
	v_rcp_f32_e32 v66, v66
	s_nop 0
	v_mul_f32_e32 v66, v79, v66
	v_mul_f32_e32 v66, v66, v75
	v_mul_f32_e32 v75, 0xbfb8aa3b, v71
	v_exp_f32_e32 v75, v75
	v_cvt_pk_bf16_f32 v66, v74, v66
	s_nop 0
	v_add_f32_e32 v75, 1.0, v75
	v_rcp_f32_e32 v75, v75
	s_nop 0
	v_mul_f32_e32 v71, v71, v75
	v_mul_f32_e32 v75, 0xbfb8aa3b, v72
	v_exp_f32_e32 v75, v75
	v_mul_f32_e32 v71, v71, v67
	v_mul_f32_e32 v67, 0xbfb8aa3b, v80
	v_exp_f32_e32 v67, v67
	v_add_f32_e32 v75, 1.0, v75
	v_rcp_f32_e32 v75, v75
	v_add_f32_e32 v67, 1.0, v67
	v_rcp_f32_e32 v67, v67
	v_mul_f32_e32 v72, v72, v75
	v_mul_f32_e32 v72, v72, v68
	v_mul_f32_e32 v68, 0xbfb8aa3b, v81
	v_exp_f32_e32 v68, v68
	v_mul_f32_e32 v75, 0xbfb8aa3b, v73
	v_exp_f32_e32 v75, v75
	v_mul_f32_e32 v67, v80, v67
	v_add_f32_e32 v68, 1.0, v68
	v_rcp_f32_e32 v68, v68
	v_add_f32_e32 v75, 1.0, v75
	v_rcp_f32_e32 v75, v75
	v_mul_f32_e32 v67, v67, v76
	v_mul_f32_e32 v68, v81, v68
	v_mul_f32_e32 v68, v68, v77
	v_cvt_pk_bf16_f32 v67, v67, v68
	v_cvt_pk_bf16_f32 v68, v70, v71
	v_or_b32_e32 v70, 48, v144
	v_mul_f32_e32 v73, v73, v75
	v_mad_i64_i32 v[70:71], s[0:1], v70, s8, v[114:115]
	v_mul_f32_e32 v69, v73, v69
	v_lshl_add_u64 v[70:71], v[70:71], 0, v[116:117]
	v_cvt_pk_bf16_f32 v69, v72, v69
	global_store_dwordx4 v[70:71], v[66:69], off
	s_nop 1
	v_mul_f32_e32 v67, 0xbfb8aa3b, v62
	v_exp_f32_e32 v67, v67
	v_add_u32_e32 v66, 0x80, v144
	v_add_f32_e32 v67, 1.0, v67
	v_rcp_f32_e32 v67, v67
	s_nop 0
	v_mul_f32_e32 v62, v62, v67
	v_mul_f32_e32 v58, v62, v58
	v_mul_f32_e32 v62, 0xbfb8aa3b, v54
	v_exp_f32_e32 v62, v62
	s_nop 0
	v_add_f32_e32 v62, 1.0, v62
	v_rcp_f32_e32 v62, v62
	s_nop 0
	v_mul_f32_e32 v54, v54, v62
	v_mul_f32_e32 v54, v54, v50
	v_mul_f32_e32 v50, 0xbfb8aa3b, v63
	v_exp_f32_e32 v50, v50
	s_nop 0
	v_add_f32_e32 v50, 1.0, v50
	v_rcp_f32_e32 v50, v50
	s_nop 0
	v_mul_f32_e32 v50, v63, v50
	v_mul_f32_e32 v50, v50, v59
	v_mul_f32_e32 v59, 0xbfb8aa3b, v55
	v_exp_f32_e32 v59, v59
	v_cvt_pk_bf16_f32 v50, v58, v50
	s_nop 0
	v_add_f32_e32 v59, 1.0, v59
	v_rcp_f32_e32 v59, v59
	s_nop 0
	v_mul_f32_e32 v55, v55, v59
	v_mul_f32_e32 v59, 0xbfb8aa3b, v56
	v_exp_f32_e32 v59, v59
	v_mul_f32_e32 v55, v55, v51
	v_mul_f32_e32 v51, 0xbfb8aa3b, v64
	v_exp_f32_e32 v51, v51
	v_add_f32_e32 v59, 1.0, v59
	v_rcp_f32_e32 v59, v59
	v_add_f32_e32 v51, 1.0, v51
	v_rcp_f32_e32 v51, v51
	v_mul_f32_e32 v56, v56, v59
	v_mul_f32_e32 v56, v56, v52
	v_mul_f32_e32 v52, 0xbfb8aa3b, v65
	v_exp_f32_e32 v52, v52
	v_mul_f32_e32 v59, 0xbfb8aa3b, v57
	v_exp_f32_e32 v59, v59
	v_mul_f32_e32 v51, v64, v51
	v_add_f32_e32 v52, 1.0, v52
	v_rcp_f32_e32 v52, v52
	v_add_f32_e32 v59, 1.0, v59
	v_rcp_f32_e32 v59, v59
	v_mul_f32_e32 v51, v51, v60
	v_mul_f32_e32 v52, v65, v52
	v_mul_f32_e32 v52, v52, v61
	v_mul_f32_e32 v57, v57, v59
	v_cvt_pk_bf16_f32 v51, v51, v52
	v_cvt_pk_bf16_f32 v52, v54, v55
	v_mad_i64_i32 v[54:55], s[0:1], v66, s8, v[114:115]
	v_mul_f32_e32 v53, v57, v53
	v_lshl_add_u64 v[54:55], v[54:55], 0, v[116:117]
	v_cvt_pk_bf16_f32 v53, v56, v53
	global_store_dwordx4 v[54:55], v[50:53], off
	s_nop 1
	v_mul_f32_e32 v50, 0xbfb8aa3b, v46
	v_exp_f32_e32 v50, v50
	s_nop 0
	v_add_f32_e32 v50, 1.0, v50
	v_rcp_f32_e32 v50, v50
	s_nop 0
	v_mul_f32_e32 v46, v46, v50
	v_mul_f32_e32 v42, v46, v42
	v_mul_f32_e32 v46, 0xbfb8aa3b, v38
	v_exp_f32_e32 v46, v46
	s_nop 0
	v_add_f32_e32 v46, 1.0, v46
	v_rcp_f32_e32 v46, v46
	s_nop 0
	v_mul_f32_e32 v38, v38, v46
	v_mul_f32_e32 v38, v38, v34
	v_mul_f32_e32 v34, 0xbfb8aa3b, v47
	v_exp_f32_e32 v34, v34
	s_nop 0
	v_add_f32_e32 v34, 1.0, v34
	v_rcp_f32_e32 v34, v34
	s_nop 0
	v_mul_f32_e32 v34, v47, v34
	v_mul_f32_e32 v34, v34, v43
	v_mul_f32_e32 v43, 0xbfb8aa3b, v39
	v_exp_f32_e32 v43, v43
	v_cvt_pk_bf16_f32 v34, v42, v34
	s_nop 0
	v_add_f32_e32 v43, 1.0, v43
	v_rcp_f32_e32 v43, v43
	s_nop 0
	v_mul_f32_e32 v39, v39, v43
	v_mul_f32_e32 v43, 0xbfb8aa3b, v40
	v_exp_f32_e32 v43, v43
	v_mul_f32_e32 v39, v39, v35
	v_mul_f32_e32 v35, 0xbfb8aa3b, v48
	v_exp_f32_e32 v35, v35
	v_add_f32_e32 v43, 1.0, v43
	v_rcp_f32_e32 v43, v43
	v_add_f32_e32 v35, 1.0, v35
	v_rcp_f32_e32 v35, v35
	v_mul_f32_e32 v40, v40, v43
	v_mul_f32_e32 v40, v40, v36
	v_mul_f32_e32 v36, 0xbfb8aa3b, v49
	v_exp_f32_e32 v36, v36
	v_mul_f32_e32 v43, 0xbfb8aa3b, v41
	v_exp_f32_e32 v43, v43
	v_mul_f32_e32 v35, v48, v35
	v_add_f32_e32 v36, 1.0, v36
	v_rcp_f32_e32 v36, v36
	v_add_f32_e32 v43, 1.0, v43
	v_rcp_f32_e32 v43, v43
	v_mul_f32_e32 v35, v35, v44
	v_mul_f32_e32 v36, v49, v36
	v_mul_f32_e32 v36, v36, v45
	v_cvt_pk_bf16_f32 v35, v35, v36
	v_cvt_pk_bf16_f32 v36, v38, v39
	v_add_u32_e32 v38, 0x90, v144
	v_mul_f32_e32 v41, v41, v43
	v_mad_i64_i32 v[38:39], s[0:1], v38, s8, v[114:115]
	v_mul_f32_e32 v37, v41, v37
	v_lshl_add_u64 v[38:39], v[38:39], 0, v[116:117]
	v_cvt_pk_bf16_f32 v37, v40, v37
	global_store_dwordx4 v[38:39], v[34:37], off
	s_nop 1
	v_mul_f32_e32 v34, 0xbfb8aa3b, v30
	v_exp_f32_e32 v34, v34
	s_nop 0
	v_add_f32_e32 v34, 1.0, v34
	v_rcp_f32_e32 v34, v34
	s_nop 0
	v_mul_f32_e32 v30, v30, v34
	v_mul_f32_e32 v26, v30, v26
	v_mul_f32_e32 v30, 0xbfb8aa3b, v22
	v_exp_f32_e32 v30, v30
	s_nop 0
	v_add_f32_e32 v30, 1.0, v30
	v_rcp_f32_e32 v30, v30
	s_nop 0
	v_mul_f32_e32 v22, v22, v30
	v_mul_f32_e32 v22, v22, v18
	v_mul_f32_e32 v18, 0xbfb8aa3b, v31
	v_exp_f32_e32 v18, v18
	s_nop 0
	v_add_f32_e32 v18, 1.0, v18
	v_rcp_f32_e32 v18, v18
	s_nop 0
	v_mul_f32_e32 v18, v31, v18
	v_mul_f32_e32 v18, v18, v27
	v_mul_f32_e32 v27, 0xbfb8aa3b, v23
	v_exp_f32_e32 v27, v27
	v_cvt_pk_bf16_f32 v18, v26, v18
	s_nop 0
	v_add_f32_e32 v27, 1.0, v27
	v_rcp_f32_e32 v27, v27
	s_nop 0
	v_mul_f32_e32 v23, v23, v27
	v_mul_f32_e32 v27, 0xbfb8aa3b, v24
	v_exp_f32_e32 v27, v27
	v_mul_f32_e32 v23, v23, v19
	v_mul_f32_e32 v19, 0xbfb8aa3b, v32
	v_exp_f32_e32 v19, v19
	v_add_f32_e32 v27, 1.0, v27
	v_rcp_f32_e32 v27, v27
	v_add_f32_e32 v19, 1.0, v19
	v_rcp_f32_e32 v19, v19
	v_mul_f32_e32 v24, v24, v27
	v_mul_f32_e32 v24, v24, v20
	v_mul_f32_e32 v20, 0xbfb8aa3b, v33
	v_exp_f32_e32 v20, v20
	v_mul_f32_e32 v27, 0xbfb8aa3b, v25
	v_exp_f32_e32 v27, v27
	v_mul_f32_e32 v19, v32, v19
	v_add_f32_e32 v20, 1.0, v20
	v_rcp_f32_e32 v20, v20
	v_add_f32_e32 v27, 1.0, v27
	v_rcp_f32_e32 v27, v27
	v_mul_f32_e32 v19, v19, v28
	v_mul_f32_e32 v20, v33, v20
	v_mul_f32_e32 v20, v20, v29
	v_cvt_pk_bf16_f32 v19, v19, v20
	v_cvt_pk_bf16_f32 v20, v22, v23
	v_add_u32_e32 v22, 0xa0, v144
	v_mul_f32_e32 v25, v25, v27
	v_mad_i64_i32 v[22:23], s[0:1], v22, s8, v[114:115]
	v_mul_f32_e32 v21, v25, v21
	v_lshl_add_u64 v[22:23], v[22:23], 0, v[116:117]
	v_cvt_pk_bf16_f32 v21, v24, v21
	global_store_dwordx4 v[22:23], v[18:21], off
	s_nop 1
	v_mul_f32_e32 v18, 0xbfb8aa3b, v14
	v_exp_f32_e32 v18, v18
	s_nop 0
	v_add_f32_e32 v18, 1.0, v18
	v_rcp_f32_e32 v18, v18
	s_nop 0
	v_mul_f32_e32 v14, v14, v18
	v_mul_f32_e32 v10, v14, v10
	v_mul_f32_e32 v14, 0xbfb8aa3b, v6
	v_exp_f32_e32 v14, v14
	s_nop 0
	v_add_f32_e32 v14, 1.0, v14
	v_rcp_f32_e32 v14, v14
	s_nop 0
	v_mul_f32_e32 v6, v6, v14
	v_mul_f32_e32 v6, v6, v2
	v_mul_f32_e32 v2, 0xbfb8aa3b, v15
	v_exp_f32_e32 v2, v2
	s_nop 0
	v_add_f32_e32 v2, 1.0, v2
	v_rcp_f32_e32 v2, v2
	s_nop 0
	v_mul_f32_e32 v2, v15, v2
	v_mul_f32_e32 v2, v2, v11
	v_mul_f32_e32 v11, 0xbfb8aa3b, v7
	v_exp_f32_e32 v11, v11
	v_cvt_pk_bf16_f32 v2, v10, v2
	s_nop 0
	v_add_f32_e32 v11, 1.0, v11
	v_rcp_f32_e32 v11, v11
	s_nop 0
	v_mul_f32_e32 v7, v7, v11
	v_mul_f32_e32 v11, 0xbfb8aa3b, v8
	v_exp_f32_e32 v11, v11
	v_mul_f32_e32 v7, v7, v3
	v_mul_f32_e32 v3, 0xbfb8aa3b, v16
	v_exp_f32_e32 v3, v3
	v_add_f32_e32 v11, 1.0, v11
	v_rcp_f32_e32 v11, v11
	v_add_f32_e32 v3, 1.0, v3
	v_rcp_f32_e32 v3, v3
	v_mul_f32_e32 v8, v8, v11
	v_mul_f32_e32 v8, v8, v4
	v_mul_f32_e32 v4, 0xbfb8aa3b, v17
	v_exp_f32_e32 v4, v4
	v_mul_f32_e32 v11, 0xbfb8aa3b, v9
	v_exp_f32_e32 v11, v11
	v_mul_f32_e32 v3, v16, v3
	v_add_f32_e32 v4, 1.0, v4
	v_rcp_f32_e32 v4, v4
	v_add_f32_e32 v11, 1.0, v11
	v_rcp_f32_e32 v11, v11
	v_mul_f32_e32 v3, v3, v12
	v_mul_f32_e32 v4, v17, v4
	v_mul_f32_e32 v4, v4, v13
	v_cvt_pk_bf16_f32 v3, v3, v4
	v_cvt_pk_bf16_f32 v4, v6, v7
	v_add_u32_e32 v6, 0xb0, v144
	v_mul_f32_e32 v9, v9, v11
	v_mad_i64_i32 v[6:7], s[0:1], v6, s8, v[114:115]
	v_mul_f32_e32 v5, v9, v5
	v_lshl_add_u64 v[6:7], v[6:7], 0, v[116:117]
	s_mov_b64 s[8:9], -1
	v_cvt_pk_bf16_f32 v5, v8, v5
	global_store_dwordx4 v[6:7], v[2:5], off
	s_cbranch_vccnz .LBB0_2497
	s_andn2_b64 vcc, exec, s[4:5]
	s_cbranch_vccnz .LBB0_2496
	s_mov_b32 s100, 1
	s_branch .LBB0_2496

.LBB0_2587:
	s_add_i32 s41, s69, -2
	s_add_u32 s70, s8, 0x100
	v_mov_b32_e32 v2, 0
	s_addc_u32 s71, s9, 0
	s_mov_b32 s48, 0
	v_mov_b32_e32 v3, v2
	v_mov_b32_e32 v4, v2
	v_mov_b32_e32 v5, v2
	v_mov_b32_e32 v6, v2
	v_mov_b32_e32 v7, v2
	v_mov_b32_e32 v8, v2
	v_mov_b32_e32 v9, v2
	v_mov_b32_e32 v14, v2
	v_mov_b32_e32 v15, v2
	v_mov_b32_e32 v16, v2
	v_mov_b32_e32 v17, v2
	v_mov_b32_e32 v22, v2
	v_mov_b32_e32 v23, v2
	v_mov_b32_e32 v24, v2
	v_mov_b32_e32 v25, v2
	v_mov_b32_e32 v30, v2
	v_mov_b32_e32 v31, v2
	v_mov_b32_e32 v32, v2
	v_mov_b32_e32 v33, v2
	v_mov_b32_e32 v38, v2
	v_mov_b32_e32 v39, v2
	v_mov_b32_e32 v40, v2
	v_mov_b32_e32 v41, v2
	s_nop 0
	v_mov_b32_e32 v46, v2
	v_mov_b32_e32 v47, v2
	v_mov_b32_e32 v48, v2
	v_mov_b32_e32 v49, v2
	v_mov_b32_e32 v54, v2
	v_mov_b32_e32 v55, v2
	v_mov_b32_e32 v56, v2
	v_mov_b32_e32 v57, v2
	v_mov_b32_e32 v10, v2
	v_mov_b32_e32 v11, v2
	v_mov_b32_e32 v12, v2
	v_mov_b32_e32 v13, v2
	v_mov_b32_e32 v18, v2
	v_mov_b32_e32 v19, v2
	v_mov_b32_e32 v20, v2
	v_mov_b32_e32 v21, v2
	v_mov_b32_e32 v26, v2
	v_mov_b32_e32 v27, v2
	v_mov_b32_e32 v28, v2
	v_mov_b32_e32 v29, v2
	v_mov_b32_e32 v34, v2
	v_mov_b32_e32 v35, v2
	v_mov_b32_e32 v36, v2
	v_mov_b32_e32 v37, v2
	v_mov_b32_e32 v42, v2
	v_mov_b32_e32 v43, v2
	v_mov_b32_e32 v44, v2
	v_mov_b32_e32 v45, v2
	v_mov_b32_e32 v50, v2
	v_mov_b32_e32 v51, v2
	v_mov_b32_e32 v52, v2
	v_mov_b32_e32 v53, v2
	v_mov_b32_e32 v58, v2
	v_mov_b32_e32 v59, v2
	v_mov_b32_e32 v60, v2
	v_mov_b32_e32 v61, v2
	v_mov_b32_e32 v62, v2
	v_mov_b32_e32 v63, v2
	v_mov_b32_e32 v64, v2
	v_mov_b32_e32 v65, v2
	v_mov_b32_e32 v66, v2
	v_mov_b32_e32 v67, v2
	v_mov_b32_e32 v68, v2
	v_mov_b32_e32 v69, v2
	v_mov_b32_e32 v70, v2
	v_mov_b32_e32 v71, v2
	v_mov_b32_e32 v72, v2
	v_mov_b32_e32 v73, v2
	v_mov_b32_e32 v78, v2
	v_mov_b32_e32 v79, v2
	v_mov_b32_e32 v80, v2
	v_mov_b32_e32 v81, v2
	v_mov_b32_e32 v86, v2
	v_mov_b32_e32 v87, v2
	v_mov_b32_e32 v88, v2
	v_mov_b32_e32 v89, v2
	v_mov_b32_e32 v94, v2
	v_mov_b32_e32 v95, v2
	v_mov_b32_e32 v96, v2
	v_mov_b32_e32 v97, v2
	v_mov_b32_e32 v102, v2
	v_mov_b32_e32 v103, v2
	v_mov_b32_e32 v104, v2
	v_mov_b32_e32 v105, v2
	v_mov_b32_e32 v114, v2
	v_mov_b32_e32 v115, v2
	v_mov_b32_e32 v116, v2
	v_mov_b32_e32 v117, v2
	v_mov_b32_e32 v118, v2
	v_mov_b32_e32 v119, v2
	v_mov_b32_e32 v120, v2
	v_mov_b32_e32 v121, v2
	v_mov_b32_e32 v74, v2
	v_mov_b32_e32 v75, v2
	v_mov_b32_e32 v76, v2
	v_mov_b32_e32 v77, v2
	v_mov_b32_e32 v82, v2
	v_mov_b32_e32 v83, v2
	v_mov_b32_e32 v84, v2
	v_mov_b32_e32 v85, v2
	v_mov_b32_e32 v90, v2
	v_mov_b32_e32 v91, v2
	v_mov_b32_e32 v92, v2
	v_mov_b32_e32 v93, v2
	v_mov_b32_e32 v98, v2
	v_mov_b32_e32 v99, v2
	v_mov_b32_e32 v100, v2
	v_mov_b32_e32 v101, v2
	v_mov_b32_e32 v106, v2
	v_mov_b32_e32 v107, v2
	v_mov_b32_e32 v108, v2
	v_mov_b32_e32 v109, v2
	v_mov_b32_e32 v110, v2
	v_mov_b32_e32 v111, v2
	v_mov_b32_e32 v112, v2
	v_mov_b32_e32 v113, v2
	v_mov_b32_e32 v122, v2
	v_mov_b32_e32 v123, v2
	v_mov_b32_e32 v124, v2
	v_mov_b32_e32 v125, v2
	v_mov_b32_e32 v126, v2
	v_mov_b32_e32 v127, v2
	v_mov_b32_e32 v128, v2
	v_mov_b32_e32 v129, v2
	s_cmp_eq_u32 s100, 1
	s_cbranch_scc0 .Ldefbar_skip_6
	s_mov_b32 s100, 0
	s_barrier
.Ldefbar_skip_6:
.LBB0_2588:
	s_add_i32 s72, s48, 2
	s_add_u32 s8, s46, 0x100
	s_addc_u32 s9, s47, 0
	s_add_i32 s0, 0, 0x10000
	s_cmp_eq_u32 s41, s48
	s_cselect_b32 s51, s43, s9
	s_cselect_b32 s50, s42, s8
	s_cselect_b32 s49, s45, s71
	s_cselect_b32 s48, s44, s70
	s_add_i32 s73, 0, 0x14000
	v_add_u32_e32 v142, s0, v188
	v_add_u32_e32 v172, s73, v188
	ds_read_b128 v[130:133], v142
	ds_read_b128 v[134:137], v142 offset:1024
	ds_read_b128 v[138:141], v142 offset:2048
	ds_read_b128 v[142:145], v142 offset:3072
	ds_read_b128 v[146:149], v172
	ds_read_b128 v[164:167], v172 offset:1024
	ds_read_b128 v[168:171], v172 offset:2048
	ds_read_b128 v[172:175], v172 offset:3072
	v_lshl_add_u64 v[194:195], s[46:47], 0, v[162:163]
	s_add_i32 m0, s27, 0xc000
	ds_read_b128 v[176:179], v189
	ds_read_b128 v[180:183], v189 offset:1024
	ds_read_b128 v[184:187], v189 offset:2048
	ds_read_b128 v[190:193], v189 offset:3072
	ds_read_b128 v[202:205], v189 offset:4096
	ds_read_b128 v[206:209], v189 offset:5120
	ds_read_b128 v[210:213], v189 offset:6144
	ds_read_b128 v[214:217], v189 offset:7168
	global_load_lds_dwordx4 v[194:195], off
	v_lshl_add_u64 v[194:195], s[46:47], 0, v[160:161]
	s_add_i32 m0, s27, 0xe000
	s_nop 0
	global_load_lds_dwordx4 v[194:195], off
	s_waitcnt vmcnt(8)
	s_waitcnt lgkmcnt(0)
	s_setprio 1
	s_barrier
	v_mfma_f32_16x16x32_bf16 v[126:129], v[130:133], v[176:179], v[126:129]
	v_mfma_f32_16x16x32_bf16 v[122:125], v[138:141], v[176:179], v[122:125]
	v_mfma_f32_16x16x32_bf16 v[110:113], v[130:133], v[184:187], v[110:113]
	v_mfma_f32_16x16x32_bf16 v[106:109], v[138:141], v[184:187], v[106:109]
	v_mfma_f32_16x16x32_bf16 v[98:101], v[130:133], v[202:205], v[98:101]
	v_mfma_f32_16x16x32_bf16 v[90:93], v[138:141], v[202:205], v[90:93]
	v_mfma_f32_16x16x32_bf16 v[82:85], v[130:133], v[210:213], v[82:85]
	v_mfma_f32_16x16x32_bf16 v[74:77], v[138:141], v[210:213], v[74:77]
	v_mfma_f32_16x16x32_bf16 v[126:129], v[134:137], v[180:183], v[126:129]
	v_mfma_f32_16x16x32_bf16 v[122:125], v[142:145], v[180:183], v[122:125]
	v_mfma_f32_16x16x32_bf16 v[110:113], v[134:137], v[190:193], v[110:113]
	v_mfma_f32_16x16x32_bf16 v[106:109], v[142:145], v[190:193], v[106:109]
	v_mfma_f32_16x16x32_bf16 v[98:101], v[134:137], v[206:209], v[98:101]
	v_mfma_f32_16x16x32_bf16 v[90:93], v[142:145], v[206:209], v[90:93]
	v_mfma_f32_16x16x32_bf16 v[82:85], v[134:137], v[214:217], v[82:85]
	v_mfma_f32_16x16x32_bf16 v[74:77], v[142:145], v[214:217], v[74:77]
	v_mfma_f32_16x16x32_bf16 v[118:121], v[146:149], v[176:179], v[118:121]
	v_mfma_f32_16x16x32_bf16 v[114:117], v[168:171], v[176:179], v[114:117]
	v_mfma_f32_16x16x32_bf16 v[102:105], v[146:149], v[184:187], v[102:105]
	v_mfma_f32_16x16x32_bf16 v[94:97], v[168:171], v[184:187], v[94:97]
	v_mfma_f32_16x16x32_bf16 v[86:89], v[146:149], v[202:205], v[86:89]
	v_mfma_f32_16x16x32_bf16 v[78:81], v[168:171], v[202:205], v[78:81]
	v_mfma_f32_16x16x32_bf16 v[70:73], v[146:149], v[210:213], v[70:73]
	v_mfma_f32_16x16x32_bf16 v[66:69], v[168:171], v[210:213], v[66:69]
	v_mfma_f32_16x16x32_bf16 v[118:121], v[164:167], v[180:183], v[118:121]
	v_mfma_f32_16x16x32_bf16 v[114:117], v[172:175], v[180:183], v[114:117]
	v_mfma_f32_16x16x32_bf16 v[102:105], v[164:167], v[190:193], v[102:105]
	v_mfma_f32_16x16x32_bf16 v[94:97], v[172:175], v[190:193], v[94:97]
	v_mfma_f32_16x16x32_bf16 v[86:89], v[164:167], v[206:209], v[86:89]
	v_mfma_f32_16x16x32_bf16 v[78:81], v[172:175], v[206:209], v[78:81]
	v_mfma_f32_16x16x32_bf16 v[70:73], v[164:167], v[214:217], v[70:73]
	v_mfma_f32_16x16x32_bf16 v[66:69], v[172:175], v[214:217], v[66:69]
	s_barrier
	s_setprio 0
	s_add_i32 s0, s0, s26
	v_lshl_add_u64 v[194:195], s[48:49], 0, v[196:197]
	s_mov_b32 m0, s0
	ds_read_b128 v[176:179], v189 offset:16384
	ds_read_b128 v[180:183], v189 offset:17408
	ds_read_b128 v[184:187], v189 offset:18432
	ds_read_b128 v[190:193], v189 offset:19456
	ds_read_b128 v[202:205], v189 offset:20480
	ds_read_b128 v[206:209], v189 offset:21504
	ds_read_b128 v[210:213], v189 offset:22528
	ds_read_b128 v[214:217], v189 offset:23552
	global_load_lds_dwordx4 v[194:195], off
	s_add_i32 m0, s0, 0x2000
	s_add_u32 s0, s48, 0x158000
	v_lshl_add_u64 v[218:219], s[48:49], 0, v[154:155]
	s_addc_u32 s1, s49, 0
	s_add_i32 s46, s73, s26
	global_load_lds_dwordx4 v[218:219], off
	v_lshl_add_u64 v[220:221], s[0:1], 0, v[196:197]
	s_mov_b32 m0, s46
	v_lshl_add_u64 v[222:223], s[50:51], 0, v[152:153]
	global_load_lds_dwordx4 v[220:221], off
	v_lshl_add_u64 v[220:221], s[0:1], 0, v[154:155]
	s_add_i32 m0, s46, 0x2000
	s_nop 0
	global_load_lds_dwordx4 v[220:221], off
	v_lshl_add_u64 v[220:221], s[50:51], 0, v[150:151]
	s_mov_b32 m0, s27
	s_nop 0
	global_load_lds_dwordx4 v[220:221], off
	s_mov_b32 m0, s30
	s_nop 0
	global_load_lds_dwordx4 v[222:223], off
	s_waitcnt vmcnt(8)
	s_waitcnt lgkmcnt(0)
	s_setprio 1
	s_barrier
	v_mfma_f32_16x16x32_bf16 v[62:65], v[130:133], v[176:179], v[62:65]
	v_mfma_f32_16x16x32_bf16 v[58:61], v[138:141], v[176:179], v[58:61]
	v_mfma_f32_16x16x32_bf16 v[50:53], v[130:133], v[184:187], v[50:53]
	v_mfma_f32_16x16x32_bf16 v[42:45], v[138:141], v[184:187], v[42:45]
	v_mfma_f32_16x16x32_bf16 v[34:37], v[130:133], v[202:205], v[34:37]
	v_mfma_f32_16x16x32_bf16 v[26:29], v[138:141], v[202:205], v[26:29]
	v_mfma_f32_16x16x32_bf16 v[18:21], v[130:133], v[210:213], v[18:21]
	v_mfma_f32_16x16x32_bf16 v[10:13], v[138:141], v[210:213], v[10:13]
	v_mfma_f32_16x16x32_bf16 v[62:65], v[134:137], v[180:183], v[62:65]
	v_mfma_f32_16x16x32_bf16 v[58:61], v[142:145], v[180:183], v[58:61]
	v_mfma_f32_16x16x32_bf16 v[50:53], v[134:137], v[190:193], v[50:53]
	v_mfma_f32_16x16x32_bf16 v[42:45], v[142:145], v[190:193], v[42:45]
	v_mfma_f32_16x16x32_bf16 v[34:37], v[134:137], v[206:209], v[34:37]
	v_mfma_f32_16x16x32_bf16 v[26:29], v[142:145], v[206:209], v[26:29]
	v_mfma_f32_16x16x32_bf16 v[18:21], v[134:137], v[214:217], v[18:21]
	v_mfma_f32_16x16x32_bf16 v[10:13], v[142:145], v[214:217], v[10:13]
	v_mfma_f32_16x16x32_bf16 v[54:57], v[146:149], v[176:179], v[54:57]
	v_mfma_f32_16x16x32_bf16 v[46:49], v[168:171], v[176:179], v[46:49]
	v_mfma_f32_16x16x32_bf16 v[38:41], v[146:149], v[184:187], v[38:41]
	v_mfma_f32_16x16x32_bf16 v[30:33], v[168:171], v[184:187], v[30:33]
	v_mfma_f32_16x16x32_bf16 v[22:25], v[146:149], v[202:205], v[22:25]
	v_mfma_f32_16x16x32_bf16 v[14:17], v[168:171], v[202:205], v[14:17]
	v_mfma_f32_16x16x32_bf16 v[6:9], v[146:149], v[210:213], v[6:9]
	v_mfma_f32_16x16x32_bf16 v[2:5], v[168:171], v[210:213], v[2:5]
	v_mfma_f32_16x16x32_bf16 v[54:57], v[164:167], v[180:183], v[54:57]
	v_mfma_f32_16x16x32_bf16 v[46:49], v[172:175], v[180:183], v[46:49]
	v_mfma_f32_16x16x32_bf16 v[38:41], v[164:167], v[190:193], v[38:41]
	v_mfma_f32_16x16x32_bf16 v[30:33], v[172:175], v[190:193], v[30:33]
	v_mfma_f32_16x16x32_bf16 v[22:25], v[164:167], v[206:209], v[22:25]
	v_mfma_f32_16x16x32_bf16 v[14:17], v[172:175], v[206:209], v[14:17]
	v_mfma_f32_16x16x32_bf16 v[6:9], v[164:167], v[214:217], v[6:9]
	v_mfma_f32_16x16x32_bf16 v[2:5], v[172:175], v[214:217], v[2:5]
	s_barrier
	s_setprio 0
	s_add_i32 s46, 0, 0x18000
	s_add_i32 s47, 0, 0x1c000
	v_add_u32_e32 v142, s46, v188
	v_add_u32_e32 v172, s47, v188
	ds_read_b128 v[130:133], v142
	ds_read_b128 v[134:137], v142 offset:1024
	ds_read_b128 v[138:141], v142 offset:2048
	ds_read_b128 v[142:145], v142 offset:3072
	ds_read_b128 v[146:149], v172
	ds_read_b128 v[164:167], v172 offset:1024
	ds_read_b128 v[168:171], v172 offset:2048
	ds_read_b128 v[172:175], v172 offset:3072
	s_add_u32 s0, s50, 0x158000
	s_addc_u32 s1, s51, 0
	s_mov_b32 m0, s31
	v_lshl_add_u64 v[224:225], s[0:1], 0, v[150:151]
	ds_read_b128 v[176:179], v189 offset:32768
	ds_read_b128 v[180:183], v189 offset:33792
	ds_read_b128 v[184:187], v189 offset:34816
	ds_read_b128 v[190:193], v189 offset:35840
	ds_read_b128 v[202:205], v189 offset:36864
	ds_read_b128 v[206:209], v189 offset:37888
	ds_read_b128 v[210:213], v189 offset:38912
	ds_read_b128 v[214:217], v189 offset:39936
	global_load_lds_dwordx4 v[224:225], off
	v_lshl_add_u64 v[224:225], s[0:1], 0, v[152:153]
	s_mov_b32 m0, s34
	s_nop 0
	global_load_lds_dwordx4 v[224:225], off
	s_waitcnt vmcnt(8)
	s_waitcnt lgkmcnt(0)
	s_setprio 1
	s_barrier
	v_mfma_f32_16x16x32_bf16 v[126:129], v[130:133], v[176:179], v[126:129]
	v_mfma_f32_16x16x32_bf16 v[122:125], v[138:141], v[176:179], v[122:125]
	v_mfma_f32_16x16x32_bf16 v[110:113], v[130:133], v[184:187], v[110:113]
	v_mfma_f32_16x16x32_bf16 v[106:109], v[138:141], v[184:187], v[106:109]
	v_mfma_f32_16x16x32_bf16 v[98:101], v[130:133], v[202:205], v[98:101]
	v_mfma_f32_16x16x32_bf16 v[90:93], v[138:141], v[202:205], v[90:93]
	v_mfma_f32_16x16x32_bf16 v[82:85], v[130:133], v[210:213], v[82:85]
	v_mfma_f32_16x16x32_bf16 v[74:77], v[138:141], v[210:213], v[74:77]
	v_mfma_f32_16x16x32_bf16 v[126:129], v[134:137], v[180:183], v[126:129]
	v_mfma_f32_16x16x32_bf16 v[122:125], v[142:145], v[180:183], v[122:125]
	v_mfma_f32_16x16x32_bf16 v[110:113], v[134:137], v[190:193], v[110:113]
	v_mfma_f32_16x16x32_bf16 v[106:109], v[142:145], v[190:193], v[106:109]
	v_mfma_f32_16x16x32_bf16 v[98:101], v[134:137], v[206:209], v[98:101]
	v_mfma_f32_16x16x32_bf16 v[90:93], v[142:145], v[206:209], v[90:93]
	v_mfma_f32_16x16x32_bf16 v[82:85], v[134:137], v[214:217], v[82:85]
	v_mfma_f32_16x16x32_bf16 v[74:77], v[142:145], v[214:217], v[74:77]
	v_mfma_f32_16x16x32_bf16 v[118:121], v[146:149], v[176:179], v[118:121]
	v_mfma_f32_16x16x32_bf16 v[114:117], v[168:171], v[176:179], v[114:117]
	v_mfma_f32_16x16x32_bf16 v[102:105], v[146:149], v[184:187], v[102:105]
	v_mfma_f32_16x16x32_bf16 v[94:97], v[168:171], v[184:187], v[94:97]
	v_mfma_f32_16x16x32_bf16 v[86:89], v[146:149], v[202:205], v[86:89]
	v_mfma_f32_16x16x32_bf16 v[78:81], v[168:171], v[202:205], v[78:81]
	v_mfma_f32_16x16x32_bf16 v[70:73], v[146:149], v[210:213], v[70:73]
	v_mfma_f32_16x16x32_bf16 v[66:69], v[168:171], v[210:213], v[66:69]
	v_mfma_f32_16x16x32_bf16 v[118:121], v[164:167], v[180:183], v[118:121]
	v_mfma_f32_16x16x32_bf16 v[114:117], v[172:175], v[180:183], v[114:117]
	v_mfma_f32_16x16x32_bf16 v[102:105], v[164:167], v[190:193], v[102:105]
	v_mfma_f32_16x16x32_bf16 v[94:97], v[172:175], v[190:193], v[94:97]
	v_mfma_f32_16x16x32_bf16 v[86:89], v[164:167], v[206:209], v[86:89]
	v_mfma_f32_16x16x32_bf16 v[78:81], v[172:175], v[206:209], v[78:81]
	v_mfma_f32_16x16x32_bf16 v[70:73], v[164:167], v[214:217], v[70:73]
	v_mfma_f32_16x16x32_bf16 v[66:69], v[172:175], v[214:217], v[66:69]
	s_barrier
	s_setprio 0
	s_add_i32 s0, s46, s26
	v_lshl_add_u64 v[194:195], v[194:195], 0, s[16:17]
	s_mov_b32 m0, s0
	ds_read_b128 v[176:179], v189 offset:49152
	ds_read_b128 v[180:183], v189 offset:50176
	ds_read_b128 v[184:187], v189 offset:51200
	ds_read_b128 v[190:193], v189 offset:52224
	ds_read_b128 v[202:205], v189 offset:53248
	ds_read_b128 v[206:209], v189 offset:54272
	ds_read_b128 v[210:213], v189 offset:55296
	ds_read_b128 v[214:217], v189 offset:56320
	global_load_lds_dwordx4 v[194:195], off
	s_add_i32 m0, s0, 0x2000
	s_add_u32 s0, s48, 0x158080
	v_lshl_add_u64 v[194:195], v[218:219], 0, s[16:17]
	s_addc_u32 s1, s49, 0
	s_add_i32 s46, s47, s26
	global_load_lds_dwordx4 v[194:195], off
	v_lshl_add_u64 v[194:195], s[0:1], 0, v[196:197]
	s_mov_b32 m0, s46
	s_nop 0
	global_load_lds_dwordx4 v[194:195], off
	v_lshl_add_u64 v[194:195], s[0:1], 0, v[154:155]
	s_add_i32 m0, s46, 0x2000
	s_nop 0
	global_load_lds_dwordx4 v[194:195], off
	v_lshl_add_u64 v[194:195], v[220:221], 0, s[16:17]
	s_mov_b32 m0, s53
	s_nop 0
	global_load_lds_dwordx4 v[194:195], off
	v_lshl_add_u64 v[194:195], v[222:223], 0, s[16:17]
	s_mov_b32 m0, s58
	s_nop 0
	global_load_lds_dwordx4 v[194:195], off
	s_waitcnt vmcnt(8)
	s_waitcnt lgkmcnt(0)
	s_setprio 1
	s_barrier
	v_mfma_f32_16x16x32_bf16 v[62:65], v[130:133], v[176:179], v[62:65]
	v_mfma_f32_16x16x32_bf16 v[58:61], v[138:141], v[176:179], v[58:61]
	v_mfma_f32_16x16x32_bf16 v[50:53], v[130:133], v[184:187], v[50:53]
	v_mfma_f32_16x16x32_bf16 v[42:45], v[138:141], v[184:187], v[42:45]
	v_mfma_f32_16x16x32_bf16 v[34:37], v[130:133], v[202:205], v[34:37]
	v_mfma_f32_16x16x32_bf16 v[26:29], v[138:141], v[202:205], v[26:29]
	v_mfma_f32_16x16x32_bf16 v[18:21], v[130:133], v[210:213], v[18:21]
	v_mfma_f32_16x16x32_bf16 v[10:13], v[138:141], v[210:213], v[10:13]
	v_mfma_f32_16x16x32_bf16 v[62:65], v[134:137], v[180:183], v[62:65]
	v_mfma_f32_16x16x32_bf16 v[58:61], v[142:145], v[180:183], v[58:61]
	v_mfma_f32_16x16x32_bf16 v[50:53], v[134:137], v[190:193], v[50:53]
	v_mfma_f32_16x16x32_bf16 v[42:45], v[142:145], v[190:193], v[42:45]
	v_mfma_f32_16x16x32_bf16 v[34:37], v[134:137], v[206:209], v[34:37]
	v_mfma_f32_16x16x32_bf16 v[26:29], v[142:145], v[206:209], v[26:29]
	v_mfma_f32_16x16x32_bf16 v[18:21], v[134:137], v[214:217], v[18:21]
	v_mfma_f32_16x16x32_bf16 v[10:13], v[142:145], v[214:217], v[10:13]
	v_mfma_f32_16x16x32_bf16 v[54:57], v[146:149], v[176:179], v[54:57]
	v_mfma_f32_16x16x32_bf16 v[46:49], v[168:171], v[176:179], v[46:49]
	v_mfma_f32_16x16x32_bf16 v[38:41], v[146:149], v[184:187], v[38:41]
	v_mfma_f32_16x16x32_bf16 v[30:33], v[168:171], v[184:187], v[30:33]
	v_mfma_f32_16x16x32_bf16 v[22:25], v[146:149], v[202:205], v[22:25]
	v_mfma_f32_16x16x32_bf16 v[14:17], v[168:171], v[202:205], v[14:17]
	v_mfma_f32_16x16x32_bf16 v[6:9], v[146:149], v[210:213], v[6:9]
	v_mfma_f32_16x16x32_bf16 v[2:5], v[168:171], v[210:213], v[2:5]
	v_mfma_f32_16x16x32_bf16 v[54:57], v[164:167], v[180:183], v[54:57]
	v_mfma_f32_16x16x32_bf16 v[46:49], v[172:175], v[180:183], v[46:49]
	v_mfma_f32_16x16x32_bf16 v[38:41], v[164:167], v[190:193], v[38:41]
	v_mfma_f32_16x16x32_bf16 v[30:33], v[172:175], v[190:193], v[30:33]
	v_mfma_f32_16x16x32_bf16 v[22:25], v[164:167], v[206:209], v[22:25]
	v_mfma_f32_16x16x32_bf16 v[14:17], v[172:175], v[206:209], v[14:17]
	v_mfma_f32_16x16x32_bf16 v[6:9], v[164:167], v[214:217], v[6:9]
	v_mfma_f32_16x16x32_bf16 v[2:5], v[172:175], v[214:217], v[2:5]
	s_barrier
	s_setprio 0
	s_add_u32 s70, s70, 0x100
	s_addc_u32 s71, s71, 0
	s_cmp_ge_i32 s72, s69
	s_mov_b64 s[46:47], s[8:9]
	s_mov_b32 s48, s72
	s_cbranch_scc0 .LBB0_2588
	s_and_b64 vcc, exec, s[28:29]
	s_cbranch_vccz .LBB0_2591
	s_barrier

.LBB0_2594:
	s_and_b64 vcc, exec, s[38:39]
	s_mov_b64 s[8:9], -1
	s_cbranch_vccnz .LBB0_2573
	s_andn2_b64 vcc, exec, s[4:5]
	s_cbranch_vccnz .LBB0_2572
	s_mov_b32 s100, 1
	s_branch .LBB0_2572
